# sc1 (agent write-through) on all 16B epilogue stores so the barrier L2 writeback has little dirty data; + LRU scan1 init hoist
# baseline (speedup 1.0000x reference)
; __device__ __forceinline__ float ssq4(const f32x4 o) { return (o[0] * o[0] + o[1] * o[1]) + (o[2] * o[2] + o[3] * o[3]); }
;     __device__ __forceinline__ void operator()(f32x4 (&acc)[2][2][4][2], const Unit& u, int wr, int wc, int fr, int fq) const {
;     ...
;         f32x4 cur[2][4], nxt[2][4];
; #pragma unroll
;         for (int q = 0; q < 2; ++q)
; #pragma unroll
;             for (int c = 0; c < 4; ++c) cur[q][c] = *(const f32x4*)(base + (size_t)EPI_ROW(q) * D + col0 + (c >> 1) * HALF + (c & 1) * 4);
; #pragma unroll
;         for (int k = 0; k < 4; ++k) {
;             if (k < 3) {
; #pragma unroll
;                 for (int q = 0; q < 2; ++q)
; #pragma unroll
;                     for (int c = 0; c < 4; ++c) nxt[q][c] = *(const f32x4*)(base + (size_t)EPI_ROW(2 * k + 2 + q) * D + col0 + (c >> 1) * HALF + (c & 1) * 4);
;             }
;             asm volatile("" ::: "memory");
; #pragma unroll
;             for (int q = 0; q < 2; ++q) { const int r = 2 * k + q, ai = r >> 2, m = r & 3; const size_t off = (size_t)EPI_ROW(r) * D + col0; float sr = 0.f;
; #pragma unroll
;                 for (int bj = 0; bj < 2; ++bj) { const f32x4 o0 = cur[q][2 * bj] + acc[ai][bj][m][0], o1 = cur[q][2 * bj + 1] + acc[ai][bj][m][1];
;                     *(f32x4*)(out + off + bj * HALF) = o0; *(f32x4*)(out + off + bj * HALF + 4) = o1;
;                     u32x4 w; w.x = cvt_pk_bf16(o0[0], o0[1]); w.y = cvt_pk_bf16(o0[2], o0[3]); w.z = cvt_pk_bf16(o1[0], o1[1]); w.w = cvt_pk_bf16(o1[2], o1[3]); *(u32x4*)(hb + off + bj * HALF) = w; sr += ssq4(o0) + ssq4(o1); }
;                 s[ai][m] = sr; }
.LBB0_1013:
	v_mov_b32_e32 v185, v246
	s_lshl_b32 s1, s6, 8
	s_or_b32 s1, s1, s42
	v_bfe_u32 v184, v185, 4, 2
	v_lshl_or_b32 v200, v184, 3, s1
	s_lshl_b32 s1, s24, 8
	v_and_b32_e32 v183, 15, v185
	s_add_i32 s3, s1, s35
	v_or_b32_e32 v202, s3, v183
	v_readlane_b32 s14, v255, 40
	v_ashrrev_i32_e32 v203, 31, v202
	v_ashrrev_i32_e32 v201, 31, v200
	v_readlane_b32 s15, v255, 41
	v_lshlrev_b64 v[130:131], 13, v[202:203]
	v_or_b32_e32 v178, 16, v202
	v_lshl_add_u64 v[204:205], v[200:201], 2, s[14:15]
	v_lshl_add_u64 v[130:131], v[204:205], 0, v[130:131]
	global_load_dwordx4 v[210:213], v[130:131], off offset:16
	global_load_dwordx4 v[214:217], v[130:131], off
	global_load_dwordx4 v[218:221], v[130:131], off offset:528
	global_load_dwordx4 v[222:225], v[130:131], off offset:512
	v_ashrrev_i32_e32 v179, 31, v178
	v_lshlrev_b64 v[130:131], 13, v[178:179]
	v_lshl_add_u64 v[130:131], v[204:205], 0, v[130:131]
	global_load_dwordx4 v[170:173], v[130:131], off offset:16
	global_load_dwordx4 v[174:177], v[130:131], off
	global_load_dwordx4 v[162:165], v[130:131], off offset:528
	global_load_dwordx4 v[166:169], v[130:131], off offset:512
	v_or_b32_e32 v208, 32, v202
	v_ashrrev_i32_e32 v209, 31, v208
	v_lshlrev_b64 v[130:131], 13, v[208:209]
	v_lshl_add_u64 v[130:131], v[204:205], 0, v[130:131]
	v_or_b32_e32 v206, 48, v202
	global_load_dwordx4 v[154:157], v[130:131], off offset:16
	global_load_dwordx4 v[158:161], v[130:131], off
	global_load_dwordx4 v[138:141], v[130:131], off offset:528
	global_load_dwordx4 v[142:145], v[130:131], off offset:512
	v_ashrrev_i32_e32 v207, 31, v206
	v_lshlrev_b64 v[130:131], 13, v[206:207]
	v_lshl_add_u64 v[134:135], v[204:205], 0, v[130:131]
	global_load_dwordx4 v[146:149], v[134:135], off offset:16
	global_load_dwordx4 v[150:153], v[134:135], off
	global_load_dwordx4 v[130:133], v[134:135], off offset:528
	s_nop 0
	global_load_dwordx4 v[134:137], v[134:135], off offset:512
	v_lshlrev_b64 v[226:227], 11, v[202:203]
	v_lshl_add_u64 v[226:227], v[226:227], 0, v[200:201]
	v_lshlrev_b64 v[208:209], 11, v[208:209]
	v_lshl_add_u64 v[208:209], v[208:209], 0, v[200:201]
	v_cmp_eq_u32_e32 vcc, 0, v184
	s_waitcnt vmcnt(0)
	v_pk_add_f32 v[122:123], v[122:123], v[210:211]
	v_pk_add_f32 v[128:129], v[128:129], v[216:217]
	v_pk_add_f32 v[126:127], v[126:127], v[214:215]
	v_lshl_add_u64 v[214:215], v[226:227], 2, s[36:37]
	v_pk_add_f32 v[124:125], v[124:125], v[212:213]
	global_store_dwordx4 v[214:215], v[126:129], off sc1
	global_store_dwordx4 v[214:215], v[122:125], off offset:16 sc1
	v_cvt_pk_bf16_f32 v210, v126, v127
	v_cvt_pk_bf16_f32 v212, v122, v123
	v_mul_f32_e32 v127, v127, v127
	v_mul_f32_e32 v123, v123, v123
	v_fmac_f32_e32 v127, v126, v126
	v_mul_f32_e32 v126, v129, v129
	v_fmac_f32_e32 v123, v122, v122
	v_mul_f32_e32 v122, v125, v125
	v_fmac_f32_e32 v126, v128, v128
	v_fmac_f32_e32 v122, v124, v124
	v_cvt_pk_bf16_f32 v211, v128, v129
	v_cvt_pk_bf16_f32 v213, v124, v125
	v_lshl_add_u64 v[216:217], v[226:227], 1, s[54:55]
	v_add_f32_e32 v126, v127, v126
	v_add_f32_e32 v122, v123, v122
	v_pk_add_f32 v[120:121], v[120:121], v[224:225]
	v_pk_add_f32 v[118:119], v[118:119], v[222:223]
	v_pk_add_f32 v[114:115], v[114:115], v[218:219]
	global_store_dwordx4 v[216:217], v[210:213], off sc1
	v_add_f32_e32 v126, v126, v122
	v_pk_add_f32 v[116:117], v[116:117], v[220:221]
	global_store_dwordx4 v[214:215], v[118:121], off offset:512 sc1
	global_store_dwordx4 v[214:215], v[114:117], off offset:528 sc1
	v_cvt_pk_bf16_f32 v122, v118, v119
	v_cvt_pk_bf16_f32 v124, v114, v115
	v_mul_f32_e32 v119, v119, v119
	v_mul_f32_e32 v115, v115, v115
	v_fmac_f32_e32 v119, v118, v118
	v_mul_f32_e32 v118, v121, v121
	v_fmac_f32_e32 v115, v114, v114
	v_mul_f32_e32 v114, v117, v117
	v_fmac_f32_e32 v118, v120, v120
	v_fmac_f32_e32 v114, v116, v116
	v_add_f32_e32 v118, v119, v118
	v_add_f32_e32 v114, v115, v114
	v_add_f32_e32 v114, v118, v114
	v_add_f32_e32 v187, v126, v114
	v_lshlrev_b64 v[114:115], 11, v[178:179]
	v_lshl_add_u64 v[118:119], v[114:115], 0, v[200:201]
	v_pk_add_f32 v[112:113], v[112:113], v[176:177]
	v_pk_add_f32 v[110:111], v[110:111], v[174:175]
	v_pk_add_f32 v[108:109], v[108:109], v[172:173]
	v_pk_add_f32 v[106:107], v[106:107], v[170:171]
	v_cvt_pk_bf16_f32 v123, v120, v121
	v_cvt_pk_bf16_f32 v125, v116, v117
	v_lshl_add_u64 v[120:121], v[118:119], 2, s[36:37]
	v_cvt_pk_bf16_f32 v114, v110, v111
	v_cvt_pk_bf16_f32 v115, v112, v113
	v_cvt_pk_bf16_f32 v116, v106, v107
	v_cvt_pk_bf16_f32 v117, v108, v109
	v_lshl_add_u64 v[118:119], v[118:119], 1, s[54:55]
	v_pk_add_f32 v[104:105], v[104:105], v[168:169]
	v_pk_add_f32 v[102:103], v[102:103], v[166:167]
	v_pk_add_f32 v[100:101], v[100:101], v[164:165]
	v_pk_add_f32 v[98:99], v[98:99], v[162:163]
	v_add_u32_e32 v210, 0x80, v202
	global_store_dwordx4 v[216:217], v[122:125], off offset:256 sc1
	global_store_dwordx4 v[120:121], v[110:113], off sc1
	global_store_dwordx4 v[120:121], v[106:109], off offset:16 sc1
	global_store_dwordx4 v[118:119], v[114:117], off sc1
	v_ashrrev_i32_e32 v211, 31, v210
	global_store_dwordx4 v[120:121], v[102:105], off offset:512 sc1
	global_store_dwordx4 v[120:121], v[98:101], off offset:528 sc1
	v_cvt_pk_bf16_f32 v114, v102, v103
	v_cvt_pk_bf16_f32 v115, v104, v105
	v_cvt_pk_bf16_f32 v116, v98, v99
	v_cvt_pk_bf16_f32 v117, v100, v101
	global_store_dwordx4 v[118:119], v[114:117], off offset:256 sc1
	v_add_u32_e32 v170, 0x90, v202
	v_ashrrev_i32_e32 v171, 31, v170
	v_lshlrev_b64 v[114:115], 13, v[210:211]
	v_lshl_add_u64 v[114:115], v[204:205], 0, v[114:115]
	global_load_dwordx4 v[172:175], v[114:115], off offset:16
	global_load_dwordx4 v[176:179], v[114:115], off
; __device__ __forceinline__ float ssq4(const f32x4 o) { return (o[0] * o[0] + o[1] * o[1]) + (o[2] * o[2] + o[3] * o[3]); }
;     __device__ __forceinline__ void operator()(f32x4 (&acc)[2][2][4][2], const Unit& u, int wr, int wc, int fr, int fq) const {
;     ...
;         f32x4 cur[2][4], nxt[2][4];
; #pragma unroll
;         for (int q = 0; q < 2; ++q)
; #pragma unroll
;             for (int c = 0; c < 4; ++c) cur[q][c] = *(const f32x4*)(base + (size_t)EPI_ROW(q) * D + col0 + (c >> 1) * HALF + (c & 1) * 4);
; #pragma unroll
;         for (int k = 0; k < 4; ++k) {
;             if (k < 3) {
; #pragma unroll
;                 for (int q = 0; q < 2; ++q)
; #pragma unroll
;                     for (int c = 0; c < 4; ++c) nxt[q][c] = *(const f32x4*)(base + (size_t)EPI_ROW(2 * k + 2 + q) * D + col0 + (c >> 1) * HALF + (c & 1) * 4);
;             }
;             asm volatile("" ::: "memory");
; #pragma unroll
;             for (int q = 0; q < 2; ++q) { const int r = 2 * k + q, ai = r >> 2, m = r & 3; const size_t off = (size_t)EPI_ROW(r) * D + col0; float sr = 0.f;
; #pragma unroll
;                 for (int bj = 0; bj < 2; ++bj) { const f32x4 o0 = cur[q][2 * bj] + acc[ai][bj][m][0], o1 = cur[q][2 * bj + 1] + acc[ai][bj][m][1];
;                     *(f32x4*)(out + off + bj * HALF) = o0; *(f32x4*)(out + off + bj * HALF + 4) = o1;
;                     u32x4 w; w.x = cvt_pk_bf16(o0[0], o0[1]); w.y = cvt_pk_bf16(o0[2], o0[3]); w.z = cvt_pk_bf16(o1[0], o1[1]); w.w = cvt_pk_bf16(o1[2], o1[3]); *(u32x4*)(hb + off + bj * HALF) = w; sr += ssq4(o0) + ssq4(o1); }
;                 s[ai][m] = sr; }
	global_load_dwordx4 v[162:165], v[114:115], off offset:528
	global_load_dwordx4 v[166:169], v[114:115], off offset:512
	v_lshlrev_b64 v[114:115], 13, v[170:171]
	v_pk_add_f32 v[96:97], v[96:97], v[160:161]
	v_pk_add_f32 v[94:95], v[94:95], v[158:159]
	v_pk_add_f32 v[92:93], v[92:93], v[156:157]
	v_pk_add_f32 v[90:91], v[90:91], v[154:155]
	v_pk_add_f32 v[88:89], v[88:89], v[144:145]
	v_pk_add_f32 v[86:87], v[86:87], v[142:143]
	v_pk_add_f32 v[80:81], v[80:81], v[140:141]
	v_pk_add_f32 v[78:79], v[78:79], v[138:139]
	v_lshl_add_u64 v[118:119], v[204:205], 0, v[114:115]
	v_lshl_add_u64 v[158:159], v[208:209], 2, s[36:37]
	v_cvt_pk_bf16_f32 v154, v94, v95
	v_cvt_pk_bf16_f32 v155, v96, v97
	v_cvt_pk_bf16_f32 v156, v90, v91
	v_cvt_pk_bf16_f32 v157, v92, v93
	v_lshl_add_u64 v[160:161], v[208:209], 1, s[54:55]
	v_cvt_pk_bf16_f32 v138, v86, v87
	v_cvt_pk_bf16_f32 v139, v88, v89
	v_cvt_pk_bf16_f32 v140, v78, v79
	v_cvt_pk_bf16_f32 v141, v80, v81
	global_load_dwordx4 v[122:125], v[118:119], off offset:16
	global_load_dwordx4 v[126:129], v[118:119], off
	global_load_dwordx4 v[114:117], v[118:119], off offset:528
	s_nop 0
	global_load_dwordx4 v[118:121], v[118:119], off offset:512
	global_store_dwordx4 v[158:159], v[94:97], off sc1
	global_store_dwordx4 v[158:159], v[90:93], off offset:16 sc1
	global_store_dwordx4 v[160:161], v[154:157], off sc1
	global_store_dwordx4 v[158:159], v[86:89], off offset:512 sc1
	global_store_dwordx4 v[158:159], v[78:81], off offset:528 sc1
	global_store_dwordx4 v[160:161], v[138:141], off offset:256 sc1
	v_pk_add_f32 v[84:85], v[84:85], v[152:153]
	v_pk_add_f32 v[82:83], v[82:83], v[150:151]
	v_lshlrev_b64 v[138:139], 11, v[206:207]
	v_lshl_add_u64 v[142:143], v[138:139], 0, v[200:201]
	v_pk_add_f32 v[76:77], v[76:77], v[148:149]
	v_pk_add_f32 v[74:75], v[74:75], v[146:147]
	v_pk_add_f32 v[72:73], v[72:73], v[136:137]
	v_pk_add_f32 v[70:71], v[70:71], v[134:135]
	v_pk_add_f32 v[68:69], v[68:69], v[132:133]
	v_pk_add_f32 v[66:67], v[66:67], v[130:131]
	v_add_u32_e32 v206, 0xa0, v202
	v_lshl_add_u64 v[144:145], v[142:143], 2, s[36:37]
	v_cvt_pk_bf16_f32 v138, v82, v83
	v_cvt_pk_bf16_f32 v139, v84, v85
	v_cvt_pk_bf16_f32 v140, v74, v75
	v_cvt_pk_bf16_f32 v141, v76, v77
	v_lshl_add_u64 v[142:143], v[142:143], 1, s[54:55]
	v_cvt_pk_bf16_f32 v130, v70, v71
	v_cvt_pk_bf16_f32 v131, v72, v73
	v_cvt_pk_bf16_f32 v132, v66, v67
	v_cvt_pk_bf16_f32 v133, v68, v69
	v_ashrrev_i32_e32 v207, 31, v206
	global_store_dwordx4 v[144:145], v[82:85], off sc1
	global_store_dwordx4 v[144:145], v[74:77], off offset:16 sc1
	global_store_dwordx4 v[142:143], v[138:141], off sc1
	global_store_dwordx4 v[144:145], v[70:73], off offset:512 sc1
	global_store_dwordx4 v[144:145], v[66:69], off offset:528 sc1
	global_store_dwordx4 v[142:143], v[130:133], off offset:256 sc1
	v_add_u32_e32 v202, 0xb0, v202
	v_ashrrev_i32_e32 v203, 31, v202
	v_lshlrev_b64 v[130:131], 13, v[206:207]
	v_lshl_add_u64 v[142:143], v[204:205], 0, v[130:131]
	global_load_dwordx4 v[130:133], v[142:143], off offset:16
	global_load_dwordx4 v[134:137], v[142:143], off
	global_load_dwordx4 v[138:141], v[142:143], off offset:528
	s_nop 0
	global_load_dwordx4 v[142:145], v[142:143], off offset:512
	v_lshlrev_b64 v[146:147], 13, v[202:203]
	v_lshl_add_u64 v[158:159], v[204:205], 0, v[146:147]
	global_load_dwordx4 v[146:149], v[158:159], off offset:16
	global_load_dwordx4 v[150:153], v[158:159], off
	global_load_dwordx4 v[154:157], v[158:159], off offset:528
	s_nop 0
	global_load_dwordx4 v[158:161], v[158:159], off offset:512
	v_lshlrev_b64 v[204:205], 11, v[210:211]
	v_lshl_add_u64 v[204:205], v[204:205], 0, v[200:201]
	s_waitcnt vmcnt(27)
	v_pk_add_f32 v[60:61], v[60:61], v[174:175]
	s_waitcnt vmcnt(26)
	v_pk_add_f32 v[64:65], v[64:65], v[178:179]
	v_pk_add_f32 v[62:63], v[62:63], v[176:177]
	v_pk_add_f32 v[58:59], v[58:59], v[172:173]
	s_waitcnt vmcnt(24)
	v_pk_add_f32 v[56:57], v[56:57], v[168:169]
	v_pk_add_f32 v[54:55], v[54:55], v[166:167]
	v_pk_add_f32 v[48:49], v[48:49], v[164:165]
	v_pk_add_f32 v[46:47], v[46:47], v[162:163]
	v_lshl_add_u64 v[176:177], v[204:205], 2, s[36:37]
	v_cvt_pk_bf16_f32 v172, v62, v63
	v_cvt_pk_bf16_f32 v173, v64, v65
	v_cvt_pk_bf16_f32 v174, v58, v59
	v_cvt_pk_bf16_f32 v175, v60, v61
	v_lshl_add_u64 v[178:179], v[204:205], 1, s[54:55]
	v_cvt_pk_bf16_f32 v162, v54, v55
	v_cvt_pk_bf16_f32 v163, v56, v57
	v_cvt_pk_bf16_f32 v164, v46, v47
	v_cvt_pk_bf16_f32 v165, v48, v49
	global_store_dwordx4 v[176:177], v[62:65], off sc1
	global_store_dwordx4 v[176:177], v[58:61], off offset:16 sc1
	global_store_dwordx4 v[178:179], v[172:175], off sc1
	global_store_dwordx4 v[176:177], v[54:57], off offset:512 sc1
	global_store_dwordx4 v[176:177], v[46:49], off offset:528 sc1
	global_store_dwordx4 v[178:179], v[162:165], off offset:256 sc1
	s_waitcnt vmcnt(28)
; __device__ __forceinline__ float shx(float v, int o, int lane) { return __builtin_bit_cast(float, __builtin_amdgcn_ds_bpermute((lane ^ o) << 2, __builtin_bit_cast(int, v))); }
; __device__ __forceinline__ float ssq4(const f32x4 o) { return (o[0] * o[0] + o[1] * o[1]) + (o[2] * o[2] + o[3] * o[3]); }
; template <bool SIXTEEN> __device__ __forceinline__ void tile_ssq(const float (&s)[2][4], const Unit& u, int wr, int wc, int fr, int fq, float* ssq, LAS float* ptab) {
;     ...
;         for (int m = 0; m < 4; ++m) { float v = s[ai][m]; v += shx(v, 16, lane); v += shx(v, 32, lane); if (fq == 0) ptab[(ai * HALF + wr * 64 + m * 16 + fr) * 4 + wc] = v; }
;     __device__ __forceinline__ void operator()(f32x4 (&acc)[2][2][4][2], const Unit& u, int wr, int wc, int fr, int fq) const {
;     ...
;             for (int q = 0; q < 2; ++q) { const int r = 2 * k + q, ai = r >> 2, m = r & 3; const size_t off = (size_t)EPI_ROW(r) * D + col0; float sr = 0.f;
; #pragma unroll
;                 for (int bj = 0; bj < 2; ++bj) { const f32x4 o0 = cur[q][2 * bj] + acc[ai][bj][m][0], o1 = cur[q][2 * bj + 1] + acc[ai][bj][m][1];
;                     *(f32x4*)(out + off + bj * HALF) = o0; *(f32x4*)(out + off + bj * HALF + 4) = o1;
;                     u32x4 w; w.x = cvt_pk_bf16(o0[0], o0[1]); w.y = cvt_pk_bf16(o0[2], o0[3]); w.z = cvt_pk_bf16(o1[0], o1[1]); w.w = cvt_pk_bf16(o1[2], o1[3]); *(u32x4*)(hb + off + bj * HALF) = w; sr += ssq4(o0) + ssq4(o1); }
;                 s[ai][m] = sr; }
	v_pk_add_f32 v[52:53], v[52:53], v[128:129]
	v_pk_add_f32 v[50:51], v[50:51], v[126:127]
	v_lshlrev_b64 v[162:163], 11, v[170:171]
	v_lshl_add_u64 v[162:163], v[162:163], 0, v[200:201]
	v_pk_add_f32 v[44:45], v[44:45], v[124:125]
	v_pk_add_f32 v[42:43], v[42:43], v[122:123]
	s_waitcnt vmcnt(26)
	v_pk_add_f32 v[40:41], v[40:41], v[120:121]
	v_pk_add_f32 v[38:39], v[38:39], v[118:119]
	v_pk_add_f32 v[36:37], v[36:37], v[116:117]
	v_pk_add_f32 v[34:35], v[34:35], v[114:115]
	v_lshl_add_u64 v[126:127], v[162:163], 2, s[36:37]
	v_cvt_pk_bf16_f32 v122, v50, v51
	v_cvt_pk_bf16_f32 v123, v52, v53
	v_cvt_pk_bf16_f32 v124, v42, v43
	v_cvt_pk_bf16_f32 v125, v44, v45
	v_lshl_add_u64 v[128:129], v[162:163], 1, s[54:55]
	v_cvt_pk_bf16_f32 v114, v38, v39
	v_cvt_pk_bf16_f32 v115, v40, v41
	v_cvt_pk_bf16_f32 v116, v34, v35
	v_cvt_pk_bf16_f32 v117, v36, v37
	global_store_dwordx4 v[126:127], v[50:53], off sc1
	global_store_dwordx4 v[126:127], v[42:45], off offset:16 sc1
	global_store_dwordx4 v[128:129], v[122:125], off sc1
	global_store_dwordx4 v[126:127], v[38:41], off offset:512 sc1
	global_store_dwordx4 v[126:127], v[34:37], off offset:528 sc1
	global_store_dwordx4 v[128:129], v[114:117], off offset:256 sc1
	s_waitcnt vmcnt(19)
	v_pk_add_f32 v[28:29], v[28:29], v[132:133]
	v_lshlrev_b64 v[114:115], 11, v[206:207]
	v_lshl_add_u64 v[118:119], v[114:115], 0, v[200:201]
	s_waitcnt vmcnt(18)
	v_pk_add_f32 v[32:33], v[32:33], v[136:137]
	v_pk_add_f32 v[30:31], v[30:31], v[134:135]
	v_pk_add_f32 v[26:27], v[26:27], v[130:131]
	v_lshl_add_u64 v[120:121], v[118:119], 2, s[36:37]
	v_cvt_pk_bf16_f32 v114, v30, v31
	v_cvt_pk_bf16_f32 v115, v32, v33
	v_cvt_pk_bf16_f32 v116, v26, v27
	v_cvt_pk_bf16_f32 v117, v28, v29
	v_lshl_add_u64 v[118:119], v[118:119], 1, s[54:55]
	s_waitcnt vmcnt(16)
	v_pk_add_f32 v[24:25], v[24:25], v[144:145]
	v_pk_add_f32 v[22:23], v[22:23], v[142:143]
	v_pk_add_f32 v[16:17], v[16:17], v[140:141]
	v_pk_add_f32 v[14:15], v[14:15], v[138:139]
	global_store_dwordx4 v[120:121], v[30:33], off sc1
	global_store_dwordx4 v[120:121], v[26:29], off offset:16 sc1
	global_store_dwordx4 v[118:119], v[114:117], off sc1
	global_store_dwordx4 v[120:121], v[22:25], off offset:512 sc1
	global_store_dwordx4 v[120:121], v[14:17], off offset:528 sc1
	v_cvt_pk_bf16_f32 v114, v22, v23
	v_cvt_pk_bf16_f32 v115, v24, v25
	v_cvt_pk_bf16_f32 v116, v14, v15
	v_cvt_pk_bf16_f32 v117, v16, v17
	global_store_dwordx4 v[118:119], v[114:117], off offset:256 sc1
	s_waitcnt vmcnt(20)
	v_pk_add_f32 v[20:21], v[20:21], v[152:153]
	v_pk_add_f32 v[18:19], v[18:19], v[150:151]
	v_lshlrev_b64 v[114:115], 11, v[202:203]
	v_lshl_add_u64 v[118:119], v[114:115], 0, v[200:201]
	v_pk_add_f32 v[12:13], v[12:13], v[148:149]
	v_pk_add_f32 v[10:11], v[10:11], v[146:147]
	v_lshl_add_u64 v[120:121], v[118:119], 2, s[36:37]
	v_cvt_pk_bf16_f32 v114, v18, v19
	v_cvt_pk_bf16_f32 v115, v20, v21
	v_cvt_pk_bf16_f32 v116, v10, v11
	v_cvt_pk_bf16_f32 v117, v12, v13
	v_lshl_add_u64 v[118:119], v[118:119], 1, s[54:55]
	s_waitcnt vmcnt(18)
	v_pk_add_f32 v[8:9], v[8:9], v[160:161]
	v_pk_add_f32 v[6:7], v[6:7], v[158:159]
	v_pk_add_f32 v[4:5], v[4:5], v[156:157]
	v_pk_add_f32 v[2:3], v[2:3], v[154:155]
	global_store_dwordx4 v[120:121], v[18:21], off sc1
	global_store_dwordx4 v[120:121], v[10:13], off offset:16 sc1
	global_store_dwordx4 v[118:119], v[114:117], off sc1
	global_store_dwordx4 v[120:121], v[6:9], off offset:512 sc1
	global_store_dwordx4 v[120:121], v[2:5], off offset:528 sc1
	v_cvt_pk_bf16_f32 v114, v6, v7
	v_cvt_pk_bf16_f32 v115, v8, v9
	v_cvt_pk_bf16_f32 v116, v2, v3
	v_cvt_pk_bf16_f32 v117, v4, v5
	global_store_dwordx4 v[118:119], v[114:117], off offset:256 sc1
	s_nop 1
	v_and_b32_e32 v114, 63, v185
	v_lshlrev_b32_e32 v115, 2, v114
	v_xor_b32_e32 v116, 64, v115
	ds_bpermute_b32 v117, v116, v187
	v_xor_b32_e32 v115, 0x80, v115
	s_waitcnt lgkmcnt(0)
	v_add_f32_e32 v118, v187, v117
	ds_bpermute_b32 v119, v115, v118
	v_lshl_add_u32 v117, v183, 4, s86
	s_and_saveexec_b64 s[14:15], vcc
	s_cbranch_execz .LBB0_1015
	s_waitcnt lgkmcnt(0)
	v_add_f32_e32 v118, v118, v119
	ds_write_b32 v117, v118

;     __device__ __forceinline__ void operator()(f32x4 (&acc)[2][2][4][2], const Unit& u, int wr, int wc, int fr, int fq) const {
;     ...
;             for (int m = 0; m < 4; ++m) { const int row = row0 + ai * HALF + m * 16; bf16_t* rowp = O + (size_t)row * ldc + col0;
;                 const float rs = ssq ? rsv[ai * 4 + m] : 1.0f;
; #pragma unroll
;                 for (int bj = 0; bj < 2; ++bj) { f32x4 v0 = acc[ai][bj][m][0] * rs, v1 = acc[ai][bj][m][1] * rs;
;                     if (ACT == 2) {
; #pragma unroll
;                         for (int j = 0; j < 4; ++j) { float a = v0[j] > 0.f ? v0[j] : 0.f; v0[j] = a * a; float b = v1[j] > 0.f ? v1[j] : 0.f; v1[j] = b * b; } }
;                     u32x4 w; w.x = cvt_pk_bf16(v0[0], v0[1]); w.y = cvt_pk_bf16(v0[2], v0[3]); w.z = cvt_pk_bf16(v1[0], v1[1]); w.w = cvt_pk_bf16(v1[2], v1[3]);
;                     *(u32x4*)(rowp + bj * HALF) = w; } }
.LBB0_1112:
	s_lshl_b32 s3, s64, 8
	v_lshl_or_b32 v130, v163, 3, s3
	v_or_b32_e32 v130, s75, v130
	v_ashrrev_i32_e32 v131, 31, v130
	v_lshlrev_b64 v[134:135], 12, v[158:159]
	v_lshl_add_u64 v[134:135], s[58:59], 0, v[134:135]
	v_lshlrev_b64 v[136:137], 1, v[130:131]
	v_lshl_add_u64 v[130:131], v[134:135], 0, v[136:137]
	v_cndmask_b32_e64 v134, v166, 1.0, s[92:93]
	v_pk_mul_f32 v[128:129], v[128:129], v[134:135] op_sel_hi:[1,0]
	v_pk_mul_f32 v[126:127], v[126:127], v[134:135] op_sel_hi:[1,0]
	v_pk_mul_f32 v[140:141], v[124:125], v[134:135] op_sel_hi:[1,0]
	v_pk_mul_f32 v[124:125], v[122:123], v[134:135] op_sel_hi:[1,0]
	v_cvt_pk_bf16_f32 v122, v126, v127
	v_cvt_pk_bf16_f32 v123, v128, v129
	v_cvt_pk_bf16_f32 v124, v124, v125
	v_cvt_pk_bf16_f32 v125, v140, v141
	global_store_dwordx4 v[130:131], v[122:125], off sc1
	v_pk_mul_f32 v[120:121], v[120:121], v[134:135] op_sel_hi:[1,0]
	v_pk_mul_f32 v[118:119], v[118:119], v[134:135] op_sel_hi:[1,0]
	v_pk_mul_f32 v[122:123], v[112:113], v[134:135] op_sel_hi:[1,0]
	v_pk_mul_f32 v[112:113], v[110:111], v[134:135] op_sel_hi:[1,0]
	v_cvt_pk_bf16_f32 v110, v118, v119
	v_cvt_pk_bf16_f32 v111, v120, v121
	v_cvt_pk_bf16_f32 v112, v112, v113
	v_cvt_pk_bf16_f32 v113, v122, v123
	global_store_dwordx4 v[130:131], v[110:113], off offset:256 sc1
	s_mov_b32 s3, 0x80000
	s_mov_b64 s[6:7], 0x80000
	v_or_b32_e32 v110, 16, v158
	v_ashrrev_i32_e32 v111, 31, v110
	v_lshlrev_b64 v[110:111], 12, v[110:111]
	v_cndmask_b32_e64 v112, v164, 1.0, s[92:93]
	v_lshl_add_u64 v[110:111], s[58:59], 0, v[110:111]
	v_pk_mul_f32 v[116:117], v[116:117], v[112:113] op_sel_hi:[1,0]
	v_pk_mul_f32 v[114:115], v[114:115], v[112:113] op_sel_hi:[1,0]
	v_pk_mul_f32 v[118:119], v[108:109], v[112:113] op_sel_hi:[1,0]
	v_pk_mul_f32 v[108:109], v[106:107], v[112:113] op_sel_hi:[1,0]
	v_lshl_add_u64 v[110:111], v[110:111], 0, v[136:137]
	v_cvt_pk_bf16_f32 v106, v114, v115
	v_cvt_pk_bf16_f32 v107, v116, v117
	v_cvt_pk_bf16_f32 v108, v108, v109
	v_cvt_pk_bf16_f32 v109, v118, v119
	global_store_dwordx4 v[110:111], v[106:109], off sc1
	v_pk_mul_f32 v[104:105], v[104:105], v[112:113] op_sel_hi:[1,0]
	v_pk_mul_f32 v[102:103], v[102:103], v[112:113] op_sel_hi:[1,0]
	v_pk_mul_f32 v[106:107], v[96:97], v[112:113] op_sel_hi:[1,0]
	v_pk_mul_f32 v[96:97], v[94:95], v[112:113] op_sel_hi:[1,0]
	v_cvt_pk_bf16_f32 v94, v102, v103
	v_cvt_pk_bf16_f32 v95, v104, v105
	v_cvt_pk_bf16_f32 v96, v96, v97
	v_cvt_pk_bf16_f32 v97, v106, v107
	global_store_dwordx4 v[110:111], v[94:97], off offset:256 sc1
	s_nop 1
	v_or_b32_e32 v94, 32, v158
	v_ashrrev_i32_e32 v95, 31, v94
	v_lshlrev_b64 v[94:95], 12, v[94:95]
	v_cndmask_b32_e64 v96, v168, 1.0, s[92:93]
	v_lshl_add_u64 v[94:95], s[58:59], 0, v[94:95]
	v_pk_mul_f32 v[100:101], v[100:101], v[96:97] op_sel_hi:[1,0]
	v_pk_mul_f32 v[98:99], v[98:99], v[96:97] op_sel_hi:[1,0]
	v_pk_mul_f32 v[102:103], v[92:93], v[96:97] op_sel_hi:[1,0]
	v_pk_mul_f32 v[92:93], v[90:91], v[96:97] op_sel_hi:[1,0]
	v_lshl_add_u64 v[94:95], v[94:95], 0, v[136:137]
	v_cvt_pk_bf16_f32 v90, v98, v99
	v_cvt_pk_bf16_f32 v91, v100, v101
	v_cvt_pk_bf16_f32 v92, v92, v93
	v_cvt_pk_bf16_f32 v93, v102, v103
	global_store_dwordx4 v[94:95], v[90:93], off sc1
	v_pk_mul_f32 v[88:89], v[88:89], v[96:97] op_sel_hi:[1,0]
	v_pk_mul_f32 v[86:87], v[86:87], v[96:97] op_sel_hi:[1,0]
	v_pk_mul_f32 v[90:91], v[80:81], v[96:97] op_sel_hi:[1,0]
	v_pk_mul_f32 v[80:81], v[78:79], v[96:97] op_sel_hi:[1,0]
	v_cvt_pk_bf16_f32 v78, v86, v87
	v_cvt_pk_bf16_f32 v79, v88, v89
	v_cvt_pk_bf16_f32 v80, v80, v81
	v_cvt_pk_bf16_f32 v81, v90, v91
	global_store_dwordx4 v[94:95], v[78:81], off offset:256 sc1
	s_nop 1
	v_or_b32_e32 v78, 48, v158
	v_ashrrev_i32_e32 v79, 31, v78
	v_lshlrev_b64 v[78:79], 12, v[78:79]
	v_cndmask_b32_e64 v80, v167, 1.0, s[92:93]
	v_lshl_add_u64 v[78:79], s[58:59], 0, v[78:79]
	v_pk_mul_f32 v[84:85], v[84:85], v[80:81] op_sel_hi:[1,0]
	v_pk_mul_f32 v[82:83], v[82:83], v[80:81] op_sel_hi:[1,0]
	v_pk_mul_f32 v[86:87], v[76:77], v[80:81] op_sel_hi:[1,0]
	v_pk_mul_f32 v[76:77], v[74:75], v[80:81] op_sel_hi:[1,0]
	v_lshl_add_u64 v[78:79], v[78:79], 0, v[136:137]
	v_cvt_pk_bf16_f32 v74, v82, v83
	v_cvt_pk_bf16_f32 v75, v84, v85
	v_cvt_pk_bf16_f32 v76, v76, v77
	v_cvt_pk_bf16_f32 v77, v86, v87
	global_store_dwordx4 v[78:79], v[74:77], off sc1
	v_pk_mul_f32 v[72:73], v[72:73], v[80:81] op_sel_hi:[1,0]
	v_pk_mul_f32 v[70:71], v[70:71], v[80:81] op_sel_hi:[1,0]
	v_pk_mul_f32 v[74:75], v[68:69], v[80:81] op_sel_hi:[1,0]
	v_pk_mul_f32 v[68:69], v[66:67], v[80:81] op_sel_hi:[1,0]
	v_cvt_pk_bf16_f32 v66, v70, v71
; #define PG8_BAR __builtin_amdgcn_s_barrier()
;     __device__ __forceinline__ void operator()(f32x4 (&acc)[2][2][4][2], const Unit& u, int wr, int wc, int fr, int fq) const {
;     ...
;             for (int m = 0; m < 4; ++m) { const int row = row0 + ai * HALF + m * 16; bf16_t* rowp = O + (size_t)row * ldc + col0;
;                 const float rs = ssq ? rsv[ai * 4 + m] : 1.0f;
; #pragma unroll
;                 for (int bj = 0; bj < 2; ++bj) { f32x4 v0 = acc[ai][bj][m][0] * rs, v1 = acc[ai][bj][m][1] * rs;
;                     if (ACT == 2) {
; #pragma unroll
;                         for (int j = 0; j < 4; ++j) { float a = v0[j] > 0.f ? v0[j] : 0.f; v0[j] = a * a; float b = v1[j] > 0.f ? v1[j] : 0.f; v1[j] = b * b; } }
;                     u32x4 w; w.x = cvt_pk_bf16(v0[0], v0[1]); w.y = cvt_pk_bf16(v0[2], v0[3]); w.z = cvt_pk_bf16(v1[0], v1[1]); w.w = cvt_pk_bf16(v1[2], v1[3]);
;                     *(u32x4*)(rowp + bj * HALF) = w; } }
; template <class Epi>
; __device__ __forceinline__ void gemm_phase(LAS unsigned char* lds, const Gemm g, const StaticOrder& S, const Epi& E) {
;     ...
;         cur = nxt; cA = nA; cB = nB; ++ui;
;         if (wr == 1) PG8_BAR;
	v_cvt_pk_bf16_f32 v67, v72, v73
	v_cvt_pk_bf16_f32 v68, v68, v69
	v_cvt_pk_bf16_f32 v69, v74, v75
	global_store_dwordx4 v[78:79], v[66:69], off offset:256 sc1
	s_nop 1
	v_cndmask_b32_e64 v68, v139, 1.0, s[92:93]
	v_pk_mul_f32 v[62:63], v[62:63], v[68:69] op_sel_hi:[1,0]
	v_pk_mul_f32 v[64:65], v[64:65], v[68:69] op_sel_hi:[1,0]
	v_pk_mul_f32 v[70:71], v[60:61], v[68:69] op_sel_hi:[1,0]
	v_pk_mul_f32 v[60:61], v[58:59], v[68:69] op_sel_hi:[1,0]
	v_cvt_pk_bf16_f32 v58, v62, v63
	v_add_co_u32_e32 v62, vcc, s3, v130
	v_cvt_pk_bf16_f32 v59, v64, v65
	v_cvt_pk_bf16_f32 v60, v60, v61
	v_cvt_pk_bf16_f32 v61, v70, v71
	v_addc_co_u32_e32 v63, vcc, 0, v131, vcc
	global_store_dwordx4 v[62:63], v[58:61], off sc1
	v_pk_mul_f32 v[52:53], v[52:53], v[68:69] op_sel_hi:[1,0]
	v_pk_mul_f32 v[50:51], v[50:51], v[68:69] op_sel_hi:[1,0]
	v_pk_mul_f32 v[58:59], v[44:45], v[68:69] op_sel_hi:[1,0]
	v_pk_mul_f32 v[44:45], v[42:43], v[68:69] op_sel_hi:[1,0]
	v_lshl_add_u64 v[66:67], v[130:131], 0, s[6:7]
	v_cvt_pk_bf16_f32 v42, v50, v51
	v_cvt_pk_bf16_f32 v43, v52, v53
	v_cvt_pk_bf16_f32 v44, v44, v45
	v_cvt_pk_bf16_f32 v45, v58, v59
	v_cndmask_b32_e64 v52, v138, 1.0, s[92:93]
	global_store_dwordx4 v[66:67], v[42:45], off offset:256 sc1
	v_pk_mul_f32 v[46:47], v[46:47], v[52:53] op_sel_hi:[1,0]
	s_mov_b32 s3, 0x90000
	v_pk_mul_f32 v[44:45], v[56:57], v[52:53] op_sel_hi:[1,0]
	v_pk_mul_f32 v[42:43], v[54:55], v[52:53] op_sel_hi:[1,0]
	v_pk_mul_f32 v[48:49], v[48:49], v[52:53] op_sel_hi:[1,0]
	v_cvt_pk_bf16_f32 v42, v42, v43
	v_cvt_pk_bf16_f32 v43, v44, v45
	v_cvt_pk_bf16_f32 v44, v46, v47
	v_add_co_u32_e32 v46, vcc, s3, v130
	v_cvt_pk_bf16_f32 v45, v48, v49
	s_nop 0
	v_addc_co_u32_e32 v47, vcc, 0, v131, vcc
	s_mov_b64 s[6:7], 0x90000
	global_store_dwordx4 v[46:47], v[42:45], off sc1
	v_pk_mul_f32 v[36:37], v[36:37], v[52:53] op_sel_hi:[1,0]
	v_pk_mul_f32 v[34:35], v[34:35], v[52:53] op_sel_hi:[1,0]
	v_pk_mul_f32 v[42:43], v[28:29], v[52:53] op_sel_hi:[1,0]
	v_pk_mul_f32 v[28:29], v[26:27], v[52:53] op_sel_hi:[1,0]
	v_lshl_add_u64 v[50:51], v[130:131], 0, s[6:7]
	v_cvt_pk_bf16_f32 v26, v34, v35
	v_cvt_pk_bf16_f32 v27, v36, v37
	v_cvt_pk_bf16_f32 v28, v28, v29
	v_cvt_pk_bf16_f32 v29, v42, v43
	v_cndmask_b32_e64 v36, v133, 1.0, s[92:93]
	global_store_dwordx4 v[50:51], v[26:29], off offset:256 sc1
	v_pk_mul_f32 v[30:31], v[30:31], v[36:37] op_sel_hi:[1,0]
	s_mov_b32 s3, 0xa0000
	v_pk_mul_f32 v[28:29], v[40:41], v[36:37] op_sel_hi:[1,0]
	v_pk_mul_f32 v[26:27], v[38:39], v[36:37] op_sel_hi:[1,0]
	v_pk_mul_f32 v[32:33], v[32:33], v[36:37] op_sel_hi:[1,0]
	v_cvt_pk_bf16_f32 v26, v26, v27
	v_cvt_pk_bf16_f32 v27, v28, v29
	v_cvt_pk_bf16_f32 v28, v30, v31
	v_add_co_u32_e32 v30, vcc, s3, v130
	v_cvt_pk_bf16_f32 v29, v32, v33
	s_nop 0
	v_addc_co_u32_e32 v31, vcc, 0, v131, vcc
	s_mov_b64 s[6:7], 0xa0000
	global_store_dwordx4 v[30:31], v[26:29], off sc1
	v_pk_mul_f32 v[20:21], v[20:21], v[36:37] op_sel_hi:[1,0]
	v_pk_mul_f32 v[18:19], v[18:19], v[36:37] op_sel_hi:[1,0]
	v_pk_mul_f32 v[26:27], v[12:13], v[36:37] op_sel_hi:[1,0]
	v_pk_mul_f32 v[12:13], v[10:11], v[36:37] op_sel_hi:[1,0]
	v_lshl_add_u64 v[34:35], v[130:131], 0, s[6:7]
	v_cvt_pk_bf16_f32 v10, v18, v19
	v_cvt_pk_bf16_f32 v11, v20, v21
	v_cvt_pk_bf16_f32 v12, v12, v13
	v_cvt_pk_bf16_f32 v13, v26, v27
	v_cndmask_b32_e64 v20, v132, 1.0, s[92:93]
	global_store_dwordx4 v[34:35], v[10:13], off offset:256 sc1
	v_pk_mul_f32 v[14:15], v[14:15], v[20:21] op_sel_hi:[1,0]
	s_mov_b32 s3, 0xb0000
	v_pk_mul_f32 v[12:13], v[24:25], v[20:21] op_sel_hi:[1,0]
	v_pk_mul_f32 v[10:11], v[22:23], v[20:21] op_sel_hi:[1,0]
	v_pk_mul_f32 v[16:17], v[16:17], v[20:21] op_sel_hi:[1,0]
	v_cvt_pk_bf16_f32 v10, v10, v11
	v_cvt_pk_bf16_f32 v11, v12, v13
	v_cvt_pk_bf16_f32 v12, v14, v15
	v_add_co_u32_e32 v14, vcc, s3, v130
	v_cvt_pk_bf16_f32 v13, v16, v17
	s_nop 0
	v_addc_co_u32_e32 v15, vcc, 0, v131, vcc
	s_mov_b64 s[6:7], 0xb0000
	global_store_dwordx4 v[14:15], v[10:13], off sc1
	v_pk_mul_f32 v[8:9], v[8:9], v[20:21] op_sel_hi:[1,0]
	v_pk_mul_f32 v[6:7], v[6:7], v[20:21] op_sel_hi:[1,0]
	v_pk_mul_f32 v[10:11], v[4:5], v[20:21] op_sel_hi:[1,0]
	v_pk_mul_f32 v[4:5], v[2:3], v[20:21] op_sel_hi:[1,0]
	v_lshl_add_u64 v[18:19], v[130:131], 0, s[6:7]
	v_cvt_pk_bf16_f32 v2, v6, v7
	v_cvt_pk_bf16_f32 v3, v8, v9
	v_cvt_pk_bf16_f32 v4, v4, v5
	v_cvt_pk_bf16_f32 v5, v10, v11
	s_andn2_b64 vcc, exec, s[4:5]
	s_mov_b64 s[4:5], -1
	global_store_dwordx4 v[18:19], v[2:5], off offset:256 sc1
	s_cbranch_vccnz .LBB0_1099
	s_andn2_b64 vcc, exec, s[8:9]
	s_cbranch_vccnz .LBB0_1098
	s_barrier
	s_branch .LBB0_1098

; __device__ __forceinline__ float sigmoidf_(float x) { return __builtin_amdgcn_rcpf(1.0f + __expf(-x)); }
; __device__ __forceinline__ float ssq4(const f32x4 o) { return (o[0] * o[0] + o[1] * o[1]) + (o[2] * o[2] + o[3] * o[3]); }
;     __device__ __forceinline__ void operator()(f32x4 (&acc)[2][2][4][2], const Unit& u, int wr, int wc, int fr, int fq) const {
;         const int ch0 = u.pn * HALF + wc * 32 + 4 * fq;
;         float s[2][4];
;         f32x4 cur[4][2], nxt[4][2];
; #pragma unroll
;         for (int q = 0; q < 4; ++q)
; #pragma unroll
;             for (int n = 0; n < 2; ++n) cur[q][n] = *(const f32x4*)(h + (size_t)EPI_ROW(q) * D + ch0 + n * 16);
; #pragma unroll
;         for (int k = 0; k < 2; ++k) {
;             if (k < 1) {
; #pragma unroll
;                 for (int q = 0; q < 4; ++q)
; #pragma unroll
;                     for (int n = 0; n < 2; ++n) nxt[q][n] = *(const f32x4*)(h + (size_t)EPI_ROW(4 + q) * D + ch0 + n * 16);
;             }
;             asm volatile("" ::: "memory");
; #pragma unroll
;             for (int q = 0; q < 4; ++q) { const int r = 4 * k + q, ai = r >> 2, m = r & 3; const size_t off = (size_t)EPI_ROW(r) * D + ch0; float sr = 0.f;
; #pragma unroll
;                 for (int n = 0; n < 2; ++n) { const f32x4 b = cur[q][n]; const f32x4 v = acc[ai][0][m][n], g = acc[ai][1][m][n]; f32x4 o;
; #pragma unroll
;                     for (int j = 0; j < 4; ++j) o[j] = b[j] + v[j] * sigmoidf_(g[j]);
;                     *(f32x4*)(h + off + n * 16) = o; u32x2 w; w.x = cvt_pk_bf16(o[0], o[1]); w.y = cvt_pk_bf16(o[2], o[3]); *(u32x2*)(hb + off + n * 16) = w; sr += ssq4(o); }
.LBB0_1327:
	v_mov_b32_e32 v185, v246
	s_lshl_b32 s3, s6, 7
	s_or_b32 s3, s3, s34
	v_bfe_u32 v184, v185, 4, 2
	s_lshl_b32 s7, s22, 8
	v_and_b32_e32 v183, 15, v185
	v_lshl_or_b32 v176, v184, 2, s3
	s_add_i32 s3, s7, s33
	v_or_b32_e32 v188, s3, v183
	v_ashrrev_i32_e32 v177, 31, v176
	v_ashrrev_i32_e32 v189, 31, v188
	v_lshl_add_u64 v[174:175], v[176:177], 2, s[36:37]
	v_lshlrev_b64 v[130:131], 13, v[188:189]
	v_lshl_add_u64 v[216:217], v[174:175], 0, v[130:131]
	global_load_dwordx4 v[192:195], v[216:217], off
	global_load_dwordx4 v[196:199], v[216:217], off offset:64
	v_mul_f32_e32 v114, 0xbfb8aa3b, v114
	s_addk_i32 s3, 0x80
	v_mul_f32_e32 v115, 0xbfb8aa3b, v115
	v_exp_f32_e32 v138, v114
	v_or_b32_e32 v114, s3, v183
	v_or_b32_e32 v218, 16, v188
	v_mul_f32_e32 v126, 0xbfb8aa3b, v126
	v_mul_f32_e32 v128, 0xbfb8aa3b, v128
	v_exp_f32_e32 v186, v115
	v_ashrrev_i32_e32 v115, 31, v114
	v_ashrrev_i32_e32 v219, 31, v218
	v_exp_f32_e32 v134, v126
	v_exp_f32_e32 v136, v128
	v_or_b32_e32 v126, 16, v114
	v_or_b32_e32 v128, 32, v114
	v_or_b32_e32 v130, 48, v114
	v_lshlrev_b64 v[114:115], 13, v[114:115]
	v_lshlrev_b64 v[132:133], 13, v[218:219]
	v_lshl_add_u64 v[222:223], v[174:175], 0, v[132:133]
	v_lshl_add_u64 v[114:115], v[174:175], 0, v[114:115]
	global_load_dwordx4 v[200:203], v[222:223], off
	global_load_dwordx4 v[154:157], v[114:115], off
	global_load_dwordx4 v[150:153], v[114:115], off offset:64
	global_load_dwordx4 v[204:207], v[222:223], off offset:64
	v_mul_f32_e32 v127, 0xbfb8aa3b, v127
	v_mul_f32_e32 v129, 0xbfb8aa3b, v129
	v_exp_f32_e32 v135, v127
	v_exp_f32_e32 v137, v129
	v_or_b32_e32 v220, 32, v188
	v_or_b32_e32 v190, 48, v188
	v_ashrrev_i32_e32 v221, 31, v220
	v_ashrrev_i32_e32 v127, 31, v126
	v_ashrrev_i32_e32 v129, 31, v128
	v_ashrrev_i32_e32 v131, 31, v130
	v_ashrrev_i32_e32 v191, 31, v190
	v_add_f32_e32 v139, 1.0, v134
	v_add_f32_e32 v140, 1.0, v135
	v_lshlrev_b64 v[134:135], 13, v[220:221]
	v_lshlrev_b64 v[126:127], 13, v[126:127]
	v_lshlrev_b64 v[128:129], 13, v[128:129]
	v_lshlrev_b64 v[130:131], 13, v[130:131]
	v_lshlrev_b64 v[132:133], 11, v[188:189]
	v_add_f32_e32 v141, 1.0, v136
	v_add_f32_e32 v142, 1.0, v137
	v_lshlrev_b64 v[136:137], 13, v[190:191]
	v_lshl_add_u64 v[230:231], v[174:175], 0, v[134:135]
	v_lshl_add_u64 v[114:115], v[174:175], 0, v[126:127]
	v_lshl_add_u64 v[126:127], v[174:175], 0, v[128:129]
	v_lshl_add_u64 v[128:129], v[174:175], 0, v[130:131]
	v_add_f32_e32 v187, 1.0, v138
	v_lshl_add_u64 v[224:225], v[132:133], 0, v[176:177]
	v_rcp_f32_e32 v226, v139
	v_rcp_f32_e32 v227, v140
	v_rcp_f32_e32 v228, v141
	v_rcp_f32_e32 v229, v142
	v_lshl_add_u64 v[178:179], v[174:175], 0, v[136:137]
	global_load_dwordx4 v[208:211], v[230:231], off
	global_load_dwordx4 v[212:215], v[230:231], off offset:64
	global_load_dwordx4 v[162:165], v[178:179], off
	global_load_dwordx4 v[158:161], v[178:179], off offset:64
	global_load_dwordx4 v[146:149], v[114:115], off
	global_load_dwordx4 v[142:145], v[114:115], off offset:64
	global_load_dwordx4 v[138:141], v[126:127], off
	global_load_dwordx4 v[134:137], v[126:127], off offset:64
	global_load_dwordx4 v[130:133], v[128:129], off
	s_nop 0
	global_load_dwordx4 v[126:129], v[128:129], off offset:64
	v_mul_f32_e32 v116, 0xbfb8aa3b, v116
	v_mul_f32_e32 v117, 0xbfb8aa3b, v117
	v_exp_f32_e32 v116, v116
	v_exp_f32_e32 v117, v117
	v_mul_f32_e32 v106, 0xbfb8aa3b, v106
	v_mul_f32_e32 v107, 0xbfb8aa3b, v107
	v_mul_f32_e32 v108, 0xbfb8aa3b, v108
	v_mul_f32_e32 v109, 0xbfb8aa3b, v109
	v_mul_f32_e32 v98, 0xbfb8aa3b, v98
	v_mul_f32_e32 v99, 0xbfb8aa3b, v99
	v_mul_f32_e32 v100, 0xbfb8aa3b, v100
	v_mul_f32_e32 v101, 0xbfb8aa3b, v101
	v_exp_f32_e32 v106, v106
	v_exp_f32_e32 v107, v107
	v_exp_f32_e32 v108, v108
	v_exp_f32_e32 v109, v109
	v_exp_f32_e32 v98, v98
	v_exp_f32_e32 v99, v99
	v_exp_f32_e32 v100, v100
	v_exp_f32_e32 v101, v101
	v_add_f32_e32 v186, 1.0, v186
	v_add_f32_e32 v116, 1.0, v116
	v_add_f32_e32 v117, 1.0, v117
	s_waitcnt vmcnt(0)
	v_pk_fma_f32 v[122:123], v[122:123], v[226:227], v[192:193]
	v_rcp_f32_e32 v192, v187
	v_rcp_f32_e32 v193, v186
	v_rcp_f32_e32 v116, v116
	v_rcp_f32_e32 v117, v117
	v_mul_f32_e32 v90, 0xbfb8aa3b, v90
	v_mul_f32_e32 v91, 0xbfb8aa3b, v91
	v_mul_f32_e32 v92, 0xbfb8aa3b, v92
	v_mul_f32_e32 v93, 0xbfb8aa3b, v93
	v_mul_f32_e32 v82, 0xbfb8aa3b, v82
	v_mul_f32_e32 v83, 0xbfb8aa3b, v83
	v_mul_f32_e32 v84, 0xbfb8aa3b, v84
	v_mul_f32_e32 v85, 0xbfb8aa3b, v85
	v_exp_f32_e32 v90, v90
	v_exp_f32_e32 v91, v91
	v_exp_f32_e32 v92, v92
	v_exp_f32_e32 v93, v93
	v_exp_f32_e32 v82, v82
	v_exp_f32_e32 v83, v83
	v_exp_f32_e32 v84, v84
	v_exp_f32_e32 v85, v85
	v_pk_fma_f32 v[124:125], v[124:125], v[228:229], v[194:195]
	v_add_f32_e32 v106, 1.0, v106
	v_add_f32_e32 v107, 1.0, v107
	v_add_f32_e32 v108, 1.0, v108
	v_add_f32_e32 v109, 1.0, v109
	v_add_f32_e32 v98, 1.0, v98
	v_add_f32_e32 v99, 1.0, v99
	v_add_f32_e32 v100, 1.0, v100
	v_add_f32_e32 v101, 1.0, v101
	v_cvt_pk_bf16_f32 v114, v122, v123
	v_cvt_pk_bf16_f32 v115, v124, v125
	v_lshl_add_u64 v[194:195], v[224:225], 1, s[54:55]
	v_rcp_f32_e32 v106, v106
	v_rcp_f32_e32 v107, v107
	v_rcp_f32_e32 v108, v108
	v_rcp_f32_e32 v109, v109
	v_rcp_f32_e32 v98, v98
	v_rcp_f32_e32 v99, v99
	v_rcp_f32_e32 v100, v100
	v_rcp_f32_e32 v101, v101
	v_mul_f32_e32 v74, 0xbfb8aa3b, v74
	v_mul_f32_e32 v75, 0xbfb8aa3b, v75
	v_mul_f32_e32 v76, 0xbfb8aa3b, v76
	v_mul_f32_e32 v77, 0xbfb8aa3b, v77
	v_mul_f32_e32 v66, 0xbfb8aa3b, v66
	v_mul_f32_e32 v67, 0xbfb8aa3b, v67
	v_mul_f32_e32 v68, 0xbfb8aa3b, v68
	v_mul_f32_e32 v69, 0xbfb8aa3b, v69
	global_store_dwordx4 v[216:217], v[122:125], off sc1
	global_store_dwordx2 v[194:195], v[114:115], off
; __device__ __forceinline__ float sigmoidf_(float x) { return __builtin_amdgcn_rcpf(1.0f + __expf(-x)); }
; __device__ __forceinline__ float ssq4(const f32x4 o) { return (o[0] * o[0] + o[1] * o[1]) + (o[2] * o[2] + o[3] * o[3]); }
;     __device__ __forceinline__ void operator()(f32x4 (&acc)[2][2][4][2], const Unit& u, int wr, int wc, int fr, int fq) const {
;     ...
;             for (int q = 0; q < 4; ++q) { const int r = 4 * k + q, ai = r >> 2, m = r & 3; const size_t off = (size_t)EPI_ROW(r) * D + ch0; float sr = 0.f;
; #pragma unroll
;                 for (int n = 0; n < 2; ++n) { const f32x4 b = cur[q][n]; const f32x4 v = acc[ai][0][m][n], g = acc[ai][1][m][n]; f32x4 o;
; #pragma unroll
;                     for (int j = 0; j < 4; ++j) o[j] = b[j] + v[j] * sigmoidf_(g[j]);
;                     *(f32x4*)(h + off + n * 16) = o; u32x2 w; w.x = cvt_pk_bf16(o[0], o[1]); w.y = cvt_pk_bf16(o[2], o[3]); *(u32x2*)(hb + off + n * 16) = w; sr += ssq4(o); }
;                 s[ai][m] = sr; }
	v_pk_fma_f32 v[114:115], v[118:119], v[192:193], v[196:197]
	v_pk_fma_f32 v[116:117], v[120:121], v[116:117], v[198:199]
	v_exp_f32_e32 v74, v74
	v_exp_f32_e32 v75, v75
	v_exp_f32_e32 v76, v76
	v_exp_f32_e32 v77, v77
	v_exp_f32_e32 v66, v66
	v_exp_f32_e32 v67, v67
	v_exp_f32_e32 v68, v68
	v_exp_f32_e32 v69, v69
	v_cvt_pk_bf16_f32 v118, v114, v115
	v_cvt_pk_bf16_f32 v119, v116, v117
	v_add_f32_e32 v90, 1.0, v90
	v_add_f32_e32 v91, 1.0, v91
	v_add_f32_e32 v92, 1.0, v92
	v_add_f32_e32 v93, 1.0, v93
	v_add_f32_e32 v82, 1.0, v82
	v_add_f32_e32 v83, 1.0, v83
	v_add_f32_e32 v84, 1.0, v84
	v_add_f32_e32 v85, 1.0, v85
	global_store_dwordx4 v[216:217], v[114:117], off offset:64 sc1
	global_store_dwordx2 v[194:195], v[118:119], off offset:32
	v_lshlrev_b64 v[118:119], 11, v[218:219]
	v_rcp_f32_e32 v90, v90
	v_rcp_f32_e32 v91, v91
	v_rcp_f32_e32 v92, v92
	v_rcp_f32_e32 v93, v93
	v_rcp_f32_e32 v82, v82
	v_rcp_f32_e32 v83, v83
	v_rcp_f32_e32 v84, v84
	v_rcp_f32_e32 v85, v85
	v_lshl_add_u64 v[118:119], v[118:119], 0, v[176:177]
	v_pk_fma_f32 v[106:107], v[110:111], v[106:107], v[200:201]
	v_pk_fma_f32 v[108:109], v[112:113], v[108:109], v[202:203]
	v_pk_fma_f32 v[98:99], v[102:103], v[98:99], v[204:205]
	v_pk_fma_f32 v[100:101], v[104:105], v[100:101], v[206:207]
	v_cvt_pk_bf16_f32 v110, v106, v107
	v_cvt_pk_bf16_f32 v111, v108, v109
	v_lshl_add_u64 v[112:113], v[118:119], 1, s[54:55]
	v_cvt_pk_bf16_f32 v102, v98, v99
	v_cvt_pk_bf16_f32 v103, v100, v101
	v_add_f32_e32 v74, 1.0, v74
	v_add_f32_e32 v75, 1.0, v75
	v_add_f32_e32 v76, 1.0, v76
	v_add_f32_e32 v77, 1.0, v77
	v_add_f32_e32 v66, 1.0, v66
	v_add_f32_e32 v67, 1.0, v67
	v_add_f32_e32 v68, 1.0, v68
	v_add_f32_e32 v69, 1.0, v69
	global_store_dwordx4 v[222:223], v[106:109], off sc1
	global_store_dwordx2 v[112:113], v[110:111], off
	global_store_dwordx4 v[222:223], v[98:101], off offset:64 sc1
	global_store_dwordx2 v[112:113], v[102:103], off offset:32
	v_lshlrev_b64 v[102:103], 11, v[220:221]
	v_rcp_f32_e32 v74, v74
	v_rcp_f32_e32 v75, v75
	v_rcp_f32_e32 v76, v76
	v_rcp_f32_e32 v77, v77
	v_rcp_f32_e32 v66, v66
	v_rcp_f32_e32 v67, v67
	v_rcp_f32_e32 v68, v68
	v_rcp_f32_e32 v69, v69
	v_lshl_add_u64 v[102:103], v[102:103], 0, v[176:177]
	v_pk_fma_f32 v[90:91], v[94:95], v[90:91], v[208:209]
	v_pk_fma_f32 v[92:93], v[96:97], v[92:93], v[210:211]
	v_pk_fma_f32 v[82:83], v[86:87], v[82:83], v[212:213]
	v_pk_fma_f32 v[84:85], v[88:89], v[84:85], v[214:215]
	v_cvt_pk_bf16_f32 v94, v90, v91
	v_cvt_pk_bf16_f32 v95, v92, v93
	v_lshl_add_u64 v[96:97], v[102:103], 1, s[54:55]
	v_cvt_pk_bf16_f32 v86, v82, v83
	v_cvt_pk_bf16_f32 v87, v84, v85
	v_mul_f32_e32 v58, 0xbfb8aa3b, v58
	v_mul_f32_e32 v59, 0xbfb8aa3b, v59
	v_mul_f32_e32 v60, 0xbfb8aa3b, v60
	v_mul_f32_e32 v61, 0xbfb8aa3b, v61
	v_mul_f32_e32 v50, 0xbfb8aa3b, v50
	v_mul_f32_e32 v51, 0xbfb8aa3b, v51
	v_mul_f32_e32 v52, 0xbfb8aa3b, v52
	v_mul_f32_e32 v53, 0xbfb8aa3b, v53
	global_store_dwordx4 v[230:231], v[90:93], off sc1
	global_store_dwordx2 v[96:97], v[94:95], off
	global_store_dwordx4 v[230:231], v[82:85], off offset:64 sc1
	global_store_dwordx2 v[96:97], v[86:87], off offset:32
	v_lshlrev_b64 v[86:87], 11, v[190:191]
	v_exp_f32_e32 v58, v58
	v_exp_f32_e32 v59, v59
	v_exp_f32_e32 v60, v60
	v_exp_f32_e32 v61, v61
	v_exp_f32_e32 v50, v50
	v_exp_f32_e32 v51, v51
	v_exp_f32_e32 v52, v52
	v_exp_f32_e32 v53, v53
	v_lshl_add_u64 v[86:87], v[86:87], 0, v[176:177]
	v_pk_fma_f32 v[74:75], v[78:79], v[74:75], v[162:163]
	v_pk_fma_f32 v[76:77], v[80:81], v[76:77], v[164:165]
	v_pk_fma_f32 v[66:67], v[70:71], v[66:67], v[158:159]
	v_pk_fma_f32 v[68:69], v[72:73], v[68:69], v[160:161]
	v_cvt_pk_bf16_f32 v78, v74, v75
	v_cvt_pk_bf16_f32 v79, v76, v77
	v_lshl_add_u64 v[80:81], v[86:87], 1, s[54:55]
	v_cvt_pk_bf16_f32 v70, v66, v67
	v_cvt_pk_bf16_f32 v71, v68, v69
	global_store_dwordx4 v[178:179], v[74:77], off sc1
	global_store_dwordx2 v[80:81], v[78:79], off
	global_store_dwordx4 v[178:179], v[66:69], off offset:64 sc1
	global_store_dwordx2 v[80:81], v[70:71], off offset:32
	v_pk_mul_f32 v[70:71], v[122:123], v[122:123]
	v_pk_mul_f32 v[72:73], v[124:125], v[124:125]
	v_pk_mul_f32 v[78:79], v[114:115], v[114:115]
	v_pk_mul_f32 v[80:81], v[116:117], v[116:117]
	v_add_f32_e32 v78, v78, v79
	v_add_f32_e32 v80, v80, v81
	v_add_f32_e32 v72, v72, v73
	v_add_f32_e32 v70, v70, v71
	v_add_f32_e32 v58, 1.0, v58
	v_add_f32_e32 v59, 1.0, v59
	v_add_f32_e32 v60, 1.0, v60
	v_add_f32_e32 v61, 1.0, v61
	v_add_f32_e32 v50, 1.0, v50
	v_add_f32_e32 v51, 1.0, v51
	v_add_f32_e32 v52, 1.0, v52
	v_add_f32_e32 v53, 1.0, v53
	v_mul_f32_e32 v42, 0xbfb8aa3b, v42
	v_mul_f32_e32 v43, 0xbfb8aa3b, v43
	v_mul_f32_e32 v44, 0xbfb8aa3b, v44
	v_mul_f32_e32 v45, 0xbfb8aa3b, v45
	v_mul_f32_e32 v34, 0xbfb8aa3b, v34
	v_mul_f32_e32 v35, 0xbfb8aa3b, v35
	v_mul_f32_e32 v36, 0xbfb8aa3b, v36
	v_mul_f32_e32 v37, 0xbfb8aa3b, v37
	v_add_f32_e32 v78, v78, v80
	v_add_f32_e32 v70, v70, v72
	v_rcp_f32_e32 v58, v58
	v_rcp_f32_e32 v59, v59
	v_rcp_f32_e32 v60, v60
	v_rcp_f32_e32 v61, v61
	v_rcp_f32_e32 v50, v50
	v_rcp_f32_e32 v51, v51
	v_rcp_f32_e32 v52, v52
	v_rcp_f32_e32 v53, v53
	v_exp_f32_e32 v42, v42
	v_exp_f32_e32 v43, v43
	v_exp_f32_e32 v44, v44
	v_exp_f32_e32 v45, v45
	v_exp_f32_e32 v34, v34
	v_exp_f32_e32 v35, v35
	v_exp_f32_e32 v36, v36
	v_exp_f32_e32 v37, v37
	v_add_f32_e32 v78, v70, v78
	v_add_u32_e32 v70, 0x80, v188
	v_ashrrev_i32_e32 v71, 31, v70
	v_lshlrev_b64 v[72:73], 11, v[70:71]
	v_lshl_add_u64 v[72:73], v[72:73], 0, v[176:177]
	v_pk_fma_f32 v[58:59], v[62:63], v[58:59], v[154:155]
	v_pk_fma_f32 v[60:61], v[64:65], v[60:61], v[156:157]
	v_lshlrev_b64 v[62:63], 13, v[70:71]
	v_pk_fma_f32 v[50:51], v[54:55], v[50:51], v[150:151]
; __device__ __forceinline__ float sigmoidf_(float x) { return __builtin_amdgcn_rcpf(1.0f + __expf(-x)); }
; __device__ __forceinline__ float shx(float v, int o, int lane) { return __builtin_bit_cast(float, __builtin_amdgcn_ds_bpermute((lane ^ o) << 2, __builtin_bit_cast(int, v))); }
; __device__ __forceinline__ float ssq4(const f32x4 o) { return (o[0] * o[0] + o[1] * o[1]) + (o[2] * o[2] + o[3] * o[3]); }
; template <bool SIXTEEN> __device__ __forceinline__ void tile_ssq(const float (&s)[2][4], const Unit& u, int wr, int wc, int fr, int fq, float* ssq, LAS float* ptab) {
;     ...
;         for (int m = 0; m < 4; ++m) { float v = s[ai][m]; v += shx(v, 16, lane); v += shx(v, 32, lane); if (fq == 0) ptab[(ai * HALF + wr * 64 + m * 16 + fr) * 4 + wc] = v; }
;     __device__ __forceinline__ void operator()(f32x4 (&acc)[2][2][4][2], const Unit& u, int wr, int wc, int fr, int fq) const {
;     ...
;             for (int q = 0; q < 4; ++q) { const int r = 4 * k + q, ai = r >> 2, m = r & 3; const size_t off = (size_t)EPI_ROW(r) * D + ch0; float sr = 0.f;
; #pragma unroll
;                 for (int n = 0; n < 2; ++n) { const f32x4 b = cur[q][n]; const f32x4 v = acc[ai][0][m][n], g = acc[ai][1][m][n]; f32x4 o;
; #pragma unroll
;                     for (int j = 0; j < 4; ++j) o[j] = b[j] + v[j] * sigmoidf_(g[j]);
;                     *(f32x4*)(h + off + n * 16) = o; u32x2 w; w.x = cvt_pk_bf16(o[0], o[1]); w.y = cvt_pk_bf16(o[2], o[3]); *(u32x2*)(hb + off + n * 16) = w; sr += ssq4(o); }
;                 s[ai][m] = sr; }
	v_pk_fma_f32 v[52:53], v[56:57], v[52:53], v[152:153]
	v_add_f32_e32 v42, 1.0, v42
	v_add_f32_e32 v43, 1.0, v43
	v_add_f32_e32 v44, 1.0, v44
	v_add_f32_e32 v45, 1.0, v45
	v_add_f32_e32 v34, 1.0, v34
	v_add_f32_e32 v35, 1.0, v35
	v_add_f32_e32 v36, 1.0, v36
	v_add_f32_e32 v37, 1.0, v37
	v_mul_f32_e32 v26, 0xbfb8aa3b, v26
	v_mul_f32_e32 v27, 0xbfb8aa3b, v27
	v_mul_f32_e32 v28, 0xbfb8aa3b, v28
	v_mul_f32_e32 v29, 0xbfb8aa3b, v29
	v_mul_f32_e32 v18, 0xbfb8aa3b, v18
	v_mul_f32_e32 v19, 0xbfb8aa3b, v19
	v_mul_f32_e32 v20, 0xbfb8aa3b, v20
	v_mul_f32_e32 v21, 0xbfb8aa3b, v21
	v_lshl_add_u64 v[62:63], v[174:175], 0, v[62:63]
	v_cvt_pk_bf16_f32 v64, v58, v59
	v_cvt_pk_bf16_f32 v65, v60, v61
	v_lshl_add_u64 v[70:71], v[72:73], 1, s[54:55]
	v_cvt_pk_bf16_f32 v54, v50, v51
	v_cvt_pk_bf16_f32 v55, v52, v53
	v_rcp_f32_e32 v42, v42
	v_rcp_f32_e32 v43, v43
	v_rcp_f32_e32 v44, v44
	v_rcp_f32_e32 v45, v45
	v_rcp_f32_e32 v34, v34
	v_rcp_f32_e32 v35, v35
	v_rcp_f32_e32 v36, v36
	v_rcp_f32_e32 v37, v37
	v_exp_f32_e32 v26, v26
	v_exp_f32_e32 v27, v27
	v_exp_f32_e32 v28, v28
	v_exp_f32_e32 v29, v29
	v_exp_f32_e32 v18, v18
	v_exp_f32_e32 v19, v19
	v_exp_f32_e32 v20, v20
	v_exp_f32_e32 v21, v21
	global_store_dwordx4 v[62:63], v[58:61], off sc1
	global_store_dwordx2 v[70:71], v[64:65], off
	global_store_dwordx4 v[62:63], v[50:53], off offset:64 sc1
	global_store_dwordx2 v[70:71], v[54:55], off offset:32
	v_add_u32_e32 v54, 0x90, v188
	v_ashrrev_i32_e32 v55, 31, v54
	v_lshlrev_b64 v[56:57], 11, v[54:55]
	v_lshl_add_u64 v[56:57], v[56:57], 0, v[176:177]
	v_pk_fma_f32 v[42:43], v[46:47], v[42:43], v[146:147]
	v_pk_fma_f32 v[44:45], v[48:49], v[44:45], v[148:149]
	v_lshlrev_b64 v[46:47], 13, v[54:55]
	v_pk_fma_f32 v[34:35], v[38:39], v[34:35], v[142:143]
	v_pk_fma_f32 v[36:37], v[40:41], v[36:37], v[144:145]
	v_add_f32_e32 v26, 1.0, v26
	v_add_f32_e32 v27, 1.0, v27
	v_add_f32_e32 v28, 1.0, v28
	v_add_f32_e32 v29, 1.0, v29
	v_add_f32_e32 v18, 1.0, v18
	v_add_f32_e32 v19, 1.0, v19
	v_add_f32_e32 v20, 1.0, v20
	v_add_f32_e32 v21, 1.0, v21
	v_mul_f32_e32 v10, 0xbfb8aa3b, v10
	v_mul_f32_e32 v11, 0xbfb8aa3b, v11
	v_mul_f32_e32 v12, 0xbfb8aa3b, v12
	v_mul_f32_e32 v13, 0xbfb8aa3b, v13
	v_lshl_add_u64 v[46:47], v[174:175], 0, v[46:47]
	v_cvt_pk_bf16_f32 v48, v42, v43
	v_cvt_pk_bf16_f32 v49, v44, v45
	v_lshl_add_u64 v[54:55], v[56:57], 1, s[54:55]
	v_cvt_pk_bf16_f32 v38, v34, v35
	v_cvt_pk_bf16_f32 v39, v36, v37
	v_rcp_f32_e32 v26, v26
	v_rcp_f32_e32 v27, v27
	v_rcp_f32_e32 v28, v28
	v_rcp_f32_e32 v29, v29
	v_rcp_f32_e32 v18, v18
	v_rcp_f32_e32 v19, v19
	v_rcp_f32_e32 v20, v20
	v_rcp_f32_e32 v21, v21
	v_exp_f32_e32 v10, v10
	v_exp_f32_e32 v11, v11
	v_exp_f32_e32 v12, v12
	v_exp_f32_e32 v13, v13
	v_mul_f32_e32 v2, 0xbfb8aa3b, v2
	v_mul_f32_e32 v3, 0xbfb8aa3b, v3
	v_mul_f32_e32 v4, 0xbfb8aa3b, v4
	v_mul_f32_e32 v5, 0xbfb8aa3b, v5
	global_store_dwordx4 v[46:47], v[42:45], off sc1
	global_store_dwordx2 v[54:55], v[48:49], off
	global_store_dwordx4 v[46:47], v[34:37], off offset:64 sc1
	global_store_dwordx2 v[54:55], v[38:39], off offset:32
	v_add_u32_e32 v38, 0xa0, v188
	v_exp_f32_e32 v2, v2
	v_exp_f32_e32 v3, v3
	v_exp_f32_e32 v4, v4
	v_exp_f32_e32 v5, v5
	v_ashrrev_i32_e32 v39, 31, v38
	v_lshlrev_b64 v[40:41], 11, v[38:39]
	v_lshl_add_u64 v[40:41], v[40:41], 0, v[176:177]
	v_pk_fma_f32 v[26:27], v[30:31], v[26:27], v[138:139]
	v_pk_fma_f32 v[28:29], v[32:33], v[28:29], v[140:141]
	v_lshlrev_b64 v[30:31], 13, v[38:39]
	v_pk_fma_f32 v[18:19], v[22:23], v[18:19], v[134:135]
	v_pk_fma_f32 v[20:21], v[24:25], v[20:21], v[136:137]
	v_add_f32_e32 v10, 1.0, v10
	v_add_f32_e32 v11, 1.0, v11
	v_add_f32_e32 v12, 1.0, v12
	v_add_f32_e32 v13, 1.0, v13
	v_lshl_add_u64 v[30:31], v[174:175], 0, v[30:31]
	v_cvt_pk_bf16_f32 v32, v26, v27
	v_cvt_pk_bf16_f32 v33, v28, v29
	v_lshl_add_u64 v[38:39], v[40:41], 1, s[54:55]
	v_cvt_pk_bf16_f32 v22, v18, v19
	v_cvt_pk_bf16_f32 v23, v20, v21
	v_rcp_f32_e32 v10, v10
	v_rcp_f32_e32 v11, v11
	v_rcp_f32_e32 v12, v12
	v_rcp_f32_e32 v13, v13
	v_add_f32_e32 v2, 1.0, v2
	v_add_f32_e32 v3, 1.0, v3
	v_add_f32_e32 v4, 1.0, v4
	v_add_f32_e32 v5, 1.0, v5
	global_store_dwordx4 v[30:31], v[26:29], off sc1
	global_store_dwordx2 v[38:39], v[32:33], off
	global_store_dwordx4 v[30:31], v[18:21], off offset:64 sc1
	global_store_dwordx2 v[38:39], v[22:23], off offset:32
	v_add_u32_e32 v22, 0xb0, v188
	v_rcp_f32_e32 v2, v2
	v_rcp_f32_e32 v3, v3
	v_rcp_f32_e32 v4, v4
	v_rcp_f32_e32 v5, v5
	v_ashrrev_i32_e32 v23, 31, v22
	v_lshlrev_b64 v[24:25], 11, v[22:23]
	v_lshl_add_u64 v[24:25], v[24:25], 0, v[176:177]
	v_pk_fma_f32 v[10:11], v[14:15], v[10:11], v[130:131]
	v_pk_fma_f32 v[12:13], v[16:17], v[12:13], v[132:133]
	v_lshlrev_b64 v[14:15], 13, v[22:23]
	v_lshl_add_u64 v[14:15], v[174:175], 0, v[14:15]
	v_cvt_pk_bf16_f32 v16, v10, v11
	v_cvt_pk_bf16_f32 v17, v12, v13
	v_lshl_add_u64 v[22:23], v[24:25], 1, s[54:55]
	v_pk_fma_f32 v[2:3], v[6:7], v[2:3], v[126:127]
	v_pk_fma_f32 v[4:5], v[8:9], v[4:5], v[128:129]
	v_and_b32_e32 v6, 63, v185
	global_store_dwordx4 v[14:15], v[10:13], off sc1
	global_store_dwordx2 v[22:23], v[16:17], off
	global_store_dwordx4 v[14:15], v[2:5], off offset:64 sc1
	v_lshlrev_b32_e32 v14, 2, v6
	v_xor_b32_e32 v7, 64, v14
	ds_bpermute_b32 v15, v7, v78
	v_cvt_pk_bf16_f32 v8, v2, v3
	v_cvt_pk_bf16_f32 v9, v4, v5
	global_store_dwordx2 v[22:23], v[8:9], off offset:32
	v_xor_b32_e32 v9, 0x80, v14
	s_waitcnt lgkmcnt(0)
	v_add_f32_e32 v14, v78, v15
	ds_bpermute_b32 v15, v9, v14
	v_cmp_eq_u32_e32 vcc, 0, v184
	v_lshl_add_u32 v8, v183, 4, s63
	s_and_saveexec_b64 s[14:15], vcc
	s_cbranch_execz .LBB0_1329
	s_waitcnt lgkmcnt(0)
	v_add_f32_e32 v14, v14, v15
	ds_write_b32 v8, v14

;     __device__ __forceinline__ void operator()(f32x4 (&acc)[2][2][4][2], const Unit& u, int wr, int wc, int fr, int fq) const {
;         const int row0 = u.pm * BM + wr * 64 + fr; const int col0 = u.pn * BM + wc * 32 + 8 * fq;
;         float rsv[8]; if (ssq) rows_rstd(ssq, row0, fr, fq, rsv);
; #pragma unroll
;         for (int ai = 0; ai < 2; ++ai)
; #pragma unroll
;             for (int m = 0; m < 4; ++m) { const int row = row0 + ai * HALF + m * 16; bf16_t* rowp = O + (size_t)row * ldc + col0;
;                 const float rs = ssq ? rsv[ai * 4 + m] : 1.0f;
; #pragma unroll
;                 for (int bj = 0; bj < 2; ++bj) { f32x4 v0 = acc[ai][bj][m][0] * rs, v1 = acc[ai][bj][m][1] * rs;
;                     if (ACT == 2) {
; #pragma unroll
;                         for (int j = 0; j < 4; ++j) { float a = v0[j] > 0.f ? v0[j] : 0.f; v0[j] = a * a; float b = v1[j] > 0.f ? v1[j] : 0.f; v1[j] = b * b; } }
;                     u32x4 w; w.x = cvt_pk_bf16(v0[0], v0[1]); w.y = cvt_pk_bf16(v0[2], v0[3]); w.z = cvt_pk_bf16(v1[0], v1[1]); w.w = cvt_pk_bf16(v1[2], v1[3]);
;                     *(u32x4*)(rowp + bj * HALF) = w; } }
.LBB0_1417:
	s_lshl_b32 s3, s62, 8
	v_lshl_or_b32 v130, v163, 3, s3
	v_or_b32_e32 v132, s42, v130
	v_ashrrev_i32_e32 v133, 31, v132
	v_mov_b64_e32 v[130:131], s[58:59]
	v_cndmask_b32_e64 v140, v165, 1.0, s[92:93]
	v_mad_i64_i32 v[136:137], s[6:7], v158, s90, v[130:131]
	v_lshlrev_b64 v[132:133], 1, v[132:133]
	v_pk_mul_f32 v[128:129], v[128:129], v[140:141] op_sel_hi:[1,0]
	v_pk_mul_f32 v[126:127], v[126:127], v[140:141] op_sel_hi:[1,0]
	v_pk_mul_f32 v[142:143], v[124:125], v[140:141] op_sel_hi:[1,0]
	v_pk_mul_f32 v[124:125], v[122:123], v[140:141] op_sel_hi:[1,0]
	v_lshl_add_u64 v[136:137], v[136:137], 0, v[132:133]
	v_cvt_pk_bf16_f32 v122, v126, v127
	v_cvt_pk_bf16_f32 v123, v128, v129
	v_cvt_pk_bf16_f32 v124, v124, v125
	v_cvt_pk_bf16_f32 v125, v142, v143
	global_store_dwordx4 v[136:137], v[122:125], off sc1
	v_pk_mul_f32 v[116:117], v[116:117], v[140:141] op_sel_hi:[1,0]
	v_pk_mul_f32 v[114:115], v[114:115], v[140:141] op_sel_hi:[1,0]
	v_pk_mul_f32 v[122:123], v[108:109], v[140:141] op_sel_hi:[1,0]
	v_pk_mul_f32 v[108:109], v[106:107], v[140:141] op_sel_hi:[1,0]
	v_cvt_pk_bf16_f32 v106, v114, v115
	v_cvt_pk_bf16_f32 v107, v116, v117
	v_cvt_pk_bf16_f32 v108, v108, v109
	v_cvt_pk_bf16_f32 v109, v122, v123
	global_store_dwordx4 v[136:137], v[106:109], off offset:256 sc1
	v_cndmask_b32_e64 v116, v164, 1.0, s[92:93]
	v_pk_mul_f32 v[112:113], v[112:113], v[116:117] op_sel_hi:[1,0]
	v_or_b32_e32 v106, 16, v158
	v_mad_i64_i32 v[106:107], s[6:7], v106, s90, v[130:131]
	v_lshl_add_u64 v[114:115], v[106:107], 0, v[132:133]
	v_pk_mul_f32 v[108:109], v[120:121], v[116:117] op_sel_hi:[1,0]
	v_pk_mul_f32 v[106:107], v[118:119], v[116:117] op_sel_hi:[1,0]
	v_pk_mul_f32 v[110:111], v[110:111], v[116:117] op_sel_hi:[1,0]
	v_cvt_pk_bf16_f32 v106, v106, v107
	v_cvt_pk_bf16_f32 v107, v108, v109
	v_cvt_pk_bf16_f32 v108, v110, v111
	v_cvt_pk_bf16_f32 v109, v112, v113
	global_store_dwordx4 v[114:115], v[106:109], off sc1
	v_pk_mul_f32 v[100:101], v[100:101], v[116:117] op_sel_hi:[1,0]
	v_pk_mul_f32 v[98:99], v[98:99], v[116:117] op_sel_hi:[1,0]
	v_pk_mul_f32 v[106:107], v[92:93], v[116:117] op_sel_hi:[1,0]
	v_pk_mul_f32 v[92:93], v[90:91], v[116:117] op_sel_hi:[1,0]
	v_cvt_pk_bf16_f32 v90, v98, v99
	v_cvt_pk_bf16_f32 v91, v100, v101
	v_cvt_pk_bf16_f32 v92, v92, v93
	v_cvt_pk_bf16_f32 v93, v106, v107
	global_store_dwordx4 v[114:115], v[90:93], off offset:256 sc1
	v_cndmask_b32_e64 v100, v167, 1.0, s[92:93]
	v_pk_mul_f32 v[96:97], v[96:97], v[100:101] op_sel_hi:[1,0]
	v_or_b32_e32 v90, 32, v158
	v_mad_i64_i32 v[90:91], s[6:7], v90, s90, v[130:131]
	v_lshl_add_u64 v[98:99], v[90:91], 0, v[132:133]
	v_pk_mul_f32 v[92:93], v[104:105], v[100:101] op_sel_hi:[1,0]
	v_pk_mul_f32 v[90:91], v[102:103], v[100:101] op_sel_hi:[1,0]
	v_pk_mul_f32 v[94:95], v[94:95], v[100:101] op_sel_hi:[1,0]
	v_cvt_pk_bf16_f32 v90, v90, v91
	v_cvt_pk_bf16_f32 v91, v92, v93
	v_cvt_pk_bf16_f32 v92, v94, v95
	v_cvt_pk_bf16_f32 v93, v96, v97
	global_store_dwordx4 v[98:99], v[90:93], off sc1
	v_pk_mul_f32 v[84:85], v[84:85], v[100:101] op_sel_hi:[1,0]
	v_pk_mul_f32 v[82:83], v[82:83], v[100:101] op_sel_hi:[1,0]
	v_pk_mul_f32 v[90:91], v[76:77], v[100:101] op_sel_hi:[1,0]
	v_pk_mul_f32 v[76:77], v[74:75], v[100:101] op_sel_hi:[1,0]
	v_cvt_pk_bf16_f32 v74, v82, v83
	v_cvt_pk_bf16_f32 v75, v84, v85
	v_cvt_pk_bf16_f32 v76, v76, v77
	v_cvt_pk_bf16_f32 v77, v90, v91
	global_store_dwordx4 v[98:99], v[74:77], off offset:256 sc1
	v_cndmask_b32_e64 v84, v166, 1.0, s[92:93]
	v_pk_mul_f32 v[80:81], v[80:81], v[84:85] op_sel_hi:[1,0]
	v_or_b32_e32 v74, 48, v158
	v_mad_i64_i32 v[74:75], s[6:7], v74, s90, v[130:131]
	v_lshl_add_u64 v[82:83], v[74:75], 0, v[132:133]
	v_pk_mul_f32 v[76:77], v[88:89], v[84:85] op_sel_hi:[1,0]
	v_pk_mul_f32 v[74:75], v[86:87], v[84:85] op_sel_hi:[1,0]
	v_pk_mul_f32 v[78:79], v[78:79], v[84:85] op_sel_hi:[1,0]
	v_cvt_pk_bf16_f32 v74, v74, v75
	v_cvt_pk_bf16_f32 v75, v76, v77
	v_cvt_pk_bf16_f32 v76, v78, v79
	v_cvt_pk_bf16_f32 v77, v80, v81
	global_store_dwordx4 v[82:83], v[74:77], off sc1
	v_pk_mul_f32 v[72:73], v[72:73], v[84:85] op_sel_hi:[1,0]
	v_pk_mul_f32 v[70:71], v[70:71], v[84:85] op_sel_hi:[1,0]
	v_pk_mul_f32 v[74:75], v[68:69], v[84:85] op_sel_hi:[1,0]
	v_pk_mul_f32 v[68:69], v[66:67], v[84:85] op_sel_hi:[1,0]
	v_cvt_pk_bf16_f32 v66, v70, v71
	v_cvt_pk_bf16_f32 v67, v72, v73
	v_cvt_pk_bf16_f32 v68, v68, v69
; #define PG8_BAR __builtin_amdgcn_s_barrier()
;     __device__ __forceinline__ void operator()(f32x4 (&acc)[2][2][4][2], const Unit& u, int wr, int wc, int fr, int fq) const {
;     ...
;             for (int m = 0; m < 4; ++m) { const int row = row0 + ai * HALF + m * 16; bf16_t* rowp = O + (size_t)row * ldc + col0;
;                 const float rs = ssq ? rsv[ai * 4 + m] : 1.0f;
; #pragma unroll
;                 for (int bj = 0; bj < 2; ++bj) { f32x4 v0 = acc[ai][bj][m][0] * rs, v1 = acc[ai][bj][m][1] * rs;
;                     if (ACT == 2) {
; #pragma unroll
;                         for (int j = 0; j < 4; ++j) { float a = v0[j] > 0.f ? v0[j] : 0.f; v0[j] = a * a; float b = v1[j] > 0.f ? v1[j] : 0.f; v1[j] = b * b; } }
;                     u32x4 w; w.x = cvt_pk_bf16(v0[0], v0[1]); w.y = cvt_pk_bf16(v0[2], v0[3]); w.z = cvt_pk_bf16(v1[0], v1[1]); w.w = cvt_pk_bf16(v1[2], v1[3]);
;                     *(u32x4*)(rowp + bj * HALF) = w; } }
; template <class Epi>
; __device__ __forceinline__ void gemm_phase(LAS unsigned char* lds, const Gemm g, const StaticOrder& S, const Epi& E) {
;     ...
;         if (!has_next) break;
; #pragma unroll
;         for (int a = 0; a < 2; ++a)
; #pragma unroll
;             for (int b = 0; b < 2; ++b)
; #pragma unroll
;                 for (int m = 0; m < 4; ++m)
; #pragma unroll
;                     for (int n = 0; n < 2; ++n) acc[a][b][m][n] = (f32x4){0.f, 0.f, 0.f, 0.f};
;         cur = nxt; cA = nA; cB = nB; ++ui;
;         if (wr == 1) PG8_BAR;
	v_cvt_pk_bf16_f32 v69, v74, v75
	global_store_dwordx4 v[82:83], v[66:69], off offset:256 sc1
	s_andn2_b64 vcc, exec, s[4:5]
	s_mov_b64 s[4:5], -1
	v_add_u32_e32 v66, 0x80, v158
	v_cndmask_b32_e64 v68, v139, 1.0, s[92:93]
	v_mad_i64_i32 v[66:67], s[6:7], v66, s90, v[130:131]
	v_pk_mul_f32 v[64:65], v[64:65], v[68:69] op_sel_hi:[1,0]
	v_pk_mul_f32 v[62:63], v[62:63], v[68:69] op_sel_hi:[1,0]
	v_pk_mul_f32 v[70:71], v[60:61], v[68:69] op_sel_hi:[1,0]
	v_pk_mul_f32 v[60:61], v[58:59], v[68:69] op_sel_hi:[1,0]
	v_lshl_add_u64 v[66:67], v[66:67], 0, v[132:133]
	v_cvt_pk_bf16_f32 v58, v62, v63
	v_cvt_pk_bf16_f32 v59, v64, v65
	v_cvt_pk_bf16_f32 v60, v60, v61
	v_cvt_pk_bf16_f32 v61, v70, v71
	global_store_dwordx4 v[66:67], v[58:61], off sc1
	v_pk_mul_f32 v[52:53], v[52:53], v[68:69] op_sel_hi:[1,0]
	v_pk_mul_f32 v[50:51], v[50:51], v[68:69] op_sel_hi:[1,0]
	v_pk_mul_f32 v[58:59], v[44:45], v[68:69] op_sel_hi:[1,0]
	v_pk_mul_f32 v[44:45], v[42:43], v[68:69] op_sel_hi:[1,0]
	v_cvt_pk_bf16_f32 v42, v50, v51
	v_cvt_pk_bf16_f32 v43, v52, v53
	v_cvt_pk_bf16_f32 v44, v44, v45
	v_cvt_pk_bf16_f32 v45, v58, v59
	global_store_dwordx4 v[66:67], v[42:45], off offset:256 sc1
	v_cndmask_b32_e64 v52, v138, 1.0, s[92:93]
	v_pk_mul_f32 v[48:49], v[48:49], v[52:53] op_sel_hi:[1,0]
	v_add_u32_e32 v42, 0x90, v158
	v_mad_i64_i32 v[42:43], s[6:7], v42, s90, v[130:131]
	v_lshl_add_u64 v[50:51], v[42:43], 0, v[132:133]
	v_pk_mul_f32 v[44:45], v[56:57], v[52:53] op_sel_hi:[1,0]
	v_pk_mul_f32 v[42:43], v[54:55], v[52:53] op_sel_hi:[1,0]
	v_pk_mul_f32 v[46:47], v[46:47], v[52:53] op_sel_hi:[1,0]
	v_cvt_pk_bf16_f32 v42, v42, v43
	v_cvt_pk_bf16_f32 v43, v44, v45
	v_cvt_pk_bf16_f32 v44, v46, v47
	v_cvt_pk_bf16_f32 v45, v48, v49
	global_store_dwordx4 v[50:51], v[42:45], off sc1
	v_pk_mul_f32 v[36:37], v[36:37], v[52:53] op_sel_hi:[1,0]
	v_pk_mul_f32 v[34:35], v[34:35], v[52:53] op_sel_hi:[1,0]
	v_pk_mul_f32 v[42:43], v[28:29], v[52:53] op_sel_hi:[1,0]
	v_pk_mul_f32 v[28:29], v[26:27], v[52:53] op_sel_hi:[1,0]
	v_cvt_pk_bf16_f32 v26, v34, v35
	v_cvt_pk_bf16_f32 v27, v36, v37
	v_cvt_pk_bf16_f32 v28, v28, v29
	v_cvt_pk_bf16_f32 v29, v42, v43
	global_store_dwordx4 v[50:51], v[26:29], off offset:256 sc1
	v_cndmask_b32_e64 v36, v135, 1.0, s[92:93]
	v_pk_mul_f32 v[32:33], v[32:33], v[36:37] op_sel_hi:[1,0]
	v_add_u32_e32 v26, 0xa0, v158
	v_mad_i64_i32 v[26:27], s[6:7], v26, s90, v[130:131]
	v_lshl_add_u64 v[34:35], v[26:27], 0, v[132:133]
	v_pk_mul_f32 v[28:29], v[40:41], v[36:37] op_sel_hi:[1,0]
	v_pk_mul_f32 v[26:27], v[38:39], v[36:37] op_sel_hi:[1,0]
	v_pk_mul_f32 v[30:31], v[30:31], v[36:37] op_sel_hi:[1,0]
	v_cvt_pk_bf16_f32 v26, v26, v27
	v_cvt_pk_bf16_f32 v27, v28, v29
	v_cvt_pk_bf16_f32 v28, v30, v31
	v_cvt_pk_bf16_f32 v29, v32, v33
	global_store_dwordx4 v[34:35], v[26:29], off sc1
	v_pk_mul_f32 v[20:21], v[20:21], v[36:37] op_sel_hi:[1,0]
	v_pk_mul_f32 v[18:19], v[18:19], v[36:37] op_sel_hi:[1,0]
	v_pk_mul_f32 v[26:27], v[12:13], v[36:37] op_sel_hi:[1,0]
	v_pk_mul_f32 v[12:13], v[10:11], v[36:37] op_sel_hi:[1,0]
	v_cvt_pk_bf16_f32 v10, v18, v19
	v_cvt_pk_bf16_f32 v11, v20, v21
	v_cvt_pk_bf16_f32 v12, v12, v13
	v_cvt_pk_bf16_f32 v13, v26, v27
	global_store_dwordx4 v[34:35], v[10:13], off offset:256 sc1
	v_cndmask_b32_e64 v20, v134, 1.0, s[92:93]
	v_pk_mul_f32 v[16:17], v[16:17], v[20:21] op_sel_hi:[1,0]
	v_add_u32_e32 v10, 0xb0, v158
	v_mad_i64_i32 v[10:11], s[6:7], v10, s90, v[130:131]
	v_lshl_add_u64 v[18:19], v[10:11], 0, v[132:133]
	v_pk_mul_f32 v[12:13], v[24:25], v[20:21] op_sel_hi:[1,0]
	v_pk_mul_f32 v[10:11], v[22:23], v[20:21] op_sel_hi:[1,0]
	v_pk_mul_f32 v[14:15], v[14:15], v[20:21] op_sel_hi:[1,0]
	v_cvt_pk_bf16_f32 v10, v10, v11
	v_cvt_pk_bf16_f32 v11, v12, v13
	v_cvt_pk_bf16_f32 v12, v14, v15
	v_cvt_pk_bf16_f32 v13, v16, v17
	global_store_dwordx4 v[18:19], v[10:13], off sc1
	v_pk_mul_f32 v[8:9], v[8:9], v[20:21] op_sel_hi:[1,0]
	v_pk_mul_f32 v[6:7], v[6:7], v[20:21] op_sel_hi:[1,0]
	v_pk_mul_f32 v[10:11], v[4:5], v[20:21] op_sel_hi:[1,0]
	v_pk_mul_f32 v[4:5], v[2:3], v[20:21] op_sel_hi:[1,0]
	v_cvt_pk_bf16_f32 v2, v6, v7
	v_cvt_pk_bf16_f32 v3, v8, v9
	v_cvt_pk_bf16_f32 v4, v4, v5
	v_cvt_pk_bf16_f32 v5, v10, v11
	global_store_dwordx4 v[18:19], v[2:5], off offset:256 sc1
	s_cbranch_vccnz .LBB0_1408
	s_andn2_b64 vcc, exec, s[8:9]
	s_cbranch_vccnz .LBB0_1407
	s_barrier
	s_branch .LBB0_1407

;     __device__ __forceinline__ void operator()(f32x4 (&acc)[2][2][4][2], const Unit& u, int wr, int wc, int fr, int fq) const {
;     ...
;             for (int m = 0; m < 4; ++m) { const int row = row0 + ai * HALF + m * 16; bf16_t* rowp = O + (size_t)row * ldc + col0;
;                 const float rs = ssq ? rsv[ai * 4 + m] : 1.0f;
; #pragma unroll
;                 for (int bj = 0; bj < 2; ++bj) { f32x4 v0 = acc[ai][bj][m][0] * rs, v1 = acc[ai][bj][m][1] * rs;
;                     if (ACT == 2) {
; #pragma unroll
;                         for (int j = 0; j < 4; ++j) { float a = v0[j] > 0.f ? v0[j] : 0.f; v0[j] = a * a; float b = v1[j] > 0.f ? v1[j] : 0.f; v1[j] = b * b; } }
;                     u32x4 w; w.x = cvt_pk_bf16(v0[0], v0[1]); w.y = cvt_pk_bf16(v0[2], v0[3]); w.z = cvt_pk_bf16(v1[0], v1[1]); w.w = cvt_pk_bf16(v1[2], v1[3]);
;                     *(u32x4*)(rowp + bj * HALF) = w; } }
.LBB0_1443:
	v_mov_b32_e32 v139, v246
	s_lshl_b32 s3, s10, 8
	s_add_i32 s3, s3, s74
	v_and_or_b32 v140, v139, 15, s3
	v_lshrrev_b32_e32 v139, 1, v139
	s_lshl_b32 s3, s95, 8
	v_and_or_b32 v139, v139, 24, s3
	v_ashrrev_i32_e32 v141, 31, v140
	v_or_b32_e32 v142, s75, v139
	v_ashrrev_i32_e32 v143, 31, v142
	v_lshlrev_b64 v[144:145], 12, v[140:141]
	v_lshl_add_u64 v[144:145], s[56:57], 0, v[144:145]
	v_lshlrev_b64 v[142:143], 1, v[142:143]
	v_lshl_add_u64 v[144:145], v[144:145], 0, v[142:143]
	s_mov_b32 s3, 0x80000
	s_mov_b64 s[12:13], 0x80000
	v_cvt_pk_bf16_f32 v62, v62, v63
	v_cvt_pk_bf16_f32 v63, v64, v65
	v_cvt_pk_bf16_f32 v64, v58, v59
	v_add_co_u32_e32 v58, vcc, s3, v144
	v_cvt_pk_bf16_f32 v70, v70, v71
	v_cvt_pk_bf16_f32 v71, v72, v73
	v_cvt_pk_bf16_f32 v72, v66, v67
	v_lshl_add_u64 v[66:67], v[144:145], 0, s[12:13]
	v_addc_co_u32_e32 v59, vcc, 0, v145, vcc
	v_cvt_pk_bf16_f32 v46, v46, v47
	v_cvt_pk_bf16_f32 v47, v48, v49
	v_cvt_pk_bf16_f32 v48, v42, v43
	v_cvt_pk_bf16_f32 v49, v44, v45
	s_mov_b32 s3, 0x90000
	v_cvt_pk_bf16_f32 v110, v110, v111
	v_cvt_pk_bf16_f32 v111, v112, v113
	v_cvt_pk_bf16_f32 v112, v106, v107
	v_or_b32_e32 v106, 16, v140
	global_store_dwordx4 v[66:67], v[46:49], off offset:256 sc1
	s_mov_b64 s[12:13], 0x90000
	v_ashrrev_i32_e32 v107, 31, v106
	v_add_co_u32_e32 v48, vcc, s3, v144
	v_cvt_pk_bf16_f32 v94, v94, v95
	v_cvt_pk_bf16_f32 v95, v96, v97
	v_cvt_pk_bf16_f32 v96, v90, v91
	v_or_b32_e32 v90, 32, v140
	v_lshl_add_u64 v[46:47], v[144:145], 0, s[12:13]
	v_addc_co_u32_e32 v49, vcc, 0, v145, vcc
	v_cvt_pk_bf16_f32 v30, v30, v31
	v_cvt_pk_bf16_f32 v31, v32, v33
	v_cvt_pk_bf16_f32 v32, v26, v27
	v_cvt_pk_bf16_f32 v33, v28, v29
	s_mov_b32 s3, 0xa0000
	v_lshlrev_b64 v[106:107], 12, v[106:107]
	v_ashrrev_i32_e32 v91, 31, v90
	v_cvt_pk_bf16_f32 v78, v78, v79
	v_cvt_pk_bf16_f32 v79, v80, v81
	v_cvt_pk_bf16_f32 v80, v74, v75
	v_or_b32_e32 v74, 48, v140
	global_store_dwordx4 v[46:47], v[30:33], off offset:256 sc1
	s_mov_b64 s[12:13], 0xa0000
	v_cvt_pk_bf16_f32 v113, v108, v109
	v_add_co_u32_e32 v32, vcc, s3, v144
	v_lshl_add_u64 v[106:107], s[56:57], 0, v[106:107]
	v_lshlrev_b64 v[90:91], 12, v[90:91]
	v_ashrrev_i32_e32 v75, 31, v74
	v_lshl_add_u64 v[30:31], v[144:145], 0, s[12:13]
	v_addc_co_u32_e32 v33, vcc, 0, v145, vcc
	v_cvt_pk_bf16_f32 v14, v14, v15
	v_cvt_pk_bf16_f32 v15, v16, v17
	v_cvt_pk_bf16_f32 v16, v10, v11
	v_cvt_pk_bf16_f32 v17, v12, v13
	global_store_dwordx4 v[144:145], v[110:113], off offset:256 sc1
	v_cvt_pk_bf16_f32 v97, v92, v93
	v_lshl_add_u64 v[90:91], s[56:57], 0, v[90:91]
	v_lshl_add_u64 v[110:111], v[106:107], 0, v[142:143]
	v_lshlrev_b64 v[74:75], 12, v[74:75]
	global_store_dwordx4 v[30:31], v[14:17], off offset:256 sc1
	global_store_dwordx4 v[110:111], v[94:97], off offset:256 sc1
	v_cvt_pk_bf16_f32 v81, v76, v77
	v_add_co_u32_e32 v16, vcc, 0xb0000, v144
	v_lshl_add_u64 v[94:95], v[90:91], 0, v[142:143]
	v_lshl_add_u64 v[74:75], s[56:57], 0, v[74:75]
	s_mov_b64 s[12:13], 0xb0000
	v_addc_co_u32_e32 v17, vcc, 0, v145, vcc
	v_readlane_b32 s30, v255, 26
	v_cvt_pk_bf16_f32 v126, v126, v127
	v_cvt_pk_bf16_f32 v127, v128, v129
	v_cvt_pk_bf16_f32 v128, v122, v123
	v_cvt_pk_bf16_f32 v129, v124, v125
	v_cvt_pk_bf16_f32 v106, v118, v119
	v_cvt_pk_bf16_f32 v107, v120, v121
	v_cvt_pk_bf16_f32 v108, v114, v115
	v_cvt_pk_bf16_f32 v109, v116, v117
	v_cvt_pk_bf16_f32 v90, v102, v103
	v_cvt_pk_bf16_f32 v91, v104, v105
	v_cvt_pk_bf16_f32 v92, v98, v99
	v_cvt_pk_bf16_f32 v93, v100, v101
	global_store_dwordx4 v[94:95], v[78:81], off offset:256 sc1
	v_cvt_pk_bf16_f32 v76, v82, v83
	v_cvt_pk_bf16_f32 v77, v84, v85
	v_lshl_add_u64 v[78:79], v[74:75], 0, v[142:143]
	v_cvt_pk_bf16_f32 v74, v86, v87
	v_cvt_pk_bf16_f32 v75, v88, v89
	v_cvt_pk_bf16_f32 v73, v68, v69
	v_cvt_pk_bf16_f32 v65, v60, v61
	v_cvt_pk_bf16_f32 v42, v54, v55
	v_cvt_pk_bf16_f32 v43, v56, v57
	v_cvt_pk_bf16_f32 v44, v50, v51
	v_cvt_pk_bf16_f32 v45, v52, v53
	v_cvt_pk_bf16_f32 v26, v38, v39
	v_cvt_pk_bf16_f32 v27, v40, v41
	v_cvt_pk_bf16_f32 v28, v34, v35
	v_cvt_pk_bf16_f32 v29, v36, v37
	v_lshl_add_u64 v[14:15], v[144:145], 0, s[12:13]
	v_cvt_pk_bf16_f32 v10, v22, v23
	v_cvt_pk_bf16_f32 v11, v24, v25
	v_cvt_pk_bf16_f32 v12, v18, v19
	v_cvt_pk_bf16_f32 v13, v20, v21
	v_cvt_pk_bf16_f32 v6, v6, v7
	v_cvt_pk_bf16_f32 v7, v8, v9
	v_cvt_pk_bf16_f32 v8, v2, v3
	v_cvt_pk_bf16_f32 v9, v4, v5
	s_andn2_b64 vcc, exec, s[4:5]
	s_mov_b64 s[4:5], -1
	v_readlane_b32 s31, v255, 27
	global_store_dwordx4 v[144:145], v[126:129], off sc1
	global_store_dwordx4 v[110:111], v[106:109], off sc1
	global_store_dwordx4 v[94:95], v[90:93], off sc1
	global_store_dwordx4 v[78:79], v[74:77], off sc1
	global_store_dwordx4 v[78:79], v[70:73], off offset:256 sc1
	global_store_dwordx4 v[58:59], v[62:65], off sc1
	global_store_dwordx4 v[48:49], v[42:45], off sc1
	global_store_dwordx4 v[32:33], v[26:29], off sc1
	global_store_dwordx4 v[16:17], v[10:13], off sc1
	global_store_dwordx4 v[14:15], v[6:9], off offset:256 sc1
	s_cbranch_vccnz .LBB0_1432
	s_andn2_b64 vcc, exec, s[6:7]
	s_cbranch_vccnz .LBB0_1431
	s_barrier
	s_branch .LBB0_1431

; __device__ __forceinline__ float ssq4(const f32x4 o) { return (o[0] * o[0] + o[1] * o[1]) + (o[2] * o[2] + o[3] * o[3]); }
;     __device__ __forceinline__ void operator()(f32x4 (&acc)[2][2][4][2], const Unit& u, int wr, int wc, int fr, int fq) const {
;     ...
;         f32x4 cur[2][4], nxt[2][4];
; #pragma unroll
;         for (int q = 0; q < 2; ++q)
; #pragma unroll
;             for (int c = 0; c < 4; ++c) cur[q][c] = *(const f32x4*)(base + (size_t)EPI_ROW(q) * D + col0 + (c >> 1) * HALF + (c & 1) * 4);
; #pragma unroll
;         for (int k = 0; k < 4; ++k) {
;             if (k < 3) {
; #pragma unroll
;                 for (int q = 0; q < 2; ++q)
; #pragma unroll
;                     for (int c = 0; c < 4; ++c) nxt[q][c] = *(const f32x4*)(base + (size_t)EPI_ROW(2 * k + 2 + q) * D + col0 + (c >> 1) * HALF + (c & 1) * 4);
;             }
;             asm volatile("" ::: "memory");
; #pragma unroll
;             for (int q = 0; q < 2; ++q) { const int r = 2 * k + q, ai = r >> 2, m = r & 3; const size_t off = (size_t)EPI_ROW(r) * D + col0; float sr = 0.f;
; #pragma unroll
;                 for (int bj = 0; bj < 2; ++bj) { const f32x4 o0 = cur[q][2 * bj] + acc[ai][bj][m][0], o1 = cur[q][2 * bj + 1] + acc[ai][bj][m][1];
;                     *(f32x4*)(out + off + bj * HALF) = o0; *(f32x4*)(out + off + bj * HALF + 4) = o1;
;                     u32x4 w; w.x = cvt_pk_bf16(o0[0], o0[1]); w.y = cvt_pk_bf16(o0[2], o0[3]); w.z = cvt_pk_bf16(o1[0], o1[1]); w.w = cvt_pk_bf16(o1[2], o1[3]); *(u32x4*)(hb + off + bj * HALF) = w; sr += ssq4(o0) + ssq4(o1); }
;                 s[ai][m] = sr; }
.LBB0_2038:
	v_mov_b32_e32 v185, v246
	s_lshl_b32 s1, s6, 8
	s_or_b32 s1, s1, s45
	v_bfe_u32 v184, v185, 4, 2
	v_lshl_or_b32 v200, v184, 3, s1
	s_lshl_b32 s1, s22, 8
	v_and_b32_e32 v183, 15, v185
	s_add_i32 s3, s1, s44
	v_or_b32_e32 v202, s3, v183
	v_readlane_b32 s14, v255, 40
	v_ashrrev_i32_e32 v203, 31, v202
	v_ashrrev_i32_e32 v201, 31, v200
	v_readlane_b32 s15, v255, 41
	v_lshlrev_b64 v[130:131], 13, v[202:203]
	v_or_b32_e32 v178, 16, v202
	v_lshl_add_u64 v[204:205], v[200:201], 2, s[14:15]
	v_lshl_add_u64 v[130:131], v[204:205], 0, v[130:131]
	global_load_dwordx4 v[210:213], v[130:131], off offset:16
	global_load_dwordx4 v[214:217], v[130:131], off
	global_load_dwordx4 v[218:221], v[130:131], off offset:528
	global_load_dwordx4 v[222:225], v[130:131], off offset:512
	v_ashrrev_i32_e32 v179, 31, v178
	v_lshlrev_b64 v[130:131], 13, v[178:179]
	v_lshl_add_u64 v[130:131], v[204:205], 0, v[130:131]
	global_load_dwordx4 v[170:173], v[130:131], off offset:16
	global_load_dwordx4 v[174:177], v[130:131], off
	global_load_dwordx4 v[162:165], v[130:131], off offset:528
	global_load_dwordx4 v[166:169], v[130:131], off offset:512
	v_or_b32_e32 v208, 32, v202
	v_ashrrev_i32_e32 v209, 31, v208
	v_lshlrev_b64 v[130:131], 13, v[208:209]
	v_lshl_add_u64 v[130:131], v[204:205], 0, v[130:131]
	v_or_b32_e32 v206, 48, v202
	global_load_dwordx4 v[154:157], v[130:131], off offset:16
	global_load_dwordx4 v[158:161], v[130:131], off
	global_load_dwordx4 v[138:141], v[130:131], off offset:528
	global_load_dwordx4 v[142:145], v[130:131], off offset:512
	v_ashrrev_i32_e32 v207, 31, v206
	v_lshlrev_b64 v[130:131], 13, v[206:207]
	v_lshl_add_u64 v[134:135], v[204:205], 0, v[130:131]
	global_load_dwordx4 v[146:149], v[134:135], off offset:16
	global_load_dwordx4 v[150:153], v[134:135], off
	global_load_dwordx4 v[130:133], v[134:135], off offset:528
	s_nop 0
	global_load_dwordx4 v[134:137], v[134:135], off offset:512
	v_lshlrev_b64 v[226:227], 11, v[202:203]
	v_lshl_add_u64 v[226:227], v[226:227], 0, v[200:201]
	v_lshlrev_b64 v[208:209], 11, v[208:209]
	v_lshl_add_u64 v[208:209], v[208:209], 0, v[200:201]
	v_cmp_eq_u32_e32 vcc, 0, v184
	s_waitcnt vmcnt(0)
	v_pk_add_f32 v[122:123], v[122:123], v[210:211]
	v_pk_add_f32 v[128:129], v[128:129], v[216:217]
	v_pk_add_f32 v[126:127], v[126:127], v[214:215]
	v_lshl_add_u64 v[214:215], v[226:227], 2, s[36:37]
	v_pk_add_f32 v[124:125], v[124:125], v[212:213]
	global_store_dwordx4 v[214:215], v[126:129], off sc1
	global_store_dwordx4 v[214:215], v[122:125], off offset:16 sc1
	v_cvt_pk_bf16_f32 v210, v126, v127
	v_cvt_pk_bf16_f32 v212, v122, v123
	v_mul_f32_e32 v127, v127, v127
	v_mul_f32_e32 v123, v123, v123
	v_fmac_f32_e32 v127, v126, v126
	v_mul_f32_e32 v126, v129, v129
	v_fmac_f32_e32 v123, v122, v122
	v_mul_f32_e32 v122, v125, v125
	v_fmac_f32_e32 v126, v128, v128
	v_fmac_f32_e32 v122, v124, v124
	v_cvt_pk_bf16_f32 v211, v128, v129
	v_cvt_pk_bf16_f32 v213, v124, v125
	v_lshl_add_u64 v[216:217], v[226:227], 1, s[54:55]
	v_add_f32_e32 v126, v127, v126
	v_add_f32_e32 v122, v123, v122
	v_pk_add_f32 v[120:121], v[120:121], v[224:225]
	v_pk_add_f32 v[118:119], v[118:119], v[222:223]
	v_pk_add_f32 v[114:115], v[114:115], v[218:219]
	global_store_dwordx4 v[216:217], v[210:213], off sc1
	v_add_f32_e32 v126, v126, v122
	v_pk_add_f32 v[116:117], v[116:117], v[220:221]
	global_store_dwordx4 v[214:215], v[118:121], off offset:512 sc1
	global_store_dwordx4 v[214:215], v[114:117], off offset:528 sc1
	v_cvt_pk_bf16_f32 v122, v118, v119
	v_cvt_pk_bf16_f32 v124, v114, v115
	v_mul_f32_e32 v119, v119, v119
	v_mul_f32_e32 v115, v115, v115
	v_fmac_f32_e32 v119, v118, v118
	v_mul_f32_e32 v118, v121, v121
	v_fmac_f32_e32 v115, v114, v114
	v_mul_f32_e32 v114, v117, v117
	v_fmac_f32_e32 v118, v120, v120
	v_fmac_f32_e32 v114, v116, v116
	v_add_f32_e32 v118, v119, v118
	v_add_f32_e32 v114, v115, v114
	v_add_f32_e32 v114, v118, v114
	v_add_f32_e32 v187, v126, v114
	v_lshlrev_b64 v[114:115], 11, v[178:179]
	v_lshl_add_u64 v[118:119], v[114:115], 0, v[200:201]
	v_pk_add_f32 v[112:113], v[112:113], v[176:177]
	v_pk_add_f32 v[110:111], v[110:111], v[174:175]
	v_pk_add_f32 v[108:109], v[108:109], v[172:173]
	v_pk_add_f32 v[106:107], v[106:107], v[170:171]
	v_cvt_pk_bf16_f32 v123, v120, v121
	v_cvt_pk_bf16_f32 v125, v116, v117
	v_lshl_add_u64 v[120:121], v[118:119], 2, s[36:37]
	v_cvt_pk_bf16_f32 v114, v110, v111
	v_cvt_pk_bf16_f32 v115, v112, v113
	v_cvt_pk_bf16_f32 v116, v106, v107
	v_cvt_pk_bf16_f32 v117, v108, v109
	v_lshl_add_u64 v[118:119], v[118:119], 1, s[54:55]
	v_pk_add_f32 v[104:105], v[104:105], v[168:169]
	v_pk_add_f32 v[102:103], v[102:103], v[166:167]
	v_pk_add_f32 v[100:101], v[100:101], v[164:165]
	v_pk_add_f32 v[98:99], v[98:99], v[162:163]
	v_add_u32_e32 v210, 0x80, v202
	global_store_dwordx4 v[216:217], v[122:125], off offset:256 sc1
	global_store_dwordx4 v[120:121], v[110:113], off sc1
	global_store_dwordx4 v[120:121], v[106:109], off offset:16 sc1
	global_store_dwordx4 v[118:119], v[114:117], off sc1
	v_ashrrev_i32_e32 v211, 31, v210
	global_store_dwordx4 v[120:121], v[102:105], off offset:512 sc1
	global_store_dwordx4 v[120:121], v[98:101], off offset:528 sc1
	v_cvt_pk_bf16_f32 v114, v102, v103
	v_cvt_pk_bf16_f32 v115, v104, v105
	v_cvt_pk_bf16_f32 v116, v98, v99
	v_cvt_pk_bf16_f32 v117, v100, v101
	global_store_dwordx4 v[118:119], v[114:117], off offset:256 sc1
	v_add_u32_e32 v170, 0x90, v202
	v_ashrrev_i32_e32 v171, 31, v170
	v_lshlrev_b64 v[114:115], 13, v[210:211]
	v_lshl_add_u64 v[114:115], v[204:205], 0, v[114:115]
	global_load_dwordx4 v[172:175], v[114:115], off offset:16
	global_load_dwordx4 v[176:179], v[114:115], off
; __device__ __forceinline__ float ssq4(const f32x4 o) { return (o[0] * o[0] + o[1] * o[1]) + (o[2] * o[2] + o[3] * o[3]); }
;     __device__ __forceinline__ void operator()(f32x4 (&acc)[2][2][4][2], const Unit& u, int wr, int wc, int fr, int fq) const {
;     ...
;             for (int c = 0; c < 4; ++c) cur[q][c] = *(const f32x4*)(base + (size_t)EPI_ROW(q) * D + col0 + (c >> 1) * HALF + (c & 1) * 4);
; #pragma unroll
;         for (int k = 0; k < 4; ++k) {
;             if (k < 3) {
; #pragma unroll
;                 for (int q = 0; q < 2; ++q)
; #pragma unroll
;                     for (int c = 0; c < 4; ++c) nxt[q][c] = *(const f32x4*)(base + (size_t)EPI_ROW(2 * k + 2 + q) * D + col0 + (c >> 1) * HALF + (c & 1) * 4);
;             }
;             asm volatile("" ::: "memory");
; #pragma unroll
;             for (int q = 0; q < 2; ++q) { const int r = 2 * k + q, ai = r >> 2, m = r & 3; const size_t off = (size_t)EPI_ROW(r) * D + col0; float sr = 0.f;
; #pragma unroll
;                 for (int bj = 0; bj < 2; ++bj) { const f32x4 o0 = cur[q][2 * bj] + acc[ai][bj][m][0], o1 = cur[q][2 * bj + 1] + acc[ai][bj][m][1];
;                     *(f32x4*)(out + off + bj * HALF) = o0; *(f32x4*)(out + off + bj * HALF + 4) = o1;
;                     u32x4 w; w.x = cvt_pk_bf16(o0[0], o0[1]); w.y = cvt_pk_bf16(o0[2], o0[3]); w.z = cvt_pk_bf16(o1[0], o1[1]); w.w = cvt_pk_bf16(o1[2], o1[3]); *(u32x4*)(hb + off + bj * HALF) = w; sr += ssq4(o0) + ssq4(o1); }
;                 s[ai][m] = sr; }
	global_load_dwordx4 v[162:165], v[114:115], off offset:528
	global_load_dwordx4 v[166:169], v[114:115], off offset:512
	v_lshlrev_b64 v[114:115], 13, v[170:171]
	v_pk_add_f32 v[96:97], v[96:97], v[160:161]
	v_pk_add_f32 v[94:95], v[94:95], v[158:159]
	v_pk_add_f32 v[92:93], v[92:93], v[156:157]
	v_pk_add_f32 v[90:91], v[90:91], v[154:155]
	v_pk_add_f32 v[88:89], v[88:89], v[144:145]
	v_pk_add_f32 v[86:87], v[86:87], v[142:143]
	v_pk_add_f32 v[80:81], v[80:81], v[140:141]
	v_pk_add_f32 v[78:79], v[78:79], v[138:139]
	v_lshl_add_u64 v[118:119], v[204:205], 0, v[114:115]
	v_lshl_add_u64 v[158:159], v[208:209], 2, s[36:37]
	v_cvt_pk_bf16_f32 v154, v94, v95
	v_cvt_pk_bf16_f32 v155, v96, v97
	v_cvt_pk_bf16_f32 v156, v90, v91
	v_cvt_pk_bf16_f32 v157, v92, v93
	v_lshl_add_u64 v[160:161], v[208:209], 1, s[54:55]
	v_cvt_pk_bf16_f32 v138, v86, v87
	v_cvt_pk_bf16_f32 v139, v88, v89
	v_cvt_pk_bf16_f32 v140, v78, v79
	v_cvt_pk_bf16_f32 v141, v80, v81
	global_load_dwordx4 v[122:125], v[118:119], off offset:16
	global_load_dwordx4 v[126:129], v[118:119], off
	global_load_dwordx4 v[114:117], v[118:119], off offset:528
	s_nop 0
	global_load_dwordx4 v[118:121], v[118:119], off offset:512
	global_store_dwordx4 v[158:159], v[94:97], off sc1
	global_store_dwordx4 v[158:159], v[90:93], off offset:16 sc1
	global_store_dwordx4 v[160:161], v[154:157], off sc1
	global_store_dwordx4 v[158:159], v[86:89], off offset:512 sc1
	global_store_dwordx4 v[158:159], v[78:81], off offset:528 sc1
	global_store_dwordx4 v[160:161], v[138:141], off offset:256 sc1
	v_pk_add_f32 v[84:85], v[84:85], v[152:153]
	v_pk_add_f32 v[82:83], v[82:83], v[150:151]
	v_lshlrev_b64 v[138:139], 11, v[206:207]
	v_lshl_add_u64 v[142:143], v[138:139], 0, v[200:201]
	v_pk_add_f32 v[76:77], v[76:77], v[148:149]
	v_pk_add_f32 v[74:75], v[74:75], v[146:147]
	v_pk_add_f32 v[72:73], v[72:73], v[136:137]
	v_pk_add_f32 v[70:71], v[70:71], v[134:135]
	v_pk_add_f32 v[68:69], v[68:69], v[132:133]
	v_pk_add_f32 v[66:67], v[66:67], v[130:131]
	v_add_u32_e32 v206, 0xa0, v202
	v_lshl_add_u64 v[144:145], v[142:143], 2, s[36:37]
	v_cvt_pk_bf16_f32 v138, v82, v83
	v_cvt_pk_bf16_f32 v139, v84, v85
	v_cvt_pk_bf16_f32 v140, v74, v75
	v_cvt_pk_bf16_f32 v141, v76, v77
	v_lshl_add_u64 v[142:143], v[142:143], 1, s[54:55]
	v_cvt_pk_bf16_f32 v130, v70, v71
	v_cvt_pk_bf16_f32 v131, v72, v73
	v_cvt_pk_bf16_f32 v132, v66, v67
	v_cvt_pk_bf16_f32 v133, v68, v69
	v_ashrrev_i32_e32 v207, 31, v206
	global_store_dwordx4 v[144:145], v[82:85], off sc1
	global_store_dwordx4 v[144:145], v[74:77], off offset:16 sc1
	global_store_dwordx4 v[142:143], v[138:141], off sc1
	global_store_dwordx4 v[144:145], v[70:73], off offset:512 sc1
	global_store_dwordx4 v[144:145], v[66:69], off offset:528 sc1
	global_store_dwordx4 v[142:143], v[130:133], off offset:256 sc1
	v_add_u32_e32 v202, 0xb0, v202
	v_ashrrev_i32_e32 v203, 31, v202
	v_lshlrev_b64 v[130:131], 13, v[206:207]
	v_lshl_add_u64 v[142:143], v[204:205], 0, v[130:131]
	global_load_dwordx4 v[130:133], v[142:143], off offset:16
	global_load_dwordx4 v[134:137], v[142:143], off
	global_load_dwordx4 v[138:141], v[142:143], off offset:528
	s_nop 0
	global_load_dwordx4 v[142:145], v[142:143], off offset:512
	v_lshlrev_b64 v[146:147], 13, v[202:203]
	v_lshl_add_u64 v[158:159], v[204:205], 0, v[146:147]
	global_load_dwordx4 v[146:149], v[158:159], off offset:16
	global_load_dwordx4 v[150:153], v[158:159], off
	global_load_dwordx4 v[154:157], v[158:159], off offset:528
	s_nop 0
	global_load_dwordx4 v[158:161], v[158:159], off offset:512
	v_lshlrev_b64 v[204:205], 11, v[210:211]
	v_lshl_add_u64 v[204:205], v[204:205], 0, v[200:201]
	s_waitcnt vmcnt(27)
	v_pk_add_f32 v[60:61], v[60:61], v[174:175]
	s_waitcnt vmcnt(26)
	v_pk_add_f32 v[64:65], v[64:65], v[178:179]
	v_pk_add_f32 v[62:63], v[62:63], v[176:177]
	v_pk_add_f32 v[58:59], v[58:59], v[172:173]
	s_waitcnt vmcnt(24)
	v_pk_add_f32 v[56:57], v[56:57], v[168:169]
	v_pk_add_f32 v[54:55], v[54:55], v[166:167]
	v_pk_add_f32 v[48:49], v[48:49], v[164:165]
	v_pk_add_f32 v[46:47], v[46:47], v[162:163]
	v_lshl_add_u64 v[176:177], v[204:205], 2, s[36:37]
	v_cvt_pk_bf16_f32 v172, v62, v63
	v_cvt_pk_bf16_f32 v173, v64, v65
	v_cvt_pk_bf16_f32 v174, v58, v59
	v_cvt_pk_bf16_f32 v175, v60, v61
	v_lshl_add_u64 v[178:179], v[204:205], 1, s[54:55]
	v_cvt_pk_bf16_f32 v162, v54, v55
	v_cvt_pk_bf16_f32 v163, v56, v57
	v_cvt_pk_bf16_f32 v164, v46, v47
	v_cvt_pk_bf16_f32 v165, v48, v49
	global_store_dwordx4 v[176:177], v[62:65], off sc1
	global_store_dwordx4 v[176:177], v[58:61], off offset:16 sc1
	global_store_dwordx4 v[178:179], v[172:175], off sc1
	global_store_dwordx4 v[176:177], v[54:57], off offset:512 sc1
	global_store_dwordx4 v[176:177], v[46:49], off offset:528 sc1
	global_store_dwordx4 v[178:179], v[162:165], off offset:256 sc1
	s_waitcnt vmcnt(28)
; __device__ __forceinline__ float shx(float v, int o, int lane) { return __builtin_bit_cast(float, __builtin_amdgcn_ds_bpermute((lane ^ o) << 2, __builtin_bit_cast(int, v))); }
; __device__ __forceinline__ float ssq4(const f32x4 o) { return (o[0] * o[0] + o[1] * o[1]) + (o[2] * o[2] + o[3] * o[3]); }
; template <bool SIXTEEN> __device__ __forceinline__ void tile_ssq(const float (&s)[2][4], const Unit& u, int wr, int wc, int fr, int fq, float* ssq, LAS float* ptab) {
;     ...
;         for (int m = 0; m < 4; ++m) { float v = s[ai][m]; v += shx(v, 16, lane); v += shx(v, 32, lane); if (fq == 0) ptab[(ai * HALF + wr * 64 + m * 16 + fr) * 4 + wc] = v; }
;     __device__ __forceinline__ void operator()(f32x4 (&acc)[2][2][4][2], const Unit& u, int wr, int wc, int fr, int fq) const {
;     ...
;             for (int q = 0; q < 2; ++q) { const int r = 2 * k + q, ai = r >> 2, m = r & 3; const size_t off = (size_t)EPI_ROW(r) * D + col0; float sr = 0.f;
; #pragma unroll
;                 for (int bj = 0; bj < 2; ++bj) { const f32x4 o0 = cur[q][2 * bj] + acc[ai][bj][m][0], o1 = cur[q][2 * bj + 1] + acc[ai][bj][m][1];
;                     *(f32x4*)(out + off + bj * HALF) = o0; *(f32x4*)(out + off + bj * HALF + 4) = o1;
;                     u32x4 w; w.x = cvt_pk_bf16(o0[0], o0[1]); w.y = cvt_pk_bf16(o0[2], o0[3]); w.z = cvt_pk_bf16(o1[0], o1[1]); w.w = cvt_pk_bf16(o1[2], o1[3]); *(u32x4*)(hb + off + bj * HALF) = w; sr += ssq4(o0) + ssq4(o1); }
;                 s[ai][m] = sr; }
	v_pk_add_f32 v[52:53], v[52:53], v[128:129]
	v_pk_add_f32 v[50:51], v[50:51], v[126:127]
	v_lshlrev_b64 v[162:163], 11, v[170:171]
	v_lshl_add_u64 v[162:163], v[162:163], 0, v[200:201]
	v_pk_add_f32 v[44:45], v[44:45], v[124:125]
	v_pk_add_f32 v[42:43], v[42:43], v[122:123]
	s_waitcnt vmcnt(26)
	v_pk_add_f32 v[40:41], v[40:41], v[120:121]
	v_pk_add_f32 v[38:39], v[38:39], v[118:119]
	v_pk_add_f32 v[36:37], v[36:37], v[116:117]
	v_pk_add_f32 v[34:35], v[34:35], v[114:115]
	v_lshl_add_u64 v[126:127], v[162:163], 2, s[36:37]
	v_cvt_pk_bf16_f32 v122, v50, v51
	v_cvt_pk_bf16_f32 v123, v52, v53
	v_cvt_pk_bf16_f32 v124, v42, v43
	v_cvt_pk_bf16_f32 v125, v44, v45
	v_lshl_add_u64 v[128:129], v[162:163], 1, s[54:55]
	v_cvt_pk_bf16_f32 v114, v38, v39
	v_cvt_pk_bf16_f32 v115, v40, v41
	v_cvt_pk_bf16_f32 v116, v34, v35
	v_cvt_pk_bf16_f32 v117, v36, v37
	global_store_dwordx4 v[126:127], v[50:53], off sc1
	global_store_dwordx4 v[126:127], v[42:45], off offset:16 sc1
	global_store_dwordx4 v[128:129], v[122:125], off sc1
	global_store_dwordx4 v[126:127], v[38:41], off offset:512 sc1
	global_store_dwordx4 v[126:127], v[34:37], off offset:528 sc1
	global_store_dwordx4 v[128:129], v[114:117], off offset:256 sc1
	s_waitcnt vmcnt(19)
	v_pk_add_f32 v[28:29], v[28:29], v[132:133]
	v_lshlrev_b64 v[114:115], 11, v[206:207]
	v_lshl_add_u64 v[118:119], v[114:115], 0, v[200:201]
	s_waitcnt vmcnt(18)
	v_pk_add_f32 v[32:33], v[32:33], v[136:137]
	v_pk_add_f32 v[30:31], v[30:31], v[134:135]
	v_pk_add_f32 v[26:27], v[26:27], v[130:131]
	v_lshl_add_u64 v[120:121], v[118:119], 2, s[36:37]
	v_cvt_pk_bf16_f32 v114, v30, v31
	v_cvt_pk_bf16_f32 v115, v32, v33
	v_cvt_pk_bf16_f32 v116, v26, v27
	v_cvt_pk_bf16_f32 v117, v28, v29
	v_lshl_add_u64 v[118:119], v[118:119], 1, s[54:55]
	s_waitcnt vmcnt(16)
	v_pk_add_f32 v[24:25], v[24:25], v[144:145]
	v_pk_add_f32 v[22:23], v[22:23], v[142:143]
	v_pk_add_f32 v[16:17], v[16:17], v[140:141]
	v_pk_add_f32 v[14:15], v[14:15], v[138:139]
	global_store_dwordx4 v[120:121], v[30:33], off sc1
	global_store_dwordx4 v[120:121], v[26:29], off offset:16 sc1
	global_store_dwordx4 v[118:119], v[114:117], off sc1
	global_store_dwordx4 v[120:121], v[22:25], off offset:512 sc1
	global_store_dwordx4 v[120:121], v[14:17], off offset:528 sc1
	v_cvt_pk_bf16_f32 v114, v22, v23
	v_cvt_pk_bf16_f32 v115, v24, v25
	v_cvt_pk_bf16_f32 v116, v14, v15
	v_cvt_pk_bf16_f32 v117, v16, v17
	global_store_dwordx4 v[118:119], v[114:117], off offset:256 sc1
	s_waitcnt vmcnt(20)
	v_pk_add_f32 v[20:21], v[20:21], v[152:153]
	v_pk_add_f32 v[18:19], v[18:19], v[150:151]
	v_lshlrev_b64 v[114:115], 11, v[202:203]
	v_lshl_add_u64 v[118:119], v[114:115], 0, v[200:201]
	v_pk_add_f32 v[12:13], v[12:13], v[148:149]
	v_pk_add_f32 v[10:11], v[10:11], v[146:147]
	v_lshl_add_u64 v[120:121], v[118:119], 2, s[36:37]
	v_cvt_pk_bf16_f32 v114, v18, v19
	v_cvt_pk_bf16_f32 v115, v20, v21
	v_cvt_pk_bf16_f32 v116, v10, v11
	v_cvt_pk_bf16_f32 v117, v12, v13
	v_lshl_add_u64 v[118:119], v[118:119], 1, s[54:55]
	s_waitcnt vmcnt(18)
	v_pk_add_f32 v[8:9], v[8:9], v[160:161]
	v_pk_add_f32 v[6:7], v[6:7], v[158:159]
	v_pk_add_f32 v[4:5], v[4:5], v[156:157]
	v_pk_add_f32 v[2:3], v[2:3], v[154:155]
	global_store_dwordx4 v[120:121], v[18:21], off sc1
	global_store_dwordx4 v[120:121], v[10:13], off offset:16 sc1
	global_store_dwordx4 v[118:119], v[114:117], off sc1
	global_store_dwordx4 v[120:121], v[6:9], off offset:512 sc1
	global_store_dwordx4 v[120:121], v[2:5], off offset:528 sc1
	v_cvt_pk_bf16_f32 v114, v6, v7
	v_cvt_pk_bf16_f32 v115, v8, v9
	v_cvt_pk_bf16_f32 v116, v2, v3
	v_cvt_pk_bf16_f32 v117, v4, v5
	global_store_dwordx4 v[118:119], v[114:117], off offset:256 sc1
	s_nop 1
	v_and_b32_e32 v114, 63, v185
	v_lshlrev_b32_e32 v115, 2, v114
	v_xor_b32_e32 v116, 64, v115
	ds_bpermute_b32 v117, v116, v187
	v_xor_b32_e32 v115, 0x80, v115
	s_waitcnt lgkmcnt(0)
	v_add_f32_e32 v118, v187, v117
	ds_bpermute_b32 v119, v115, v118
	v_lshl_add_u32 v117, v183, 4, s91
	s_and_saveexec_b64 s[14:15], vcc
	s_cbranch_execz .LBB0_2040
	s_waitcnt lgkmcnt(0)
	v_add_f32_e32 v118, v118, v119
	ds_write_b32 v117, v118

;     __device__ __forceinline__ void operator()(f32x4 (&acc)[2][2][4][2], const Unit& u, int wr, int wc, int fr, int fq) const {
;     ...
;             for (int m = 0; m < 4; ++m) { const int row = row0 + ai * HALF + m * 16; bf16_t* rowp = O + (size_t)row * ldc + col0;
;                 const float rs = ssq ? rsv[ai * 4 + m] : 1.0f;
; #pragma unroll
;                 for (int bj = 0; bj < 2; ++bj) { f32x4 v0 = acc[ai][bj][m][0] * rs, v1 = acc[ai][bj][m][1] * rs;
;                     if (ACT == 2) {
; #pragma unroll
;                         for (int j = 0; j < 4; ++j) { float a = v0[j] > 0.f ? v0[j] : 0.f; v0[j] = a * a; float b = v1[j] > 0.f ? v1[j] : 0.f; v1[j] = b * b; } }
;                     u32x4 w; w.x = cvt_pk_bf16(v0[0], v0[1]); w.y = cvt_pk_bf16(v0[2], v0[3]); w.z = cvt_pk_bf16(v1[0], v1[1]); w.w = cvt_pk_bf16(v1[2], v1[3]);
;                     *(u32x4*)(rowp + bj * HALF) = w; } }
.LBB0_2133:
	v_mov_b32_e32 v142, v246
	s_lshl_b32 s3, s18, 8
	s_add_i32 s3, s3, s31
	v_and_or_b32 v146, v142, 15, s3
	v_lshrrev_b32_e32 v142, 1, v142
	s_lshl_b32 s3, s45, 8
	v_max_f32_e32 v122, v122, v122
	v_max_f32_e32 v123, v123, v123
	v_max_f32_e32 v124, v124, v124
	v_and_or_b32 v142, v142, 24, s3
	v_max_f32_e32 v122, 0, v122
	v_max_f32_e32 v123, 0, v123
	v_max_f32_e32 v124, 0, v124
	v_ashrrev_i32_e32 v147, 31, v146
	v_or_b32_e32 v142, s33, v142
	v_max_f32_e32 v126, v126, v126
	v_mul_f32_e32 v145, v122, v122
	v_max_f32_e32 v122, v127, v127
	v_mul_f32_e32 v127, v123, v123
	v_max_f32_e32 v123, v128, v128
	v_mul_f32_e32 v128, v124, v124
	v_max_f32_e32 v124, v129, v129
	v_max_f32_e32 v125, v125, v125
	v_ashrrev_i32_e32 v143, 31, v142
	v_lshlrev_b64 v[148:149], 14, v[146:147]
	v_max_f32_e32 v126, 0, v126
	v_max_f32_e32 v122, 0, v122
	v_max_f32_e32 v123, 0, v123
	v_max_f32_e32 v124, 0, v124
	v_max_f32_e32 v125, 0, v125
	v_lshl_add_u64 v[148:149], s[58:59], 0, v[148:149]
	v_lshlrev_b64 v[150:151], 1, v[142:143]
	v_mul_f32_e32 v126, v126, v126
	v_mul_f32_e32 v122, v122, v122
	v_mul_f32_e32 v123, v123, v123
	v_mul_f32_e32 v124, v124, v124
	v_mul_f32_e32 v125, v125, v125
	v_max_f32_e32 v114, v114, v114
	v_max_f32_e32 v115, v115, v115
	v_max_f32_e32 v116, v116, v116
	v_lshl_add_u64 v[142:143], v[148:149], 0, v[150:151]
	v_cvt_pk_bf16_f32 v122, v126, v122
	v_cvt_pk_bf16_f32 v123, v123, v124
	v_cvt_pk_bf16_f32 v124, v145, v127
	v_cvt_pk_bf16_f32 v125, v128, v125
	v_max_f32_e32 v114, 0, v114
	v_max_f32_e32 v115, 0, v115
	v_max_f32_e32 v116, 0, v116
	global_store_dwordx4 v[142:143], v[122:125], off sc1
	v_max_f32_e32 v118, v118, v118
	v_max_f32_e32 v117, v117, v117
	v_mul_f32_e32 v122, v114, v114
	v_max_f32_e32 v114, v119, v119
	v_mul_f32_e32 v119, v115, v115
	v_max_f32_e32 v115, v120, v120
	v_mul_f32_e32 v120, v116, v116
	v_max_f32_e32 v116, v121, v121
	v_max_f32_e32 v118, 0, v118
	v_max_f32_e32 v114, 0, v114
	v_max_f32_e32 v115, 0, v115
	v_max_f32_e32 v116, 0, v116
	v_max_f32_e32 v117, 0, v117
	v_mul_f32_e32 v118, v118, v118
	v_mul_f32_e32 v114, v114, v114
	v_mul_f32_e32 v115, v115, v115
	v_mul_f32_e32 v116, v116, v116
	v_mul_f32_e32 v117, v117, v117
	v_cvt_pk_bf16_f32 v114, v118, v114
	v_cvt_pk_bf16_f32 v115, v115, v116
	v_cvt_pk_bf16_f32 v116, v122, v119
	v_cvt_pk_bf16_f32 v117, v120, v117
	v_max_f32_e32 v106, v106, v106
	v_max_f32_e32 v107, v107, v107
	v_max_f32_e32 v108, v108, v108
	global_store_dwordx4 v[142:143], v[114:117], off offset:256 sc1
	v_max_f32_e32 v106, 0, v106
	v_max_f32_e32 v107, 0, v107
	v_or_b32_e32 v114, 16, v146
	v_max_f32_e32 v108, 0, v108
	v_ashrrev_i32_e32 v115, 31, v114
	v_max_f32_e32 v110, v110, v110
	v_mul_f32_e32 v116, v106, v106
	v_max_f32_e32 v106, v111, v111
	v_mul_f32_e32 v111, v107, v107
	v_max_f32_e32 v107, v112, v112
	v_mul_f32_e32 v112, v108, v108
	v_max_f32_e32 v108, v113, v113
	v_max_f32_e32 v109, v109, v109
	v_lshlrev_b64 v[114:115], 14, v[114:115]
	v_max_f32_e32 v110, 0, v110
	v_max_f32_e32 v106, 0, v106
	v_max_f32_e32 v107, 0, v107
	v_max_f32_e32 v108, 0, v108
	v_max_f32_e32 v109, 0, v109
	v_lshl_add_u64 v[114:115], s[58:59], 0, v[114:115]
	v_mul_f32_e32 v110, v110, v110
	v_mul_f32_e32 v106, v106, v106
	v_mul_f32_e32 v107, v107, v107
	v_mul_f32_e32 v108, v108, v108
	v_mul_f32_e32 v109, v109, v109
	v_max_f32_e32 v98, v98, v98
	v_max_f32_e32 v99, v99, v99
	v_max_f32_e32 v100, v100, v100
	v_lshl_add_u64 v[114:115], v[114:115], 0, v[150:151]
	v_cvt_pk_bf16_f32 v106, v110, v106
	v_cvt_pk_bf16_f32 v107, v107, v108
	v_cvt_pk_bf16_f32 v108, v116, v111
	v_cvt_pk_bf16_f32 v109, v112, v109
	v_max_f32_e32 v98, 0, v98
	v_max_f32_e32 v99, 0, v99
	v_max_f32_e32 v100, 0, v100
	global_store_dwordx4 v[114:115], v[106:109], off sc1
	v_max_f32_e32 v102, v102, v102
	v_max_f32_e32 v101, v101, v101
	v_mul_f32_e32 v106, v98, v98
	v_max_f32_e32 v98, v103, v103
	v_mul_f32_e32 v103, v99, v99
	v_max_f32_e32 v99, v104, v104
	v_mul_f32_e32 v104, v100, v100
	v_max_f32_e32 v100, v105, v105
	v_max_f32_e32 v102, 0, v102
	v_max_f32_e32 v98, 0, v98
	v_max_f32_e32 v99, 0, v99
	v_max_f32_e32 v100, 0, v100
	v_max_f32_e32 v101, 0, v101
	v_mul_f32_e32 v102, v102, v102
	v_mul_f32_e32 v98, v98, v98
	v_mul_f32_e32 v99, v99, v99
	v_mul_f32_e32 v100, v100, v100
	v_mul_f32_e32 v101, v101, v101
	v_cvt_pk_bf16_f32 v98, v102, v98
	v_cvt_pk_bf16_f32 v99, v99, v100
	v_cvt_pk_bf16_f32 v100, v106, v103
	v_cvt_pk_bf16_f32 v101, v104, v101
	v_max_f32_e32 v90, v90, v90
	v_max_f32_e32 v91, v91, v91
	v_max_f32_e32 v92, v92, v92
	global_store_dwordx4 v[114:115], v[98:101], off offset:256 sc1
	v_max_f32_e32 v90, 0, v90
	v_max_f32_e32 v91, 0, v91
	v_or_b32_e32 v98, 32, v146
	v_max_f32_e32 v92, 0, v92
	v_ashrrev_i32_e32 v99, 31, v98
	v_max_f32_e32 v94, v94, v94
	v_mul_f32_e32 v100, v90, v90
	v_max_f32_e32 v90, v95, v95
	v_mul_f32_e32 v95, v91, v91
	v_max_f32_e32 v91, v96, v96
	v_mul_f32_e32 v96, v92, v92
	v_max_f32_e32 v92, v97, v97
	v_max_f32_e32 v93, v93, v93
	v_lshlrev_b64 v[98:99], 14, v[98:99]
	v_max_f32_e32 v94, 0, v94
	v_max_f32_e32 v90, 0, v90
	v_max_f32_e32 v91, 0, v91
	v_max_f32_e32 v92, 0, v92
	v_max_f32_e32 v93, 0, v93
	v_lshl_add_u64 v[98:99], s[58:59], 0, v[98:99]
	v_mul_f32_e32 v94, v94, v94
	v_mul_f32_e32 v90, v90, v90
	v_mul_f32_e32 v91, v91, v91
	v_mul_f32_e32 v92, v92, v92
	v_mul_f32_e32 v93, v93, v93
	v_max_f32_e32 v82, v82, v82
	v_max_f32_e32 v83, v83, v83
	v_max_f32_e32 v84, v84, v84
	v_lshl_add_u64 v[98:99], v[98:99], 0, v[150:151]
	v_cvt_pk_bf16_f32 v90, v94, v90
	v_cvt_pk_bf16_f32 v91, v91, v92
	v_cvt_pk_bf16_f32 v92, v100, v95
	v_cvt_pk_bf16_f32 v93, v96, v93
	v_max_f32_e32 v82, 0, v82
	v_max_f32_e32 v83, 0, v83
	v_max_f32_e32 v84, 0, v84
;     __device__ __forceinline__ void operator()(f32x4 (&acc)[2][2][4][2], const Unit& u, int wr, int wc, int fr, int fq) const {
;     ...
;             for (int m = 0; m < 4; ++m) { const int row = row0 + ai * HALF + m * 16; bf16_t* rowp = O + (size_t)row * ldc + col0;
;                 const float rs = ssq ? rsv[ai * 4 + m] : 1.0f;
; #pragma unroll
;                 for (int bj = 0; bj < 2; ++bj) { f32x4 v0 = acc[ai][bj][m][0] * rs, v1 = acc[ai][bj][m][1] * rs;
;                     if (ACT == 2) {
; #pragma unroll
;                         for (int j = 0; j < 4; ++j) { float a = v0[j] > 0.f ? v0[j] : 0.f; v0[j] = a * a; float b = v1[j] > 0.f ? v1[j] : 0.f; v1[j] = b * b; } }
;                     u32x4 w; w.x = cvt_pk_bf16(v0[0], v0[1]); w.y = cvt_pk_bf16(v0[2], v0[3]); w.z = cvt_pk_bf16(v1[0], v1[1]); w.w = cvt_pk_bf16(v1[2], v1[3]);
;                     *(u32x4*)(rowp + bj * HALF) = w; } }
	global_store_dwordx4 v[98:99], v[90:93], off sc1
	v_max_f32_e32 v86, v86, v86
	v_max_f32_e32 v85, v85, v85
	v_mul_f32_e32 v90, v82, v82
	v_max_f32_e32 v82, v87, v87
	v_mul_f32_e32 v87, v83, v83
	v_max_f32_e32 v83, v88, v88
	v_mul_f32_e32 v88, v84, v84
	v_max_f32_e32 v84, v89, v89
	v_max_f32_e32 v86, 0, v86
	v_max_f32_e32 v82, 0, v82
	v_max_f32_e32 v83, 0, v83
	v_max_f32_e32 v84, 0, v84
	v_max_f32_e32 v85, 0, v85
	v_mul_f32_e32 v86, v86, v86
	v_mul_f32_e32 v82, v82, v82
	v_mul_f32_e32 v83, v83, v83
	v_mul_f32_e32 v84, v84, v84
	v_mul_f32_e32 v85, v85, v85
	v_cvt_pk_bf16_f32 v82, v86, v82
	v_cvt_pk_bf16_f32 v83, v83, v84
	v_cvt_pk_bf16_f32 v84, v90, v87
	v_cvt_pk_bf16_f32 v85, v88, v85
	v_max_f32_e32 v74, v74, v74
	v_max_f32_e32 v75, v75, v75
	v_max_f32_e32 v76, v76, v76
	global_store_dwordx4 v[98:99], v[82:85], off offset:256 sc1
	v_max_f32_e32 v74, 0, v74
	v_max_f32_e32 v75, 0, v75
	v_or_b32_e32 v82, 48, v146
	v_max_f32_e32 v76, 0, v76
	v_ashrrev_i32_e32 v83, 31, v82
	v_max_f32_e32 v78, v78, v78
	v_mul_f32_e32 v84, v74, v74
	v_max_f32_e32 v74, v79, v79
	v_mul_f32_e32 v79, v75, v75
	v_max_f32_e32 v75, v80, v80
	v_mul_f32_e32 v80, v76, v76
	v_max_f32_e32 v76, v81, v81
	v_max_f32_e32 v77, v77, v77
	v_lshlrev_b64 v[82:83], 14, v[82:83]
	v_max_f32_e32 v78, 0, v78
	v_max_f32_e32 v74, 0, v74
	v_max_f32_e32 v75, 0, v75
	v_max_f32_e32 v76, 0, v76
	v_max_f32_e32 v77, 0, v77
	v_lshl_add_u64 v[82:83], s[58:59], 0, v[82:83]
	v_mul_f32_e32 v78, v78, v78
	v_mul_f32_e32 v74, v74, v74
	v_mul_f32_e32 v75, v75, v75
	v_mul_f32_e32 v76, v76, v76
	v_mul_f32_e32 v77, v77, v77
	v_max_f32_e32 v66, v66, v66
	v_max_f32_e32 v67, v67, v67
	v_max_f32_e32 v68, v68, v68
	v_lshl_add_u64 v[82:83], v[82:83], 0, v[150:151]
	v_cvt_pk_bf16_f32 v74, v78, v74
	v_cvt_pk_bf16_f32 v75, v75, v76
	v_cvt_pk_bf16_f32 v76, v84, v79
	v_cvt_pk_bf16_f32 v77, v80, v77
	v_max_f32_e32 v66, 0, v66
	v_max_f32_e32 v67, 0, v67
	v_max_f32_e32 v68, 0, v68
	global_store_dwordx4 v[82:83], v[74:77], off sc1
	v_max_f32_e32 v70, v70, v70
	v_max_f32_e32 v69, v69, v69
	v_mul_f32_e32 v74, v66, v66
	v_max_f32_e32 v66, v71, v71
	v_mul_f32_e32 v71, v67, v67
	v_max_f32_e32 v67, v72, v72
	v_mul_f32_e32 v72, v68, v68
	v_max_f32_e32 v68, v73, v73
	v_max_f32_e32 v70, 0, v70
	v_max_f32_e32 v66, 0, v66
	v_max_f32_e32 v67, 0, v67
	v_max_f32_e32 v68, 0, v68
	v_max_f32_e32 v69, 0, v69
	v_mul_f32_e32 v70, v70, v70
	v_mul_f32_e32 v66, v66, v66
	v_mul_f32_e32 v67, v67, v67
	v_mul_f32_e32 v68, v68, v68
	v_mul_f32_e32 v69, v69, v69
	v_max_f32_e32 v58, v58, v58
	v_cvt_pk_bf16_f32 v66, v70, v66
	v_cvt_pk_bf16_f32 v67, v67, v68
	v_cvt_pk_bf16_f32 v68, v74, v71
	v_cvt_pk_bf16_f32 v69, v72, v69
	v_max_f32_e32 v58, 0, v58
	v_max_f32_e32 v59, v59, v59
	v_max_f32_e32 v60, v60, v60
	global_store_dwordx4 v[82:83], v[66:69], off offset:256 sc1
	v_max_f32_e32 v62, v62, v62
	v_max_f32_e32 v59, 0, v59
	v_mul_f32_e32 v68, v58, v58
	v_max_f32_e32 v58, v63, v63
	v_max_f32_e32 v60, 0, v60
	v_max_f32_e32 v62, 0, v62
	v_max_f32_e32 v58, 0, v58
	v_mul_f32_e32 v63, v59, v59
	v_max_f32_e32 v59, v64, v64
	v_mul_f32_e32 v64, v60, v60
	v_max_f32_e32 v60, v65, v65
	v_max_f32_e32 v61, v61, v61
	v_mul_f32_e32 v62, v62, v62
	v_mul_f32_e32 v58, v58, v58
	v_max_f32_e32 v59, 0, v59
	v_max_f32_e32 v60, 0, v60
	v_max_f32_e32 v61, 0, v61
	s_mov_b32 s3, 0x200000
	v_mul_f32_e32 v59, v59, v59
	v_mul_f32_e32 v60, v60, v60
	v_mul_f32_e32 v61, v61, v61
	v_cvt_pk_bf16_f32 v58, v62, v58
	v_add_co_u32_e32 v62, vcc, s3, v142
	v_max_f32_e32 v50, v50, v50
	v_max_f32_e32 v51, v51, v51
	v_max_f32_e32 v52, v52, v52
	v_cvt_pk_bf16_f32 v59, v59, v60
	v_cvt_pk_bf16_f32 v60, v68, v63
	v_cvt_pk_bf16_f32 v61, v64, v61
	v_addc_co_u32_e32 v63, vcc, 0, v143, vcc
	v_max_f32_e32 v50, 0, v50
	v_max_f32_e32 v51, 0, v51
	v_max_f32_e32 v52, 0, v52
	global_store_dwordx4 v[62:63], v[58:61], off sc1
	v_max_f32_e32 v54, v54, v54
	v_max_f32_e32 v53, v53, v53
	v_mul_f32_e32 v58, v50, v50
	v_max_f32_e32 v50, v55, v55
	v_mul_f32_e32 v55, v51, v51
	v_max_f32_e32 v51, v56, v56
	v_mul_f32_e32 v56, v52, v52
	v_max_f32_e32 v52, v57, v57
	v_max_f32_e32 v54, 0, v54
	v_max_f32_e32 v50, 0, v50
	v_max_f32_e32 v51, 0, v51
	v_max_f32_e32 v52, 0, v52
	v_max_f32_e32 v53, 0, v53
	s_mov_b64 s[14:15], 0x200000
	v_mul_f32_e32 v54, v54, v54
	v_mul_f32_e32 v50, v50, v50
	v_mul_f32_e32 v51, v51, v51
	v_mul_f32_e32 v52, v52, v52
	v_mul_f32_e32 v53, v53, v53
	v_max_f32_e32 v42, v42, v42
	v_lshl_add_u64 v[66:67], v[142:143], 0, s[14:15]
	v_cvt_pk_bf16_f32 v50, v54, v50
	v_cvt_pk_bf16_f32 v51, v51, v52
	v_cvt_pk_bf16_f32 v52, v58, v55
	v_cvt_pk_bf16_f32 v53, v56, v53
	v_max_f32_e32 v42, 0, v42
	v_max_f32_e32 v43, v43, v43
	v_max_f32_e32 v44, v44, v44
	global_store_dwordx4 v[66:67], v[50:53], off offset:256 sc1
	v_max_f32_e32 v46, v46, v46
	v_max_f32_e32 v43, 0, v43
	v_mul_f32_e32 v52, v42, v42
	v_max_f32_e32 v42, v47, v47
	v_max_f32_e32 v44, 0, v44
	v_max_f32_e32 v46, 0, v46
	v_max_f32_e32 v42, 0, v42
	v_mul_f32_e32 v47, v43, v43
	v_max_f32_e32 v43, v48, v48
	v_mul_f32_e32 v48, v44, v44
	v_max_f32_e32 v44, v49, v49
	v_max_f32_e32 v45, v45, v45
	v_mul_f32_e32 v46, v46, v46
	v_mul_f32_e32 v42, v42, v42
	v_max_f32_e32 v43, 0, v43
	v_max_f32_e32 v44, 0, v44
	v_max_f32_e32 v45, 0, v45
	s_mov_b32 s3, 0x240000
; #define PG8_BAR __builtin_amdgcn_s_barrier()
;     __device__ __forceinline__ void operator()(f32x4 (&acc)[2][2][4][2], const Unit& u, int wr, int wc, int fr, int fq) const {
;     ...
;             for (int m = 0; m < 4; ++m) { const int row = row0 + ai * HALF + m * 16; bf16_t* rowp = O + (size_t)row * ldc + col0;
;                 const float rs = ssq ? rsv[ai * 4 + m] : 1.0f;
; #pragma unroll
;                 for (int bj = 0; bj < 2; ++bj) { f32x4 v0 = acc[ai][bj][m][0] * rs, v1 = acc[ai][bj][m][1] * rs;
;                     if (ACT == 2) {
; #pragma unroll
;                         for (int j = 0; j < 4; ++j) { float a = v0[j] > 0.f ? v0[j] : 0.f; v0[j] = a * a; float b = v1[j] > 0.f ? v1[j] : 0.f; v1[j] = b * b; } }
;                     u32x4 w; w.x = cvt_pk_bf16(v0[0], v0[1]); w.y = cvt_pk_bf16(v0[2], v0[3]); w.z = cvt_pk_bf16(v1[0], v1[1]); w.w = cvt_pk_bf16(v1[2], v1[3]);
;                     *(u32x4*)(rowp + bj * HALF) = w; } }
; template <class Epi>
; __device__ __forceinline__ void gemm_phase(LAS unsigned char* lds, const Gemm g, const StaticOrder& S, const Epi& E) {
;     ...
;         if (!has_next) break;
; #pragma unroll
;         for (int a = 0; a < 2; ++a)
; #pragma unroll
;             for (int b = 0; b < 2; ++b)
; #pragma unroll
;                 for (int m = 0; m < 4; ++m)
; #pragma unroll
;                     for (int n = 0; n < 2; ++n) acc[a][b][m][n] = (f32x4){0.f, 0.f, 0.f, 0.f};
;         cur = nxt; cA = nA; cB = nB; ++ui;
;         if (wr == 1) PG8_BAR;
	v_mul_f32_e32 v43, v43, v43
	v_mul_f32_e32 v44, v44, v44
	v_mul_f32_e32 v45, v45, v45
	v_cvt_pk_bf16_f32 v42, v46, v42
	v_add_co_u32_e32 v46, vcc, s3, v142
	v_max_f32_e32 v34, v34, v34
	v_max_f32_e32 v35, v35, v35
	v_max_f32_e32 v36, v36, v36
	v_cvt_pk_bf16_f32 v43, v43, v44
	v_cvt_pk_bf16_f32 v44, v52, v47
	v_cvt_pk_bf16_f32 v45, v48, v45
	v_addc_co_u32_e32 v47, vcc, 0, v143, vcc
	v_max_f32_e32 v34, 0, v34
	v_max_f32_e32 v35, 0, v35
	v_max_f32_e32 v36, 0, v36
	global_store_dwordx4 v[46:47], v[42:45], off sc1
	v_max_f32_e32 v38, v38, v38
	v_max_f32_e32 v37, v37, v37
	v_mul_f32_e32 v42, v34, v34
	v_max_f32_e32 v34, v39, v39
	v_mul_f32_e32 v39, v35, v35
	v_max_f32_e32 v35, v40, v40
	v_mul_f32_e32 v40, v36, v36
	v_max_f32_e32 v36, v41, v41
	v_max_f32_e32 v38, 0, v38
	v_max_f32_e32 v34, 0, v34
	v_max_f32_e32 v35, 0, v35
	v_max_f32_e32 v36, 0, v36
	v_max_f32_e32 v37, 0, v37
	s_mov_b64 s[14:15], 0x240000
	v_mul_f32_e32 v38, v38, v38
	v_mul_f32_e32 v34, v34, v34
	v_mul_f32_e32 v35, v35, v35
	v_mul_f32_e32 v36, v36, v36
	v_mul_f32_e32 v37, v37, v37
	v_max_f32_e32 v26, v26, v26
	v_lshl_add_u64 v[50:51], v[142:143], 0, s[14:15]
	v_cvt_pk_bf16_f32 v34, v38, v34
	v_cvt_pk_bf16_f32 v35, v35, v36
	v_cvt_pk_bf16_f32 v36, v42, v39
	v_cvt_pk_bf16_f32 v37, v40, v37
	v_max_f32_e32 v26, 0, v26
	v_max_f32_e32 v27, v27, v27
	v_max_f32_e32 v28, v28, v28
	global_store_dwordx4 v[50:51], v[34:37], off offset:256 sc1
	v_max_f32_e32 v30, v30, v30
	v_max_f32_e32 v27, 0, v27
	v_mul_f32_e32 v36, v26, v26
	v_max_f32_e32 v26, v31, v31
	v_max_f32_e32 v28, 0, v28
	v_max_f32_e32 v30, 0, v30
	v_max_f32_e32 v26, 0, v26
	v_mul_f32_e32 v31, v27, v27
	v_max_f32_e32 v27, v32, v32
	v_mul_f32_e32 v32, v28, v28
	v_max_f32_e32 v28, v33, v33
	v_max_f32_e32 v29, v29, v29
	v_mul_f32_e32 v30, v30, v30
	v_mul_f32_e32 v26, v26, v26
	v_max_f32_e32 v27, 0, v27
	v_max_f32_e32 v28, 0, v28
	v_max_f32_e32 v29, 0, v29
	s_mov_b32 s3, 0x280000
	v_mul_f32_e32 v27, v27, v27
	v_mul_f32_e32 v28, v28, v28
	v_mul_f32_e32 v29, v29, v29
	v_cvt_pk_bf16_f32 v26, v30, v26
	v_add_co_u32_e32 v30, vcc, s3, v142
	v_max_f32_e32 v18, v18, v18
	v_max_f32_e32 v19, v19, v19
	v_max_f32_e32 v20, v20, v20
	v_cvt_pk_bf16_f32 v27, v27, v28
	v_cvt_pk_bf16_f32 v28, v36, v31
	v_cvt_pk_bf16_f32 v29, v32, v29
	v_addc_co_u32_e32 v31, vcc, 0, v143, vcc
	v_max_f32_e32 v18, 0, v18
	v_max_f32_e32 v19, 0, v19
	v_max_f32_e32 v20, 0, v20
	global_store_dwordx4 v[30:31], v[26:29], off sc1
	v_max_f32_e32 v22, v22, v22
	v_max_f32_e32 v21, v21, v21
	v_mul_f32_e32 v26, v18, v18
	v_max_f32_e32 v18, v23, v23
	v_mul_f32_e32 v23, v19, v19
	v_max_f32_e32 v19, v24, v24
	v_mul_f32_e32 v24, v20, v20
	v_max_f32_e32 v20, v25, v25
	v_max_f32_e32 v22, 0, v22
	v_max_f32_e32 v18, 0, v18
	v_max_f32_e32 v19, 0, v19
	v_max_f32_e32 v20, 0, v20
	v_max_f32_e32 v21, 0, v21
	s_mov_b64 s[14:15], 0x280000
	v_mul_f32_e32 v22, v22, v22
	v_mul_f32_e32 v18, v18, v18
	v_mul_f32_e32 v19, v19, v19
	v_mul_f32_e32 v20, v20, v20
	v_mul_f32_e32 v21, v21, v21
	v_max_f32_e32 v10, v10, v10
	v_lshl_add_u64 v[34:35], v[142:143], 0, s[14:15]
	v_cvt_pk_bf16_f32 v18, v22, v18
	v_cvt_pk_bf16_f32 v19, v19, v20
	v_cvt_pk_bf16_f32 v20, v26, v23
	v_cvt_pk_bf16_f32 v21, v24, v21
	v_max_f32_e32 v10, 0, v10
	v_max_f32_e32 v11, v11, v11
	v_max_f32_e32 v12, v12, v12
	global_store_dwordx4 v[34:35], v[18:21], off offset:256 sc1
	v_max_f32_e32 v14, v14, v14
	v_max_f32_e32 v11, 0, v11
	v_mul_f32_e32 v20, v10, v10
	v_max_f32_e32 v10, v15, v15
	v_max_f32_e32 v12, 0, v12
	v_max_f32_e32 v14, 0, v14
	v_max_f32_e32 v10, 0, v10
	v_mul_f32_e32 v15, v11, v11
	v_max_f32_e32 v11, v16, v16
	v_mul_f32_e32 v16, v12, v12
	v_max_f32_e32 v12, v17, v17
	v_max_f32_e32 v13, v13, v13
	v_mul_f32_e32 v14, v14, v14
	v_mul_f32_e32 v10, v10, v10
	v_max_f32_e32 v11, 0, v11
	v_max_f32_e32 v12, 0, v12
	v_max_f32_e32 v13, 0, v13
	s_mov_b32 s3, 0x2c0000
	v_mul_f32_e32 v11, v11, v11
	v_mul_f32_e32 v12, v12, v12
	v_mul_f32_e32 v13, v13, v13
	v_cvt_pk_bf16_f32 v10, v14, v10
	v_add_co_u32_e32 v14, vcc, s3, v142
	v_max_f32_e32 v2, v2, v2
	v_max_f32_e32 v3, v3, v3
	v_max_f32_e32 v4, v4, v4
	v_cvt_pk_bf16_f32 v11, v11, v12
	v_cvt_pk_bf16_f32 v12, v20, v15
	v_cvt_pk_bf16_f32 v13, v16, v13
	v_addc_co_u32_e32 v15, vcc, 0, v143, vcc
	v_max_f32_e32 v2, 0, v2
	v_max_f32_e32 v3, 0, v3
	v_max_f32_e32 v4, 0, v4
	global_store_dwordx4 v[14:15], v[10:13], off sc1
	v_max_f32_e32 v6, v6, v6
	v_max_f32_e32 v5, v5, v5
	v_mul_f32_e32 v10, v2, v2
	v_max_f32_e32 v2, v7, v7
	v_mul_f32_e32 v7, v3, v3
	v_max_f32_e32 v3, v8, v8
	v_mul_f32_e32 v8, v4, v4
	v_max_f32_e32 v4, v9, v9
	v_max_f32_e32 v6, 0, v6
	v_max_f32_e32 v2, 0, v2
	v_max_f32_e32 v3, 0, v3
	v_max_f32_e32 v4, 0, v4
	v_max_f32_e32 v5, 0, v5
	s_mov_b64 s[14:15], 0x2c0000
	v_mul_f32_e32 v6, v6, v6
	v_mul_f32_e32 v2, v2, v2
	v_mul_f32_e32 v3, v3, v3
	v_mul_f32_e32 v4, v4, v4
	v_mul_f32_e32 v5, v5, v5
	v_lshl_add_u64 v[18:19], v[142:143], 0, s[14:15]
	v_cvt_pk_bf16_f32 v2, v6, v2
	v_cvt_pk_bf16_f32 v3, v3, v4
	v_cvt_pk_bf16_f32 v4, v10, v7
	v_cvt_pk_bf16_f32 v5, v8, v5
	s_andn2_b64 vcc, exec, s[4:5]
	s_mov_b64 s[4:5], -1
	global_store_dwordx4 v[18:19], v[2:5], off offset:256 sc1
	s_cbranch_vccnz .LBB0_2122
	s_andn2_b64 vcc, exec, s[0:1]
	s_cbranch_vccnz .LBB0_2121
	s_barrier
	s_branch .LBB0_2121

;     __device__ __forceinline__ void operator()(f32x4 (&acc)[2][2][4][2], const Unit& u, int wr, int wc, int fr, int fq) const {
;     ...
;             for (int m = 0; m < 4; ++m) { const int row = row0 + ai * HALF + m * 16; bf16_t* rowp = O + (size_t)row * ldc + col0;
;                 const float rs = ssq ? rsv[ai * 4 + m] : 1.0f;
; #pragma unroll
;                 for (int bj = 0; bj < 2; ++bj) { f32x4 v0 = acc[ai][bj][m][0] * rs, v1 = acc[ai][bj][m][1] * rs;
;                     if (ACT == 2) {
; #pragma unroll
;                         for (int j = 0; j < 4; ++j) { float a = v0[j] > 0.f ? v0[j] : 0.f; v0[j] = a * a; float b = v1[j] > 0.f ? v1[j] : 0.f; v1[j] = b * b; } }
;                     u32x4 w; w.x = cvt_pk_bf16(v0[0], v0[1]); w.y = cvt_pk_bf16(v0[2], v0[3]); w.z = cvt_pk_bf16(v1[0], v1[1]); w.w = cvt_pk_bf16(v1[2], v1[3]);
;                     *(u32x4*)(rowp + bj * HALF) = w; } }
.LBB0_2158:
	v_mov_b32_e32 v139, v246
	s_lshl_b32 s3, s10, 8
	s_add_i32 s3, s3, s74
	v_and_or_b32 v140, v139, 15, s3
	v_lshrrev_b32_e32 v139, 1, v139
	s_lshl_b32 s3, s95, 8
	v_and_or_b32 v139, v139, 24, s3
	v_ashrrev_i32_e32 v141, 31, v140
	v_or_b32_e32 v142, s75, v139
	v_ashrrev_i32_e32 v143, 31, v142
	v_lshlrev_b64 v[144:145], 12, v[140:141]
	v_lshl_add_u64 v[144:145], s[56:57], 0, v[144:145]
	v_lshlrev_b64 v[142:143], 1, v[142:143]
	v_lshl_add_u64 v[144:145], v[144:145], 0, v[142:143]
	s_mov_b32 s3, 0x80000
	s_mov_b64 s[12:13], 0x80000
	v_cvt_pk_bf16_f32 v62, v62, v63
	v_cvt_pk_bf16_f32 v63, v64, v65
	v_cvt_pk_bf16_f32 v64, v58, v59
	v_add_co_u32_e32 v58, vcc, s3, v144
	v_cvt_pk_bf16_f32 v70, v70, v71
	v_cvt_pk_bf16_f32 v71, v72, v73
	v_cvt_pk_bf16_f32 v72, v66, v67
	v_lshl_add_u64 v[66:67], v[144:145], 0, s[12:13]
	v_addc_co_u32_e32 v59, vcc, 0, v145, vcc
	v_cvt_pk_bf16_f32 v46, v46, v47
	v_cvt_pk_bf16_f32 v47, v48, v49
	v_cvt_pk_bf16_f32 v48, v42, v43
	v_cvt_pk_bf16_f32 v49, v44, v45
	s_mov_b32 s3, 0x90000
	v_cvt_pk_bf16_f32 v110, v110, v111
	v_cvt_pk_bf16_f32 v111, v112, v113
	v_cvt_pk_bf16_f32 v112, v106, v107
	v_or_b32_e32 v106, 16, v140
	global_store_dwordx4 v[66:67], v[46:49], off offset:256 sc1
	s_mov_b64 s[12:13], 0x90000
	v_ashrrev_i32_e32 v107, 31, v106
	v_add_co_u32_e32 v48, vcc, s3, v144
	v_cvt_pk_bf16_f32 v94, v94, v95
	v_cvt_pk_bf16_f32 v95, v96, v97
	v_cvt_pk_bf16_f32 v96, v90, v91
	v_or_b32_e32 v90, 32, v140
	v_lshl_add_u64 v[46:47], v[144:145], 0, s[12:13]
	v_addc_co_u32_e32 v49, vcc, 0, v145, vcc
	v_cvt_pk_bf16_f32 v30, v30, v31
	v_cvt_pk_bf16_f32 v31, v32, v33
	v_cvt_pk_bf16_f32 v32, v26, v27
	v_cvt_pk_bf16_f32 v33, v28, v29
	s_mov_b32 s3, 0xa0000
	v_lshlrev_b64 v[106:107], 12, v[106:107]
	v_ashrrev_i32_e32 v91, 31, v90
	v_cvt_pk_bf16_f32 v78, v78, v79
	v_cvt_pk_bf16_f32 v79, v80, v81
	v_cvt_pk_bf16_f32 v80, v74, v75
	v_or_b32_e32 v74, 48, v140
	global_store_dwordx4 v[46:47], v[30:33], off offset:256 sc1
	s_mov_b64 s[12:13], 0xa0000
	v_cvt_pk_bf16_f32 v113, v108, v109
	v_add_co_u32_e32 v32, vcc, s3, v144
	v_lshl_add_u64 v[106:107], s[56:57], 0, v[106:107]
	v_lshlrev_b64 v[90:91], 12, v[90:91]
	v_ashrrev_i32_e32 v75, 31, v74
	v_lshl_add_u64 v[30:31], v[144:145], 0, s[12:13]
	v_addc_co_u32_e32 v33, vcc, 0, v145, vcc
	v_cvt_pk_bf16_f32 v14, v14, v15
	v_cvt_pk_bf16_f32 v15, v16, v17
	v_cvt_pk_bf16_f32 v16, v10, v11
	v_cvt_pk_bf16_f32 v17, v12, v13
	global_store_dwordx4 v[144:145], v[110:113], off offset:256 sc1
	v_cvt_pk_bf16_f32 v97, v92, v93
	v_lshl_add_u64 v[90:91], s[56:57], 0, v[90:91]
	v_lshl_add_u64 v[110:111], v[106:107], 0, v[142:143]
	v_lshlrev_b64 v[74:75], 12, v[74:75]
	global_store_dwordx4 v[30:31], v[14:17], off offset:256 sc1
	global_store_dwordx4 v[110:111], v[94:97], off offset:256 sc1
	v_cvt_pk_bf16_f32 v81, v76, v77
	v_add_co_u32_e32 v16, vcc, 0xb0000, v144
	v_lshl_add_u64 v[94:95], v[90:91], 0, v[142:143]
	v_lshl_add_u64 v[74:75], s[56:57], 0, v[74:75]
	s_mov_b64 s[12:13], 0xb0000
	v_addc_co_u32_e32 v17, vcc, 0, v145, vcc
	v_readlane_b32 s30, v255, 26
	v_cvt_pk_bf16_f32 v126, v126, v127
	v_cvt_pk_bf16_f32 v127, v128, v129
	v_cvt_pk_bf16_f32 v128, v122, v123
	v_cvt_pk_bf16_f32 v129, v124, v125
	v_cvt_pk_bf16_f32 v106, v118, v119
	v_cvt_pk_bf16_f32 v107, v120, v121
	v_cvt_pk_bf16_f32 v108, v114, v115
	v_cvt_pk_bf16_f32 v109, v116, v117
	v_cvt_pk_bf16_f32 v90, v102, v103
	v_cvt_pk_bf16_f32 v91, v104, v105
	v_cvt_pk_bf16_f32 v92, v98, v99
	v_cvt_pk_bf16_f32 v93, v100, v101
	global_store_dwordx4 v[94:95], v[78:81], off offset:256 sc1
	v_cvt_pk_bf16_f32 v76, v82, v83
	v_cvt_pk_bf16_f32 v77, v84, v85
	v_lshl_add_u64 v[78:79], v[74:75], 0, v[142:143]
	v_cvt_pk_bf16_f32 v74, v86, v87
	v_cvt_pk_bf16_f32 v75, v88, v89
	v_cvt_pk_bf16_f32 v73, v68, v69
	v_cvt_pk_bf16_f32 v65, v60, v61
	v_cvt_pk_bf16_f32 v42, v54, v55
	v_cvt_pk_bf16_f32 v43, v56, v57
	v_cvt_pk_bf16_f32 v44, v50, v51
	v_cvt_pk_bf16_f32 v45, v52, v53
	v_cvt_pk_bf16_f32 v26, v38, v39
	v_cvt_pk_bf16_f32 v27, v40, v41
	v_cvt_pk_bf16_f32 v28, v34, v35
	v_cvt_pk_bf16_f32 v29, v36, v37
	v_lshl_add_u64 v[14:15], v[144:145], 0, s[12:13]
	v_cvt_pk_bf16_f32 v10, v22, v23
	v_cvt_pk_bf16_f32 v11, v24, v25
	v_cvt_pk_bf16_f32 v12, v18, v19
	v_cvt_pk_bf16_f32 v13, v20, v21
	v_cvt_pk_bf16_f32 v6, v6, v7
	v_cvt_pk_bf16_f32 v7, v8, v9
	v_cvt_pk_bf16_f32 v8, v2, v3
	v_cvt_pk_bf16_f32 v9, v4, v5
	s_andn2_b64 vcc, exec, s[6:7]
	s_mov_b64 s[6:7], -1
	v_readlane_b32 s31, v255, 27
	global_store_dwordx4 v[144:145], v[126:129], off sc1
	global_store_dwordx4 v[110:111], v[106:109], off sc1
	global_store_dwordx4 v[94:95], v[90:93], off sc1
	global_store_dwordx4 v[78:79], v[74:77], off sc1
	global_store_dwordx4 v[78:79], v[70:73], off offset:256 sc1
	global_store_dwordx4 v[58:59], v[62:65], off sc1
	global_store_dwordx4 v[48:49], v[42:45], off sc1
	global_store_dwordx4 v[32:33], v[26:29], off sc1
	global_store_dwordx4 v[16:17], v[10:13], off sc1
	global_store_dwordx4 v[14:15], v[6:9], off offset:256 sc1
	s_cbranch_vccnz .LBB0_2147
	s_andn2_b64 vcc, exec, s[0:1]
	s_cbranch_vccnz .LBB0_2146
	s_barrier
	s_branch .LBB0_2146

; __device__ __forceinline__ float ssq4(const f32x4 o) { return (o[0] * o[0] + o[1] * o[1]) + (o[2] * o[2] + o[3] * o[3]); }
;     __device__ __forceinline__ void operator()(f32x4 (&acc)[2][2][4][2], const Unit& u, int wr, int wc, int fr, int fq) const {
;     ...
;         f32x4 cur[2][4], nxt[2][4];
; #pragma unroll
;         for (int q = 0; q < 2; ++q)
; #pragma unroll
;             for (int c = 0; c < 4; ++c) cur[q][c] = *(const f32x4*)(base + (size_t)EPI_ROW(q) * D + col0 + (c >> 1) * HALF + (c & 1) * 4);
; #pragma unroll
;         for (int k = 0; k < 4; ++k) {
;             if (k < 3) {
; #pragma unroll
;                 for (int q = 0; q < 2; ++q)
; #pragma unroll
;                     for (int c = 0; c < 4; ++c) nxt[q][c] = *(const f32x4*)(base + (size_t)EPI_ROW(2 * k + 2 + q) * D + col0 + (c >> 1) * HALF + (c & 1) * 4);
;             }
;             asm volatile("" ::: "memory");
; #pragma unroll
;             for (int q = 0; q < 2; ++q) { const int r = 2 * k + q, ai = r >> 2, m = r & 3; const size_t off = (size_t)EPI_ROW(r) * D + col0; float sr = 0.f;
; #pragma unroll
;                 for (int bj = 0; bj < 2; ++bj) { const f32x4 o0 = cur[q][2 * bj] + acc[ai][bj][m][0], o1 = cur[q][2 * bj + 1] + acc[ai][bj][m][1];
;                     *(f32x4*)(out + off + bj * HALF) = o0; *(f32x4*)(out + off + bj * HALF + 4) = o1;
;                     u32x4 w; w.x = cvt_pk_bf16(o0[0], o0[1]); w.y = cvt_pk_bf16(o0[2], o0[3]); w.z = cvt_pk_bf16(o1[0], o1[1]); w.w = cvt_pk_bf16(o1[2], o1[3]); *(u32x4*)(hb + off + bj * HALF) = w; sr += ssq4(o0) + ssq4(o1); }
;                 s[ai][m] = sr; }
.LBB0_2238:
	s_lshl_b32 s3, s0, 8
	s_or_b32 s3, s3, s45
	v_lshl_or_b32 v130, v168, 3, s3
	v_ashrrev_i32_e32 v131, 31, v130
	v_or_b32_e32 v138, 16, v162
	v_lshl_add_u64 v[132:133], v[130:131], 2, s[36:37]
	v_lshlrev_b64 v[134:135], 13, v[162:163]
	v_ashrrev_i32_e32 v139, 31, v138
	v_lshl_add_u64 v[148:149], v[132:133], 0, v[134:135]
	v_lshlrev_b64 v[134:135], 13, v[138:139]
	global_load_dwordx4 v[140:143], v[148:149], off
	global_load_dwordx4 v[144:147], v[148:149], off offset:16
	global_load_dwordx4 v[170:173], v[148:149], off offset:528
	global_load_dwordx4 v[174:177], v[148:149], off offset:512
	v_lshl_add_u64 v[164:165], v[132:133], 0, v[134:135]
	global_load_dwordx4 v[188:191], v[164:165], off
	global_load_dwordx4 v[192:195], v[164:165], off offset:16
	global_load_dwordx4 v[196:199], v[164:165], off offset:512
	global_load_dwordx4 v[200:203], v[164:165], off offset:528
	v_or_b32_e32 v136, 32, v162
	v_or_b32_e32 v134, 48, v162
	v_ashrrev_i32_e32 v137, 31, v136
	v_ashrrev_i32_e32 v135, 31, v134
	v_lshlrev_b64 v[184:185], 13, v[136:137]
	v_lshlrev_b64 v[138:139], 11, v[138:139]
	v_lshlrev_b64 v[204:205], 13, v[134:135]
	v_lshl_add_u64 v[206:207], v[138:139], 0, v[130:131]
	v_lshl_add_u64 v[184:185], v[132:133], 0, v[184:185]
	v_lshl_add_u64 v[138:139], v[132:133], 0, v[204:205]
	v_lshl_add_u64 v[236:237], v[206:207], 1, s[60:61]
	global_load_dwordx4 v[204:207], v[184:185], off offset:16
	global_load_dwordx4 v[208:211], v[184:185], off
	global_load_dwordx4 v[212:215], v[184:185], off offset:528
	global_load_dwordx4 v[216:219], v[184:185], off offset:512
	global_load_dwordx4 v[220:223], v[138:139], off offset:16
	global_load_dwordx4 v[224:227], v[138:139], off
	global_load_dwordx4 v[228:231], v[138:139], off offset:528
	global_load_dwordx4 v[232:235], v[138:139], off offset:512
	v_lshlrev_b64 v[178:179], 11, v[162:163]
	v_lshl_add_u64 v[178:179], v[178:179], 0, v[130:131]
	v_lshl_add_u64 v[178:179], v[178:179], 1, s[60:61]
	v_add_u32_e32 v238, 0x90, v162
	v_ashrrev_i32_e32 v239, 31, v238
	v_cmp_eq_u32_e32 vcc, 0, v168
	s_waitcnt vmcnt(0)
	v_pk_add_f32 v[128:129], v[128:129], v[142:143]
	v_pk_add_f32 v[126:127], v[126:127], v[140:141]
	v_pk_add_f32 v[124:125], v[124:125], v[146:147]
	v_pk_add_f32 v[122:123], v[122:123], v[144:145]
	v_pk_add_f32 v[142:143], v[112:113], v[176:177]
	v_pk_add_f32 v[140:141], v[110:111], v[174:175]
	v_pk_add_f32 v[146:147], v[108:109], v[172:173]
	v_pk_add_f32 v[144:145], v[106:107], v[170:171]
	v_pk_add_f32 v[112:113], v[120:121], v[190:191]
	v_pk_add_f32 v[110:111], v[118:119], v[188:189]
	v_pk_add_f32 v[108:109], v[116:117], v[194:195]
	v_pk_add_f32 v[106:107], v[114:115], v[192:193]
	v_cvt_pk_bf16_f32 v114, v126, v127
	v_cvt_pk_bf16_f32 v115, v128, v129
	v_cvt_pk_bf16_f32 v116, v122, v123
	v_cvt_pk_bf16_f32 v117, v124, v125
	v_pk_add_f32 v[104:105], v[104:105], v[198:199]
	v_pk_add_f32 v[102:103], v[102:103], v[196:197]
	v_pk_add_f32 v[100:101], v[100:101], v[202:203]
	v_pk_add_f32 v[98:99], v[98:99], v[200:201]
	global_store_dwordx4 v[148:149], v[126:129], off sc1
	global_store_dwordx4 v[148:149], v[122:125], off offset:16 sc1
	v_cvt_pk_bf16_f32 v118, v140, v141
	v_cvt_pk_bf16_f32 v119, v142, v143
	v_cvt_pk_bf16_f32 v120, v144, v145
	v_cvt_pk_bf16_f32 v121, v146, v147
	v_cvt_pk_bf16_f32 v170, v110, v111
	v_cvt_pk_bf16_f32 v171, v112, v113
	v_cvt_pk_bf16_f32 v172, v106, v107
	v_cvt_pk_bf16_f32 v173, v108, v109
	global_store_dwordx4 v[178:179], v[114:117], off sc1
	global_store_dwordx4 v[148:149], v[140:143], off offset:512 sc1
	global_store_dwordx4 v[148:149], v[144:147], off offset:528 sc1
	global_store_dwordx4 v[178:179], v[118:121], off offset:256 sc1
	global_store_dwordx4 v[164:165], v[110:113], off sc1
	global_store_dwordx4 v[164:165], v[106:109], off offset:16 sc1
	global_store_dwordx4 v[236:237], v[170:173], off sc1
	global_store_dwordx4 v[164:165], v[102:105], off offset:512 sc1
	global_store_dwordx4 v[164:165], v[98:101], off offset:528 sc1
	v_add_u32_e32 v178, 0x80, v162
	v_mul_f32_e32 v181, v125, v125
	v_cvt_pk_bf16_f32 v114, v102, v103
	v_cvt_pk_bf16_f32 v115, v104, v105
	v_cvt_pk_bf16_f32 v116, v98, v99
	v_cvt_pk_bf16_f32 v117, v100, v101
	v_ashrrev_i32_e32 v179, 31, v178
	v_fmac_f32_e32 v181, v124, v124
	global_store_dwordx4 v[236:237], v[114:117], off offset:256 sc1
	v_lshlrev_b64 v[124:125], 11, v[136:137]
	v_mul_f32_e32 v127, v127, v127
	v_lshlrev_b64 v[114:115], 13, v[178:179]
	v_mul_f32_e32 v129, v129, v129
	v_mul_f32_e32 v163, v123, v123
	v_lshl_add_u64 v[236:237], v[132:133], 0, v[114:115]
	v_lshlrev_b64 v[114:115], 13, v[238:239]
	v_lshl_add_u64 v[124:125], v[124:125], 0, v[130:131]
	v_pk_add_f32 v[96:97], v[96:97], v[210:211]
	v_pk_add_f32 v[94:95], v[94:95], v[208:209]
	v_pk_add_f32 v[92:93], v[92:93], v[206:207]
	v_pk_add_f32 v[90:91], v[90:91], v[204:205]
	v_fmac_f32_e32 v127, v126, v126
	v_fmac_f32_e32 v129, v128, v128
	v_fmac_f32_e32 v163, v122, v122
	v_lshl_add_u64 v[122:123], v[132:133], 0, v[114:115]
	v_cvt_pk_bf16_f32 v200, v94, v95
	v_cvt_pk_bf16_f32 v201, v96, v97
	v_cvt_pk_bf16_f32 v202, v90, v91
	v_cvt_pk_bf16_f32 v203, v92, v93
	v_lshl_add_u64 v[124:125], v[124:125], 1, s[60:61]
	v_pk_add_f32 v[88:89], v[88:89], v[218:219]
	v_pk_add_f32 v[86:87], v[86:87], v[216:217]
	v_pk_add_f32 v[80:81], v[80:81], v[214:215]
	v_pk_add_f32 v[78:79], v[78:79], v[212:213]
	v_add_f32_e32 v148, v127, v129
	global_load_dwordx4 v[126:129], v[236:237], off offset:16
	global_load_dwordx4 v[170:173], v[236:237], off
	global_load_dwordx4 v[174:177], v[236:237], off offset:528
	global_load_dwordx4 v[188:191], v[236:237], off offset:512
	global_load_dwordx4 v[192:195], v[122:123], off offset:16
; __device__ __forceinline__ float ssq4(const f32x4 o) { return (o[0] * o[0] + o[1] * o[1]) + (o[2] * o[2] + o[3] * o[3]); }
;     __device__ __forceinline__ void operator()(f32x4 (&acc)[2][2][4][2], const Unit& u, int wr, int wc, int fr, int fq) const {
;     ...
;             for (int c = 0; c < 4; ++c) cur[q][c] = *(const f32x4*)(base + (size_t)EPI_ROW(q) * D + col0 + (c >> 1) * HALF + (c & 1) * 4);
; #pragma unroll
;         for (int k = 0; k < 4; ++k) {
;             if (k < 3) {
; #pragma unroll
;                 for (int q = 0; q < 2; ++q)
; #pragma unroll
;                     for (int c = 0; c < 4; ++c) nxt[q][c] = *(const f32x4*)(base + (size_t)EPI_ROW(2 * k + 2 + q) * D + col0 + (c >> 1) * HALF + (c & 1) * 4);
;             }
;             asm volatile("" ::: "memory");
; #pragma unroll
;             for (int q = 0; q < 2; ++q) { const int r = 2 * k + q, ai = r >> 2, m = r & 3; const size_t off = (size_t)EPI_ROW(r) * D + col0; float sr = 0.f;
; #pragma unroll
;                 for (int bj = 0; bj < 2; ++bj) { const f32x4 o0 = cur[q][2 * bj] + acc[ai][bj][m][0], o1 = cur[q][2 * bj + 1] + acc[ai][bj][m][1];
;                     *(f32x4*)(out + off + bj * HALF) = o0; *(f32x4*)(out + off + bj * HALF + 4) = o1;
;                     u32x4 w; w.x = cvt_pk_bf16(o0[0], o0[1]); w.y = cvt_pk_bf16(o0[2], o0[3]); w.z = cvt_pk_bf16(o1[0], o1[1]); w.w = cvt_pk_bf16(o1[2], o1[3]); *(u32x4*)(hb + off + bj * HALF) = w; sr += ssq4(o0) + ssq4(o1); }
;                 s[ai][m] = sr; }
	global_load_dwordx4 v[196:199], v[122:123], off
	global_load_dwordx4 v[114:117], v[122:123], off offset:528
	global_load_dwordx4 v[118:121], v[122:123], off offset:512
	global_store_dwordx4 v[184:185], v[94:97], off sc1
	global_store_dwordx4 v[184:185], v[90:93], off offset:16 sc1
	global_store_dwordx4 v[124:125], v[200:203], off sc1
	global_store_dwordx4 v[184:185], v[86:89], off offset:512 sc1
	global_store_dwordx4 v[184:185], v[78:81], off offset:528 sc1
	v_cvt_pk_bf16_f32 v200, v86, v87
	v_cvt_pk_bf16_f32 v201, v88, v89
	v_cvt_pk_bf16_f32 v202, v78, v79
	v_cvt_pk_bf16_f32 v203, v80, v81
	global_store_dwordx4 v[124:125], v[200:203], off offset:256 sc1
	v_lshlrev_b64 v[124:125], 11, v[134:135]
	v_lshl_add_u64 v[124:125], v[124:125], 0, v[130:131]
	v_pk_add_f32 v[84:85], v[84:85], v[226:227]
	v_pk_add_f32 v[82:83], v[82:83], v[224:225]
	v_pk_add_f32 v[76:77], v[76:77], v[222:223]
	v_pk_add_f32 v[74:75], v[74:75], v[220:221]
	v_cvt_pk_bf16_f32 v134, v82, v83
	v_cvt_pk_bf16_f32 v135, v84, v85
	v_cvt_pk_bf16_f32 v136, v74, v75
	v_cvt_pk_bf16_f32 v137, v76, v77
	v_lshl_add_u64 v[124:125], v[124:125], 1, s[60:61]
	v_pk_add_f32 v[72:73], v[72:73], v[234:235]
	v_pk_add_f32 v[70:71], v[70:71], v[232:233]
	v_pk_add_f32 v[68:69], v[68:69], v[230:231]
	v_pk_add_f32 v[66:67], v[66:67], v[228:229]
	v_add_u32_e32 v184, 0xa0, v162
	global_store_dwordx4 v[138:139], v[82:85], off sc1
	global_store_dwordx4 v[138:139], v[74:77], off offset:16 sc1
	global_store_dwordx4 v[124:125], v[134:137], off sc1
	v_ashrrev_i32_e32 v185, 31, v184
	global_store_dwordx4 v[138:139], v[70:73], off offset:512 sc1
	global_store_dwordx4 v[138:139], v[66:69], off offset:528 sc1
	v_cvt_pk_bf16_f32 v134, v70, v71
	v_cvt_pk_bf16_f32 v135, v72, v73
	v_cvt_pk_bf16_f32 v136, v66, v67
	v_cvt_pk_bf16_f32 v137, v68, v69
	global_store_dwordx4 v[124:125], v[134:137], off offset:256 sc1
	v_lshlrev_b64 v[124:125], 13, v[184:185]
	v_lshl_add_u64 v[212:213], v[132:133], 0, v[124:125]
	v_add_f32_e32 v124, v163, v181
	v_mul_f32_e32 v125, v141, v141
	v_mul_f32_e32 v138, v143, v143
	global_load_dwordx4 v[134:137], v[212:213], off offset:16
	global_load_dwordx4 v[200:203], v[212:213], off
	v_add_f32_e32 v124, v148, v124
	v_fmac_f32_e32 v125, v140, v140
	v_fmac_f32_e32 v138, v142, v142
	v_mul_f32_e32 v148, v145, v145
	v_mul_f32_e32 v147, v147, v147
	v_add_f32_e32 v125, v125, v138
	v_fmac_f32_e32 v148, v144, v144
	global_load_dwordx4 v[138:141], v[212:213], off offset:528
	global_load_dwordx4 v[142:145], v[212:213], off offset:512
	v_fmac_f32_e32 v147, v146, v146
	v_add_f32_e32 v146, v148, v147
	v_add_u32_e32 v214, 0xb0, v162
	v_add_f32_e32 v125, v125, v146
	v_ashrrev_i32_e32 v215, 31, v214
	v_add_f32_e32 v181, v124, v125
	v_lshlrev_b64 v[124:125], 13, v[214:215]
	v_lshl_add_u64 v[124:125], v[132:133], 0, v[124:125]
	global_load_dwordx4 v[146:149], v[124:125], off offset:16
	global_load_dwordx4 v[162:165], v[124:125], off
	global_load_dwordx4 v[204:207], v[124:125], off offset:528
	global_load_dwordx4 v[208:211], v[124:125], off offset:512
	v_lshlrev_b64 v[132:133], 11, v[178:179]
	v_lshl_add_u64 v[132:133], v[132:133], 0, v[130:131]
	v_lshl_add_u64 v[132:133], v[132:133], 1, s[60:61]
	s_waitcnt vmcnt(27)
	v_pk_add_f32 v[60:61], v[60:61], v[128:129]
	s_waitcnt vmcnt(26)
	v_pk_add_f32 v[64:65], v[64:65], v[172:173]
	v_pk_add_f32 v[62:63], v[62:63], v[170:171]
	v_pk_add_f32 v[58:59], v[58:59], v[126:127]
	v_cvt_pk_bf16_f32 v126, v62, v63
	v_cvt_pk_bf16_f32 v127, v64, v65
	v_cvt_pk_bf16_f32 v128, v58, v59
	v_cvt_pk_bf16_f32 v129, v60, v61
	s_waitcnt vmcnt(24)
	v_pk_add_f32 v[56:57], v[56:57], v[190:191]
	v_pk_add_f32 v[54:55], v[54:55], v[188:189]
	v_pk_add_f32 v[48:49], v[48:49], v[176:177]
	v_pk_add_f32 v[46:47], v[46:47], v[174:175]
	global_store_dwordx4 v[236:237], v[62:65], off sc1
	global_store_dwordx4 v[236:237], v[58:61], off offset:16 sc1
	global_store_dwordx4 v[132:133], v[126:129], off sc1
	global_store_dwordx4 v[236:237], v[54:57], off offset:512 sc1
	global_store_dwordx4 v[236:237], v[46:49], off offset:528 sc1
	v_cvt_pk_bf16_f32 v126, v54, v55
	v_cvt_pk_bf16_f32 v127, v56, v57
	v_cvt_pk_bf16_f32 v128, v46, v47
	v_cvt_pk_bf16_f32 v129, v48, v49
	global_store_dwordx4 v[132:133], v[126:129], off offset:256 sc1
	s_waitcnt vmcnt(28)
; __device__ __forceinline__ float shx(float v, int o, int lane) { return __builtin_bit_cast(float, __builtin_amdgcn_ds_bpermute((lane ^ o) << 2, __builtin_bit_cast(int, v))); }
; __device__ __forceinline__ float ssq4(const f32x4 o) { return (o[0] * o[0] + o[1] * o[1]) + (o[2] * o[2] + o[3] * o[3]); }
; template <bool SIXTEEN> __device__ __forceinline__ void tile_ssq(const float (&s)[2][4], const Unit& u, int wr, int wc, int fr, int fq, float* ssq, LAS float* ptab) {
;     ...
;         for (int m = 0; m < 4; ++m) { float v = s[ai][m]; v += shx(v, 16, lane); v += shx(v, 32, lane); if (fq == 0) ptab[(ai * HALF + wr * 64 + m * 16 + fr) * 4 + wc] = v; }
;     __device__ __forceinline__ void operator()(f32x4 (&acc)[2][2][4][2], const Unit& u, int wr, int wc, int fr, int fq) const {
;     ...
;             for (int q = 0; q < 2; ++q) { const int r = 2 * k + q, ai = r >> 2, m = r & 3; const size_t off = (size_t)EPI_ROW(r) * D + col0; float sr = 0.f;
; #pragma unroll
;                 for (int bj = 0; bj < 2; ++bj) { const f32x4 o0 = cur[q][2 * bj] + acc[ai][bj][m][0], o1 = cur[q][2 * bj + 1] + acc[ai][bj][m][1];
;                     *(f32x4*)(out + off + bj * HALF) = o0; *(f32x4*)(out + off + bj * HALF + 4) = o1;
;                     u32x4 w; w.x = cvt_pk_bf16(o0[0], o0[1]); w.y = cvt_pk_bf16(o0[2], o0[3]); w.z = cvt_pk_bf16(o1[0], o1[1]); w.w = cvt_pk_bf16(o1[2], o1[3]); *(u32x4*)(hb + off + bj * HALF) = w; sr += ssq4(o0) + ssq4(o1); }
;                 s[ai][m] = sr; }
	v_pk_add_f32 v[52:53], v[52:53], v[198:199]
	v_pk_add_f32 v[50:51], v[50:51], v[196:197]
	v_lshlrev_b64 v[126:127], 11, v[238:239]
	v_lshl_add_u64 v[132:133], v[126:127], 0, v[130:131]
	v_pk_add_f32 v[44:45], v[44:45], v[194:195]
	v_pk_add_f32 v[42:43], v[42:43], v[192:193]
	s_waitcnt vmcnt(26)
	v_pk_add_f32 v[40:41], v[40:41], v[120:121]
	v_pk_add_f32 v[38:39], v[38:39], v[118:119]
	v_pk_add_f32 v[36:37], v[36:37], v[116:117]
	v_pk_add_f32 v[34:35], v[34:35], v[114:115]
	v_cvt_pk_bf16_f32 v126, v50, v51
	v_cvt_pk_bf16_f32 v127, v52, v53
	v_cvt_pk_bf16_f32 v128, v42, v43
	v_cvt_pk_bf16_f32 v129, v44, v45
	v_lshl_add_u64 v[132:133], v[132:133], 1, s[60:61]
	v_cvt_pk_bf16_f32 v114, v38, v39
	v_cvt_pk_bf16_f32 v115, v40, v41
	v_cvt_pk_bf16_f32 v116, v34, v35
	v_cvt_pk_bf16_f32 v117, v36, v37
	global_store_dwordx4 v[122:123], v[50:53], off sc1
	global_store_dwordx4 v[122:123], v[42:45], off offset:16 sc1
	global_store_dwordx4 v[132:133], v[126:129], off sc1
	global_store_dwordx4 v[122:123], v[38:41], off offset:512 sc1
	global_store_dwordx4 v[122:123], v[34:37], off offset:528 sc1
	global_store_dwordx4 v[132:133], v[114:117], off offset:256 sc1
	s_waitcnt vmcnt(19)
	v_pk_add_f32 v[28:29], v[28:29], v[136:137]
	s_waitcnt vmcnt(18)
	v_pk_add_f32 v[32:33], v[32:33], v[202:203]
	v_lshlrev_b64 v[114:115], 11, v[184:185]
	v_lshl_add_u64 v[118:119], v[114:115], 0, v[130:131]
	v_pk_add_f32 v[30:31], v[30:31], v[200:201]
	v_pk_add_f32 v[26:27], v[26:27], v[134:135]
	v_cvt_pk_bf16_f32 v114, v30, v31
	v_cvt_pk_bf16_f32 v115, v32, v33
	v_cvt_pk_bf16_f32 v116, v26, v27
	v_cvt_pk_bf16_f32 v117, v28, v29
	v_lshl_add_u64 v[118:119], v[118:119], 1, s[60:61]
	s_waitcnt vmcnt(16)
	v_pk_add_f32 v[24:25], v[24:25], v[144:145]
	v_pk_add_f32 v[22:23], v[22:23], v[142:143]
	v_pk_add_f32 v[16:17], v[16:17], v[140:141]
	v_pk_add_f32 v[14:15], v[14:15], v[138:139]
	global_store_dwordx4 v[212:213], v[30:33], off sc1
	global_store_dwordx4 v[212:213], v[26:29], off offset:16 sc1
	global_store_dwordx4 v[118:119], v[114:117], off sc1
	global_store_dwordx4 v[212:213], v[22:25], off offset:512 sc1
	global_store_dwordx4 v[212:213], v[14:17], off offset:528 sc1
	v_cvt_pk_bf16_f32 v114, v22, v23
	v_cvt_pk_bf16_f32 v115, v24, v25
	v_cvt_pk_bf16_f32 v116, v14, v15
	v_cvt_pk_bf16_f32 v117, v16, v17
	global_store_dwordx4 v[118:119], v[114:117], off offset:256 sc1
	s_waitcnt vmcnt(20)
	v_pk_add_f32 v[20:21], v[20:21], v[164:165]
	v_pk_add_f32 v[18:19], v[18:19], v[162:163]
	v_lshlrev_b64 v[114:115], 11, v[214:215]
	v_lshl_add_u64 v[118:119], v[114:115], 0, v[130:131]
	v_pk_add_f32 v[12:13], v[12:13], v[148:149]
	v_pk_add_f32 v[10:11], v[10:11], v[146:147]
	v_cvt_pk_bf16_f32 v114, v18, v19
	v_cvt_pk_bf16_f32 v115, v20, v21
	v_cvt_pk_bf16_f32 v116, v10, v11
	v_cvt_pk_bf16_f32 v117, v12, v13
	v_lshl_add_u64 v[120:121], v[118:119], 1, s[60:61]
	global_store_dwordx4 v[124:125], v[18:21], off sc1
	global_store_dwordx4 v[124:125], v[10:13], off offset:16 sc1
	global_store_dwordx4 v[120:121], v[114:117], off sc1
	s_waitcnt vmcnt(21)
	v_pk_add_f32 v[8:9], v[8:9], v[210:211]
	v_pk_add_f32 v[6:7], v[6:7], v[208:209]
	v_and_b32_e32 v114, 63, v169
	v_lshlrev_b32_e32 v122, 2, v114
	v_xor_b32_e32 v115, 64, v122
	ds_bpermute_b32 v123, v115, v181
	v_pk_add_f32 v[4:5], v[4:5], v[206:207]
	v_pk_add_f32 v[2:3], v[2:3], v[204:205]
	v_cvt_pk_bf16_f32 v116, v6, v7
	v_cvt_pk_bf16_f32 v117, v8, v9
	v_cvt_pk_bf16_f32 v118, v2, v3
	v_cvt_pk_bf16_f32 v119, v4, v5
	global_store_dwordx4 v[124:125], v[6:9], off offset:512 sc1
	global_store_dwordx4 v[124:125], v[2:5], off offset:528 sc1
	global_store_dwordx4 v[120:121], v[116:119], off offset:256 sc1
	s_nop 1
	v_xor_b32_e32 v117, 0x80, v122
	s_waitcnt lgkmcnt(0)
	v_add_f32_e32 v118, v181, v123
	ds_bpermute_b32 v119, v117, v118
	v_lshl_add_u32 v116, v167, 4, s33
	s_and_saveexec_b64 s[8:9], vcc
	s_cbranch_execz .LBB0_2240
	s_waitcnt lgkmcnt(0)
	v_add_f32_e32 v118, v118, v119
	ds_write_b32 v116, v118

; __device__ __forceinline__ float shx(float v, int o, int lane) { return __builtin_bit_cast(float, __builtin_amdgcn_ds_bpermute((lane ^ o) << 2, __builtin_bit_cast(int, v))); }
; __device__ __forceinline__ void rows_rstd(const float* ssq, int row0  , int fr, int fq, float (&rs)[8]) {
;     const int lane = fq * 16 + fr; f32x4 p[8];
;     const float* b0 = ssq + (size_t)row0 * 16 + fq * 4;
; #pragma unroll
;     for (int r = 0; r < 8; ++r) p[r] = *(const f32x4*)(b0 + (r >> 2) * (HALF * 16) + (r & 3) * 256);
; #pragma unroll
;     for (int r = 0; r < 8; ++r) { float v = (p[r][0] + p[r][1]) + (p[r][2] + p[r][3]); v += shx(v, 16, lane); v += shx(v, 32, lane); rs[r] = rsqrtf(v * (1.0f / 2048.0f) + 1e-6f); }
; }
;     __device__ __forceinline__ void operator()(f32x4 (&acc)[2][2][4][2], const Unit& u, int wr, int wc, int fr, int fq) const {
;     ...
;         { float rsv[8]; rows_rstd(ssq_in, u.pm * BM + wr * 64 + fr, fr, fq, rsv);
; #pragma unroll
;             for (int r = 0; r < 8; ++r)
; #pragma unroll
;                 for (int c = 0; c < 4; ++c) acc[r >> 2][c >> 1][r & 3][c & 1] = acc[r >> 2][c >> 1][r & 3][c & 1] * rsv[r]; }
.LBB0_2335:
	v_mov_b32_e32 v183, v246
	s_lshl_b32 s1, s8, 8
	s_add_i32 s3, s1, s68
	v_and_b32_e32 v184, 15, v183
	v_or_b32_e32 v172, s3, v184
	v_ashrrev_i32_e32 v173, 31, v172
	v_readlane_b32 s8, v254, 13
	v_bfe_u32 v185, v183, 4, 2
	v_lshlrev_b64 v[130:131], 6, v[172:173]
	v_readlane_b32 s9, v254, 14
	v_lshlrev_b32_e32 v132, 4, v185
	v_mov_b32_e32 v133, v0
	v_lshl_add_u64 v[130:131], s[8:9], 0, v[130:131]
	v_lshl_add_u64 v[130:131], v[130:131], 0, v[132:133]
	global_load_dwordx4 v[174:177], v[130:131], off
	global_load_dwordx4 v[188:191], v[130:131], off offset:1024
	global_load_dwordx4 v[150:153], v[130:131], off offset:2048
	global_load_dwordx4 v[146:149], v[130:131], off offset:3072
	v_add_co_u32_e32 v130, vcc, s63, v130
	v_lshlrev_b32_e32 v166, 6, v185
	s_nop 0
	v_addc_co_u32_e32 v131, vcc, 0, v131, vcc
	global_load_dwordx4 v[142:145], v[130:131], off
	global_load_dwordx4 v[138:141], v[130:131], off offset:1024
	global_load_dwordx4 v[134:137], v[130:131], off offset:2048
	s_nop 0
	global_load_dwordx4 v[130:133], v[130:131], off offset:3072
	v_lshlrev_b32_e32 v167, 2, v184
	v_bitop3_b32 v169, v166, 64, v167 bitop3:0x36
	v_bitop3_b32 v167, v166, s71, v167 bitop3:0x36
	s_mov_b32 s8, 0x358637bd
	v_mov_b32_e32 v182, v246
	v_or_b32_e32 v242, 32, v172
	v_or_b32_e32 v228, 48, v172
	v_ashrrev_i32_e32 v243, 31, v242
	v_ashrrev_i32_e32 v229, 31, v228
	s_waitcnt vmcnt(0)
	v_mov_b32_e32 v170, v175
	v_mov_b32_e32 v171, v176
	v_mov_b32_e32 v175, v177
	v_pk_add_f32 v[170:171], v[170:171], v[174:175]
	v_mov_b32_e32 v174, v189
	v_mov_b32_e32 v175, v190
	v_mov_b32_e32 v189, v191
	v_pk_add_f32 v[174:175], v[174:175], v[188:189]
	v_mov_b32_e32 v177, v170
	v_mov_b32_e32 v176, v174
	v_mov_b32_e32 v170, v175
	v_pk_add_f32 v[170:171], v[176:177], v[170:171]
	ds_bpermute_b32 v175, v169, v171
	ds_bpermute_b32 v174, v169, v170
	s_waitcnt lgkmcnt(0)
	v_pk_add_f32 v[170:171], v[170:171], v[174:175]
	ds_bpermute_b32 v175, v167, v171
	ds_bpermute_b32 v174, v167, v170
	s_waitcnt lgkmcnt(0)
	v_pk_add_f32 v[174:175], v[170:171], v[174:175]
	v_mov_b64_e32 v[170:171], s[8:9]
	v_pk_fma_f32 v[174:175], v[174:175], s[2:3], v[170:171] op_sel_hi:[1,0,0]
	s_nop 0
	v_mul_f32_e32 v166, 0x4b800000, v175
	v_cmp_gt_f32_e64 s[8:9], s46, v175
	v_cmp_gt_f32_e32 vcc, s46, v174
	s_nop 0
	v_cndmask_b32_e64 v166, v175, v166, s[8:9]
	v_rsq_f32_e32 v166, v166
	v_mov_b32_e32 v175, v152
	v_mov_b32_e32 v152, v147
	v_mov_b32_e32 v147, v149
	v_mul_f32_e32 v168, 0x45800000, v166
	v_cndmask_b32_e64 v168, v166, v168, s[8:9]
	v_mul_f32_e32 v166, 0x4b800000, v174
	v_cndmask_b32_e32 v166, v174, v166, vcc
	v_rsq_f32_e32 v166, v166
	v_pk_mul_f32 v[252:253], v[128:129], v[168:169] op_sel_hi:[1,0]
	v_pk_mul_f32 v[178:179], v[126:127], v[168:169] op_sel_hi:[1,0]
	v_pk_mul_f32 v[248:249], v[124:125], v[168:169] op_sel_hi:[1,0]
	v_mul_f32_e32 v174, 0x45800000, v166
	v_cndmask_b32_e32 v166, v166, v174, vcc
	v_mov_b32_e32 v174, v151
	v_mov_b32_e32 v151, v153
	v_mov_b32_e32 v153, v148
	v_pk_add_f32 v[150:151], v[174:175], v[150:151]
	v_pk_add_f32 v[146:147], v[152:153], v[146:147]
	v_mov_b32_e32 v149, v150
	v_mov_b32_e32 v148, v146
	v_mov_b32_e32 v150, v147
	v_pk_add_f32 v[146:147], v[148:149], v[150:151]
	ds_bpermute_b32 v149, v169, v147
	ds_bpermute_b32 v148, v169, v146
	v_mov_b32_e32 v150, v143
	v_mov_b32_e32 v151, v144
	v_mov_b32_e32 v143, v145
	v_mov_b32_e32 v144, v139
	v_mov_b32_e32 v145, v140
	v_mov_b32_e32 v139, v141
	v_pk_add_f32 v[142:143], v[150:151], v[142:143]
	v_pk_add_f32 v[138:139], v[144:145], v[138:139]
	s_waitcnt lgkmcnt(0)
	v_pk_add_f32 v[146:147], v[146:147], v[148:149]
	v_mov_b32_e32 v140, v138
	v_mov_b32_e32 v141, v142
	v_mov_b32_e32 v142, v139
	ds_bpermute_b32 v149, v167, v147
	ds_bpermute_b32 v148, v167, v146
	v_pk_add_f32 v[138:139], v[140:141], v[142:143]
	ds_bpermute_b32 v141, v169, v139
	ds_bpermute_b32 v140, v169, v138
	v_mov_b32_e32 v142, v135
	v_mov_b32_e32 v143, v136
	v_mov_b32_e32 v135, v137
	v_mov_b32_e32 v136, v131
	v_mov_b32_e32 v137, v132
	v_mov_b32_e32 v131, v133
	s_waitcnt lgkmcnt(2)
	v_pk_add_f32 v[146:147], v[146:147], v[148:149]
	v_pk_add_f32 v[134:135], v[142:143], v[134:135]
	v_pk_add_f32 v[130:131], v[136:137], v[130:131]
	v_pk_fma_f32 v[146:147], v[146:147], s[2:3], v[170:171] op_sel_hi:[1,0,0]
	s_waitcnt lgkmcnt(0)
	v_pk_add_f32 v[138:139], v[138:139], v[140:141]
	v_mov_b32_e32 v132, v130
	v_mov_b32_e32 v133, v134
	v_mov_b32_e32 v134, v131
	v_mul_f32_e32 v148, 0x4b800000, v147
	v_cmp_gt_f32_e64 s[8:9], s46, v147
	ds_bpermute_b32 v141, v167, v139
	ds_bpermute_b32 v140, v167, v138
	v_pk_add_f32 v[130:131], v[132:133], v[134:135]
	v_cndmask_b32_e64 v147, v147, v148, s[8:9]
	ds_bpermute_b32 v133, v169, v131
	ds_bpermute_b32 v132, v169, v130
	v_rsq_f32_e32 v147, v147
	s_waitcnt lgkmcnt(2)
	v_pk_add_f32 v[138:139], v[138:139], v[140:141]
	v_cmp_gt_f32_e32 vcc, s46, v146
	v_pk_fma_f32 v[138:139], v[138:139], s[2:3], v[170:171] op_sel_hi:[1,0,0]
	v_mul_f32_e32 v148, 0x45800000, v147
	s_waitcnt lgkmcnt(0)
	v_pk_add_f32 v[130:131], v[130:131], v[132:133]
	v_cndmask_b32_e64 v148, v147, v148, s[8:9]
	v_mul_f32_e32 v147, 0x4b800000, v146
	v_mul_f32_e32 v140, 0x4b800000, v139
	v_cmp_gt_f32_e64 s[8:9], s46, v139
	ds_bpermute_b32 v133, v167, v131
	ds_bpermute_b32 v132, v167, v130
	v_cndmask_b32_e32 v146, v146, v147, vcc
	v_cndmask_b32_e64 v139, v139, v140, s[8:9]
	v_rsq_f32_e32 v146, v146
	v_rsq_f32_e32 v139, v139
	s_waitcnt lgkmcnt(0)
;     __device__ __forceinline__ void operator()(f32x4 (&acc)[2][2][4][2], const Unit& u, int wr, int wc, int fr, int fq) const {
;     ...
;         { float rsv[8]; rows_rstd(ssq_in, u.pm * BM + wr * 64 + fr, fr, fq, rsv);
; #pragma unroll
;             for (int r = 0; r < 8; ++r)
; #pragma unroll
;                 for (int c = 0; c < 4; ++c) acc[r >> 2][c >> 1][r & 3][c & 1] = acc[r >> 2][c >> 1][r & 3][c & 1] * rsv[r]; }
;         f32x4 cur[2][4], nxt[2][4]; u32x2 pcur[4], pnxt[4];
; #pragma unroll
;         for (int q = 0; q < 2; ++q)
; #pragma unroll
;             for (int c = 0; c < 4; ++c) cur[q][c] = *(const f32x4*)(h + (size_t)EPI_ROW(q) * D + col0 + (c >> 1) * HALF + (c & 1) * 4);
; #pragma unroll
;         for (int c = 0; c < 4; ++c) pcur[c] = *(const u32x2*)(pp + (size_t)EPI_ROW(0) * D + col0 + (c >> 1) * HALF + (c & 1) * 4);
	v_pk_add_f32 v[130:131], v[130:131], v[132:133]
	v_pk_mul_f32 v[250:251], v[122:123], v[168:169] op_sel_hi:[1,0]
	v_mul_f32_e32 v147, 0x45800000, v146
	v_mul_f32_e32 v140, 0x45800000, v139
	v_pk_fma_f32 v[130:131], v[130:131], s[2:3], v[170:171] op_sel_hi:[1,0,0]
	v_cndmask_b32_e32 v146, v146, v147, vcc
	v_cmp_gt_f32_e32 vcc, s46, v138
	v_cndmask_b32_e64 v140, v139, v140, s[8:9]
	v_mul_f32_e32 v139, 0x4b800000, v138
	v_mul_f32_e32 v132, 0x4b800000, v131
	v_cmp_gt_f32_e64 s[8:9], s46, v131
	v_cndmask_b32_e32 v138, v138, v139, vcc
	v_rsq_f32_e32 v138, v138
	v_cndmask_b32_e64 v131, v131, v132, s[8:9]
	v_rsq_f32_e32 v131, v131
	s_lshl_b32 s3, s0, 8
	v_mul_f32_e32 v139, 0x45800000, v138
	v_cndmask_b32_e32 v138, v138, v139, vcc
	v_mul_f32_e32 v132, 0x45800000, v131
	v_cmp_gt_f32_e32 vcc, s46, v130
	v_cndmask_b32_e64 v132, v131, v132, s[8:9]
	v_mul_f32_e32 v131, 0x4b800000, v130
	v_cndmask_b32_e32 v130, v130, v131, vcc
	v_rsq_f32_e32 v130, v130
	s_or_b32 s3, s3, s69
	v_pk_mul_f32 v[244:245], v[112:113], v[168:169] op_sel_hi:[1,0]
	v_pk_mul_f32 v[246:247], v[110:111], v[168:169] op_sel_hi:[1,0]
	v_mul_f32_e32 v131, 0x45800000, v130
	v_cndmask_b32_e32 v152, v130, v131, vcc
	v_pk_mul_f32 v[238:239], v[108:109], v[168:169] op_sel_hi:[1,0]
	v_pk_mul_f32 v[240:241], v[106:107], v[168:169] op_sel_hi:[1,0]
	v_pk_mul_f32 v[234:235], v[120:121], v[166:167] op_sel_hi:[1,0]
	v_pk_mul_f32 v[236:237], v[118:119], v[166:167] op_sel_hi:[1,0]
	v_pk_mul_f32 v[222:223], v[116:117], v[166:167] op_sel_hi:[1,0]
	v_pk_mul_f32 v[232:233], v[114:115], v[166:167] op_sel_hi:[1,0]
	v_pk_mul_f32 v[96:97], v[96:97], v[166:167] op_sel_hi:[1,0]
	v_pk_mul_f32 v[94:95], v[94:95], v[166:167] op_sel_hi:[1,0]
	v_pk_mul_f32 v[92:93], v[92:93], v[166:167] op_sel_hi:[1,0]
	v_pk_mul_f32 v[90:91], v[90:91], v[166:167] op_sel_hi:[1,0]
	v_pk_mul_f32 v[224:225], v[104:105], v[148:149] op_sel_hi:[1,0]
	v_pk_mul_f32 v[226:227], v[102:103], v[148:149] op_sel_hi:[1,0]
	v_pk_mul_f32 v[126:127], v[100:101], v[148:149] op_sel_hi:[1,0]
	v_pk_mul_f32 v[128:129], v[98:99], v[148:149] op_sel_hi:[1,0]
	v_pk_mul_f32 v[122:123], v[80:81], v[148:149] op_sel_hi:[1,0]
	v_pk_mul_f32 v[124:125], v[78:79], v[148:149] op_sel_hi:[1,0]
	v_pk_mul_f32 v[114:115], v[76:77], v[148:149] op_sel_hi:[1,0]
	v_pk_mul_f32 v[116:117], v[74:75], v[148:149] op_sel_hi:[1,0]
	v_pk_mul_f32 v[110:111], v[88:89], v[146:147] op_sel_hi:[1,0]
	v_pk_mul_f32 v[112:113], v[86:87], v[146:147] op_sel_hi:[1,0]
	v_pk_mul_f32 v[106:107], v[84:85], v[146:147] op_sel_hi:[1,0]
	v_pk_mul_f32 v[108:109], v[82:83], v[146:147] op_sel_hi:[1,0]
	v_pk_mul_f32 v[102:103], v[72:73], v[146:147] op_sel_hi:[1,0]
	v_pk_mul_f32 v[104:105], v[70:71], v[146:147] op_sel_hi:[1,0]
	v_pk_mul_f32 v[98:99], v[68:69], v[146:147] op_sel_hi:[1,0]
	v_pk_mul_f32 v[100:101], v[66:67], v[146:147] op_sel_hi:[1,0]
	v_pk_mul_f32 v[218:219], v[64:65], v[140:141] op_sel_hi:[1,0]
	v_pk_mul_f32 v[220:221], v[62:63], v[140:141] op_sel_hi:[1,0]
	v_pk_mul_f32 v[214:215], v[60:61], v[140:141] op_sel_hi:[1,0]
	v_pk_mul_f32 v[216:217], v[58:59], v[140:141] op_sel_hi:[1,0]
	v_pk_mul_f32 v[210:211], v[44:45], v[140:141] op_sel_hi:[1,0]
	v_pk_mul_f32 v[212:213], v[42:43], v[140:141] op_sel_hi:[1,0]
	v_pk_mul_f32 v[206:207], v[36:37], v[140:141] op_sel_hi:[1,0]
	v_pk_mul_f32 v[208:209], v[34:35], v[140:141] op_sel_hi:[1,0]
	v_pk_mul_f32 v[202:203], v[56:57], v[138:139] op_sel_hi:[1,0]
	v_pk_mul_f32 v[204:205], v[54:55], v[138:139] op_sel_hi:[1,0]
	v_pk_mul_f32 v[196:197], v[52:53], v[138:139] op_sel_hi:[1,0]
	v_pk_mul_f32 v[200:201], v[50:51], v[138:139] op_sel_hi:[1,0]
	v_pk_mul_f32 v[192:193], v[28:29], v[138:139] op_sel_hi:[1,0]
	v_pk_mul_f32 v[194:195], v[26:27], v[138:139] op_sel_hi:[1,0]
	v_pk_mul_f32 v[188:189], v[20:21], v[138:139] op_sel_hi:[1,0]
	v_pk_mul_f32 v[190:191], v[18:19], v[138:139] op_sel_hi:[1,0]
	v_pk_mul_f32 v[174:175], v[48:49], v[132:133] op_sel_hi:[1,0]
	v_pk_mul_f32 v[176:177], v[46:47], v[132:133] op_sel_hi:[1,0]
	v_pk_mul_f32 v[168:169], v[40:41], v[132:133] op_sel_hi:[1,0]
	v_pk_mul_f32 v[170:171], v[38:39], v[132:133] op_sel_hi:[1,0]
	v_pk_mul_f32 v[150:151], v[16:17], v[132:133] op_sel_hi:[1,0]
	v_pk_mul_f32 v[166:167], v[14:15], v[132:133] op_sel_hi:[1,0]
	v_pk_mul_f32 v[146:147], v[12:13], v[132:133] op_sel_hi:[1,0]
	v_pk_mul_f32 v[148:149], v[10:11], v[132:133] op_sel_hi:[1,0]
	v_pk_mul_f32 v[142:143], v[32:33], v[152:153] op_sel_hi:[1,0]
	v_pk_mul_f32 v[144:145], v[30:31], v[152:153] op_sel_hi:[1,0]
	v_pk_mul_f32 v[138:139], v[24:25], v[152:153] op_sel_hi:[1,0]
	v_pk_mul_f32 v[140:141], v[22:23], v[152:153] op_sel_hi:[1,0]
	v_pk_mul_f32 v[134:135], v[8:9], v[152:153] op_sel_hi:[1,0]
	v_pk_mul_f32 v[136:137], v[6:7], v[152:153] op_sel_hi:[1,0]
	v_pk_mul_f32 v[130:131], v[4:5], v[152:153] op_sel_hi:[1,0]
	v_pk_mul_f32 v[132:133], v[2:3], v[152:153] op_sel_hi:[1,0]
	v_lshl_or_b32 v152, v185, 3, s3
	v_ashrrev_i32_e32 v153, 31, v152
	v_or_b32_e32 v84, 16, v172
	v_lshl_add_u64 v[118:119], v[152:153], 2, s[36:37]
	v_lshlrev_b64 v[2:3], 13, v[172:173]
	v_ashrrev_i32_e32 v85, 31, v84
	v_lshlrev_b64 v[18:19], 12, v[172:173]
	v_lshl_add_u64 v[86:87], v[118:119], 0, v[2:3]
	v_lshlrev_b64 v[2:3], 13, v[84:85]
	v_lshl_add_u64 v[18:19], s[56:57], 0, v[18:19]
	v_lshlrev_b64 v[198:199], 1, v[152:153]
	v_lshl_add_u64 v[82:83], v[118:119], 0, v[2:3]
	v_lshl_add_u64 v[18:19], v[18:19], 0, v[198:199]
	global_load_dwordx4 v[66:69], v[86:87], off offset:16
	global_load_dwordx4 v[78:81], v[86:87], off
	global_load_dwordx4 v[54:57], v[86:87], off offset:528
	global_load_dwordx4 v[62:65], v[86:87], off offset:512
	global_load_dwordx4 v[6:9], v[82:83], off offset:16
; __device__ __forceinline__ float sigmoidf_(float x) { return __builtin_amdgcn_rcpf(1.0f + __expf(-x)); }
; __device__ __forceinline__ float ssq4(const f32x4 o) { return (o[0] * o[0] + o[1] * o[1]) + (o[2] * o[2] + o[3] * o[3]); }
;     __device__ __forceinline__ void operator()(f32x4 (&acc)[2][2][4][2], const Unit& u, int wr, int wc, int fr, int fq) const {
;     ...
;             for (int q = 0; q < 2; ++q) { const int r = 2 * k + q, ai = r >> 2, m = r & 3; const size_t off = (size_t)EPI_ROW(r) * D + col0; float sr = 0.f;
;                 if (r < 7) {
; #pragma unroll
;                     for (int c = 0; c < 4; ++c) pnxt[c] = *(const u32x2*)(pp + (size_t)EPI_ROW(r + 1) * D + col0 + (c >> 1) * HALF + (c & 1) * 4);
;                 }
;                 asm volatile("" ::: "memory");
; #pragma unroll
;                 for (int bj = 0; bj < 2; ++bj) { f32x4 o2[2];
; #pragma unroll
;                     for (int n = 0; n < 2; ++n) { const f32x4 b = cur[q][2 * bj + n]; const u32x2 qw = pcur[2 * bj + n];
;                         const f32x4 pq = (f32x4){bflo(qw.x), bfhi(qw.x), bflo(qw.y), bfhi(qw.y)}; const f32x4 a = acc[ai][bj][m][n];
; #pragma unroll
;                         for (int j = 0; j < 4; ++j) o2[n][j] = b[j] + pq[j] * sigmoidf_(a[j]); }
;                     *(f32x4*)(h + off + bj * HALF) = o2[0]; *(f32x4*)(h + off + bj * HALF + 4) = o2[1];
;                     if (!LAST) { u32x4 w; w.x = cvt_pk_bf16(o2[0][0], o2[0][1]); w.y = cvt_pk_bf16(o2[0][2], o2[0][3]); w.z = cvt_pk_bf16(o2[1][0], o2[1][1]); w.w = cvt_pk_bf16(o2[1][2], o2[1][3]);
;                         *(u32x4*)(hb + off + bj * HALF) = w; sr += ssq4(o2[0]) + ssq4(o2[1]); } }
;                 s[ai][m] = sr;
;                 asm volatile("" ::: "memory");
; #pragma unroll
;                 for (int c = 0; c < 4; ++c) pcur[c] = pnxt[c];
;             }
	global_load_dwordx4 v[2:5], v[82:83], off
	global_load_dwordx4 v[14:17], v[82:83], off offset:528
	global_load_dwordx4 v[10:13], v[82:83], off offset:512
	global_load_dwordx4 v[74:77], v[18:19], off
	global_load_dwordx4 v[70:73], v[18:19], off offset:256
	v_lshlrev_b64 v[50:51], 11, v[172:173]
	v_mul_f32_e32 v173, 0xbfb8aa3b, v178
	v_exp_f32_e32 v173, v173
	v_lshl_add_u64 v[88:89], v[50:51], 0, v[152:153]
	v_lshlrev_b64 v[50:51], 12, v[84:85]
	v_lshlrev_b64 v[18:19], 13, v[242:243]
	v_add_f32_e32 v173, 1.0, v173
	v_rcp_f32_e32 v178, v173
	v_mul_f32_e32 v173, 0xbfb8aa3b, v179
	v_exp_f32_e32 v173, v173
	v_lshlrev_b64 v[34:35], 13, v[228:229]
	v_lshl_add_u64 v[50:51], s[56:57], 0, v[50:51]
	v_lshl_add_u64 v[230:231], v[118:119], 0, v[18:19]
	v_add_f32_e32 v173, 1.0, v173
	v_rcp_f32_e32 v179, v173
	v_lshl_add_u64 v[120:121], v[118:119], 0, v[34:35]
	v_lshl_add_u64 v[50:51], v[50:51], 0, v[198:199]
	global_load_dwordx4 v[22:25], v[230:231], off offset:16
	global_load_dwordx4 v[18:21], v[230:231], off
	global_load_dwordx4 v[30:33], v[230:231], off offset:528
	global_load_dwordx4 v[26:29], v[230:231], off offset:512
	global_load_dwordx4 v[38:41], v[120:121], off offset:16
	global_load_dwordx4 v[34:37], v[120:121], off
	global_load_dwordx4 v[46:49], v[120:121], off offset:528
	global_load_dwordx4 v[42:45], v[120:121], off offset:512
	global_load_dwordx4 v[58:61], v[50:51], off
	s_nop 0
	global_load_dwordx4 v[50:53], v[50:51], off offset:256
	v_lshl_add_u64 v[88:89], v[88:89], 1, s[54:55]
	v_mul_f32_e32 v173, 0xbfb8aa3b, v226
	v_exp_f32_e32 v173, v173
	v_mul_f32_e32 v176, 0xbfb8aa3b, v176
	v_mul_f32_e32 v177, 0xbfb8aa3b, v177
	v_exp_f32_e32 v176, v176
	v_add_f32_e32 v173, 1.0, v173
	v_rcp_f32_e32 v226, v173
	v_mul_f32_e32 v173, 0xbfb8aa3b, v227
	v_exp_f32_e32 v173, v173
	v_exp_f32_e32 v177, v177
	v_add_f32_e32 v176, 1.0, v176
	v_rcp_f32_e32 v176, v176
	v_add_f32_e32 v173, 1.0, v173
	v_rcp_f32_e32 v227, v173
	v_add_f32_e32 v177, 1.0, v177
	v_rcp_f32_e32 v177, v177
	v_cmp_eq_u32_e32 vcc, 0, v185
	s_waitcnt vmcnt(11)
	v_lshlrev_b32_e32 v186, 16, v74
	v_and_b32_e32 v187, 0xffff0000, v74
	v_mul_f32_e32 v74, 0xbfb8aa3b, v252
	v_exp_f32_e32 v74, v74
	v_pk_fma_f32 v[78:79], v[178:179], v[186:187], v[78:79]
	v_add_f32_e32 v74, 1.0, v74
	v_rcp_f32_e32 v178, v74
	v_mul_f32_e32 v74, 0xbfb8aa3b, v253
	v_exp_f32_e32 v74, v74
	s_nop 0
	v_add_f32_e32 v74, 1.0, v74
	v_rcp_f32_e32 v179, v74
	v_lshlrev_b32_e32 v74, 16, v75
	v_and_b32_e32 v75, 0xffff0000, v75
	v_pk_fma_f32 v[80:81], v[178:179], v[74:75], v[80:81]
	v_mul_f32_e32 v74, 0xbfb8aa3b, v250
	v_mul_f32_e32 v75, 0xbfb8aa3b, v251
	v_exp_f32_e32 v74, v74
	v_exp_f32_e32 v75, v75
	v_lshlrev_b32_e32 v178, 16, v76
	v_and_b32_e32 v179, 0xffff0000, v76
	v_add_f32_e32 v74, 1.0, v74
	v_add_f32_e32 v75, 1.0, v75
	v_rcp_f32_e32 v74, v74
	v_rcp_f32_e32 v75, v75
	v_lshlrev_b32_e32 v76, 16, v77
	v_and_b32_e32 v77, 0xffff0000, v77
	v_pk_fma_f32 v[66:67], v[74:75], v[178:179], v[66:67]
	v_mul_f32_e32 v74, 0xbfb8aa3b, v248
	v_mul_f32_e32 v75, 0xbfb8aa3b, v249
	v_exp_f32_e32 v74, v74
	v_exp_f32_e32 v75, v75
	v_mul_f32_e32 v179, 0xbfb8aa3b, v220
	v_exp_f32_e32 v179, v179
	v_add_f32_e32 v74, 1.0, v74
	v_add_f32_e32 v75, 1.0, v75
	v_rcp_f32_e32 v74, v74
	v_rcp_f32_e32 v75, v75
	v_add_f32_e32 v179, 1.0, v179
	v_rcp_f32_e32 v220, v179
	v_mul_f32_e32 v179, 0xbfb8aa3b, v221
	v_pk_fma_f32 v[68:69], v[74:75], v[76:77], v[68:69]
	v_cvt_pk_bf16_f32 v74, v78, v79
	v_cvt_pk_bf16_f32 v75, v80, v81
	v_cvt_pk_bf16_f32 v76, v66, v67
	v_cvt_pk_bf16_f32 v77, v68, v69
	global_store_dwordx4 v[86:87], v[78:81], off sc1
	global_store_dwordx4 v[86:87], v[66:69], off offset:16 sc1
	global_store_dwordx4 v[88:89], v[74:77], off sc1
	v_exp_f32_e32 v179, v179
	s_nop 0
	v_pk_mul_f32 v[74:75], v[78:79], v[78:79]
	v_pk_mul_f32 v[78:79], v[66:67], v[66:67]
	v_mul_f32_e32 v66, 0xbfb8aa3b, v246
	v_mul_f32_e32 v67, 0xbfb8aa3b, v247
	v_exp_f32_e32 v66, v66
	v_exp_f32_e32 v67, v67
	v_pk_mul_f32 v[76:77], v[80:81], v[80:81]
	v_pk_mul_f32 v[80:81], v[68:69], v[68:69]
	v_add_f32_e32 v66, 1.0, v66
	v_add_f32_e32 v67, 1.0, v67
	v_rcp_f32_e32 v66, v66
	v_rcp_f32_e32 v67, v67
	s_waitcnt vmcnt(13)
	v_lshlrev_b32_e32 v68, 16, v70
	v_and_b32_e32 v69, 0xffff0000, v70
	v_add_f32_e32 v179, 1.0, v179
	v_pk_fma_f32 v[62:63], v[66:67], v[68:69], v[62:63]
	v_mul_f32_e32 v66, 0xbfb8aa3b, v244
	v_mul_f32_e32 v67, 0xbfb8aa3b, v245
	v_exp_f32_e32 v66, v66
	v_exp_f32_e32 v67, v67
	v_lshlrev_b32_e32 v68, 16, v71
	v_and_b32_e32 v69, 0xffff0000, v71
	v_add_f32_e32 v66, 1.0, v66
	v_add_f32_e32 v67, 1.0, v67
	v_rcp_f32_e32 v66, v66
	v_rcp_f32_e32 v67, v67
	v_rcp_f32_e32 v221, v179
	v_mul_f32_e32 v179, 0xbfb8aa3b, v204
	v_exp_f32_e32 v179, v179
	v_pk_fma_f32 v[64:65], v[66:67], v[68:69], v[64:65]
	v_mul_f32_e32 v66, 0xbfb8aa3b, v240
	v_mul_f32_e32 v67, 0xbfb8aa3b, v241
	v_exp_f32_e32 v66, v66
	v_exp_f32_e32 v67, v67
	v_lshlrev_b32_e32 v68, 16, v72
	v_and_b32_e32 v69, 0xffff0000, v72
	v_add_f32_e32 v66, 1.0, v66
	v_add_f32_e32 v67, 1.0, v67
	v_rcp_f32_e32 v66, v66
	v_rcp_f32_e32 v67, v67
	v_add_f32_e32 v179, 1.0, v179
	v_rcp_f32_e32 v204, v179
	v_mul_f32_e32 v179, 0xbfb8aa3b, v205
	v_pk_fma_f32 v[54:55], v[66:67], v[68:69], v[54:55]
	v_mul_f32_e32 v66, 0xbfb8aa3b, v238
	v_mul_f32_e32 v67, 0xbfb8aa3b, v239
	v_exp_f32_e32 v66, v66
	v_exp_f32_e32 v67, v67
	v_lshlrev_b32_e32 v68, 16, v73
	v_and_b32_e32 v69, 0xffff0000, v73
	v_add_f32_e32 v66, 1.0, v66
	v_add_f32_e32 v67, 1.0, v67
	v_rcp_f32_e32 v66, v66
	v_rcp_f32_e32 v67, v67
	v_exp_f32_e32 v179, v179
	v_pk_fma_f32 v[56:57], v[66:67], v[68:69], v[56:57]
	global_store_dwordx4 v[86:87], v[62:65], off offset:512 sc1
	global_store_dwordx4 v[86:87], v[54:57], off offset:528 sc1
	v_cvt_pk_bf16_f32 v68, v54, v55
	v_cvt_pk_bf16_f32 v69, v56, v57
	v_pk_mul_f32 v[54:55], v[54:55], v[54:55]
	v_pk_mul_f32 v[56:57], v[56:57], v[56:57]
	v_cvt_pk_bf16_f32 v66, v62, v63
	v_cvt_pk_bf16_f32 v67, v64, v65
	v_pk_mul_f32 v[62:63], v[62:63], v[62:63]
	v_pk_mul_f32 v[64:65], v[64:65], v[64:65]
	v_add_f32_e32 v56, v56, v57
	v_add_f32_e32 v54, v54, v55
	v_add_f32_e32 v54, v54, v56
	v_add_f32_e32 v55, v64, v65
	v_add_f32_e32 v56, v62, v63
	v_add_f32_e32 v55, v56, v55
	v_add_f32_e32 v54, v55, v54
	v_add_f32_e32 v55, v80, v81
	v_add_f32_e32 v56, v78, v79
	v_add_f32_e32 v55, v56, v55
	v_add_f32_e32 v56, v76, v77
	v_add_f32_e32 v57, v74, v75
	v_add_f32_e32 v56, v57, v56
	v_add_f32_e32 v55, v56, v55
	v_add_f32_e32 v178, v55, v54
	v_lshlrev_b64 v[54:55], 11, v[84:85]
	global_store_dwordx4 v[88:89], v[66:69], off offset:256 sc1
	s_waitcnt vmcnt(7)
; __device__ __forceinline__ float sigmoidf_(float x) { return __builtin_amdgcn_rcpf(1.0f + __expf(-x)); }
; __device__ __forceinline__ float ssq4(const f32x4 o) { return (o[0] * o[0] + o[1] * o[1]) + (o[2] * o[2] + o[3] * o[3]); }
;     __device__ __forceinline__ void operator()(f32x4 (&acc)[2][2][4][2], const Unit& u, int wr, int wc, int fr, int fq) const {
;     ...
;             for (int q = 0; q < 2; ++q) { const int r = 2 * k + q, ai = r >> 2, m = r & 3; const size_t off = (size_t)EPI_ROW(r) * D + col0; float sr = 0.f;
;                 if (r < 7) {
; #pragma unroll
;                     for (int c = 0; c < 4; ++c) pnxt[c] = *(const u32x2*)(pp + (size_t)EPI_ROW(r + 1) * D + col0 + (c >> 1) * HALF + (c & 1) * 4);
;                 }
;                 asm volatile("" ::: "memory");
; #pragma unroll
;                 for (int bj = 0; bj < 2; ++bj) { f32x4 o2[2];
; #pragma unroll
;                     for (int n = 0; n < 2; ++n) { const f32x4 b = cur[q][2 * bj + n]; const u32x2 qw = pcur[2 * bj + n];
;                         const f32x4 pq = (f32x4){bflo(qw.x), bfhi(qw.x), bflo(qw.y), bfhi(qw.y)}; const f32x4 a = acc[ai][bj][m][n];
; #pragma unroll
;                         for (int j = 0; j < 4; ++j) o2[n][j] = b[j] + pq[j] * sigmoidf_(a[j]); }
;                     *(f32x4*)(h + off + bj * HALF) = o2[0]; *(f32x4*)(h + off + bj * HALF + 4) = o2[1];
;                     if (!LAST) { u32x4 w; w.x = cvt_pk_bf16(o2[0][0], o2[0][1]); w.y = cvt_pk_bf16(o2[0][2], o2[0][3]); w.z = cvt_pk_bf16(o2[1][0], o2[1][1]); w.w = cvt_pk_bf16(o2[1][2], o2[1][3]);
;                         *(u32x4*)(hb + off + bj * HALF) = w; sr += ssq4(o2[0]) + ssq4(o2[1]); } }
;                 s[ai][m] = sr;
;                 asm volatile("" ::: "memory");
; #pragma unroll
;                 for (int c = 0; c < 4; ++c) pcur[c] = pnxt[c];
;             }
	v_lshlrev_b32_e32 v56, 16, v58
	v_and_b32_e32 v57, 0xffff0000, v58
	v_lshl_add_u64 v[66:67], v[54:55], 0, v[152:153]
	v_lshlrev_b64 v[54:55], 12, v[242:243]
	v_lshl_add_u64 v[54:55], s[56:57], 0, v[54:55]
	v_lshl_add_u64 v[54:55], v[54:55], 0, v[198:199]
	global_load_dwordx4 v[86:89], v[54:55], off
	global_load_dwordx4 v[62:65], v[54:55], off offset:256
	v_mul_f32_e32 v54, 0xbfb8aa3b, v236
	v_mul_f32_e32 v55, 0xbfb8aa3b, v237
	v_exp_f32_e32 v54, v54
	v_exp_f32_e32 v55, v55
	v_add_u32_e32 v236, 0x80, v172
	v_add_f32_e32 v54, 1.0, v54
	v_add_f32_e32 v55, 1.0, v55
	v_rcp_f32_e32 v54, v54
	v_rcp_f32_e32 v55, v55
	v_lshlrev_b64 v[74:75], 11, v[242:243]
	v_ashrrev_i32_e32 v237, 31, v236
	v_lshl_add_u64 v[186:187], v[74:75], 0, v[152:153]
	v_pk_fma_f32 v[2:3], v[54:55], v[56:57], v[2:3]
	v_mul_f32_e32 v54, 0xbfb8aa3b, v234
	v_mul_f32_e32 v55, 0xbfb8aa3b, v235
	v_exp_f32_e32 v54, v54
	v_exp_f32_e32 v55, v55
	v_lshlrev_b32_e32 v56, 16, v59
	v_and_b32_e32 v57, 0xffff0000, v59
	v_add_f32_e32 v54, 1.0, v54
	v_add_f32_e32 v55, 1.0, v55
	v_rcp_f32_e32 v54, v54
	v_rcp_f32_e32 v55, v55
	v_lshl_add_u64 v[58:59], v[66:67], 1, s[54:55]
	v_lshlrev_b64 v[74:75], 12, v[228:229]
	v_lshl_add_u64 v[74:75], s[56:57], 0, v[74:75]
	v_pk_fma_f32 v[4:5], v[54:55], v[56:57], v[4:5]
	v_mul_f32_e32 v54, 0xbfb8aa3b, v232
	v_mul_f32_e32 v55, 0xbfb8aa3b, v233
	v_exp_f32_e32 v54, v54
	v_exp_f32_e32 v55, v55
	v_lshlrev_b32_e32 v56, 16, v60
	v_and_b32_e32 v57, 0xffff0000, v60
	v_add_f32_e32 v54, 1.0, v54
	v_add_f32_e32 v55, 1.0, v55
	v_rcp_f32_e32 v54, v54
	v_rcp_f32_e32 v55, v55
	v_add_u32_e32 v232, 0x90, v172
	v_ashrrev_i32_e32 v233, 31, v232
	v_lshl_add_u64 v[74:75], v[74:75], 0, v[198:199]
	v_pk_fma_f32 v[6:7], v[54:55], v[56:57], v[6:7]
	v_mul_f32_e32 v54, 0xbfb8aa3b, v222
	v_mul_f32_e32 v55, 0xbfb8aa3b, v223
	v_exp_f32_e32 v54, v54
	v_exp_f32_e32 v55, v55
	v_lshlrev_b32_e32 v56, 16, v61
	v_and_b32_e32 v57, 0xffff0000, v61
	v_add_f32_e32 v54, 1.0, v54
	v_add_f32_e32 v55, 1.0, v55
	v_rcp_f32_e32 v54, v54
	v_rcp_f32_e32 v55, v55
	v_add_f32_e32 v179, 1.0, v179
	v_rcp_f32_e32 v205, v179
	v_pk_fma_f32 v[8:9], v[54:55], v[56:57], v[8:9]
	v_cvt_pk_bf16_f32 v54, v2, v3
	v_cvt_pk_bf16_f32 v55, v4, v5
	v_cvt_pk_bf16_f32 v56, v6, v7
	v_cvt_pk_bf16_f32 v57, v8, v9
	global_store_dwordx4 v[82:83], v[2:5], off sc1
	global_store_dwordx4 v[82:83], v[6:9], off offset:16 sc1
	global_store_dwordx4 v[58:59], v[54:57], off sc1
	s_waitcnt vmcnt(4)
	v_lshlrev_b32_e32 v238, 16, v86
	v_mul_f32_e32 v54, 0xbfb8aa3b, v94
	v_mul_f32_e32 v55, 0xbfb8aa3b, v95
	v_exp_f32_e32 v54, v54
	v_exp_f32_e32 v55, v55
	v_lshlrev_b32_e32 v56, 16, v50
	v_and_b32_e32 v57, 0xffff0000, v50
	v_mul_f32_e32 v50, 0xbfb8aa3b, v96
	v_add_f32_e32 v54, 1.0, v54
	v_add_f32_e32 v55, 1.0, v55
	v_exp_f32_e32 v50, v50
	v_rcp_f32_e32 v54, v54
	v_rcp_f32_e32 v55, v55
	v_and_b32_e32 v239, 0xffff0000, v86
	v_add_f32_e32 v50, 1.0, v50
	v_mul_f32_e32 v86, 0xbfb8aa3b, v224
	v_pk_fma_f32 v[10:11], v[54:55], v[56:57], v[10:11]
	v_rcp_f32_e32 v54, v50
	v_mul_f32_e32 v50, 0xbfb8aa3b, v97
	v_exp_f32_e32 v50, v50
	v_exp_f32_e32 v86, v86
	v_pk_fma_f32 v[18:19], v[226:227], v[238:239], v[18:19]
	v_add_f32_e32 v50, 1.0, v50
	v_rcp_f32_e32 v55, v50
	v_lshlrev_b32_e32 v50, 16, v51
	v_and_b32_e32 v51, 0xffff0000, v51
	v_add_f32_e32 v86, 1.0, v86
	v_pk_fma_f32 v[12:13], v[54:55], v[50:51], v[12:13]
	v_mul_f32_e32 v50, 0xbfb8aa3b, v90
	v_mul_f32_e32 v51, 0xbfb8aa3b, v91
	v_exp_f32_e32 v50, v50
	v_exp_f32_e32 v51, v51
	v_lshlrev_b32_e32 v54, 16, v52
	v_and_b32_e32 v55, 0xffff0000, v52
	v_add_f32_e32 v50, 1.0, v50
	v_add_f32_e32 v51, 1.0, v51
	v_rcp_f32_e32 v50, v50
	v_rcp_f32_e32 v51, v51
	v_rcp_f32_e32 v224, v86
	v_mul_f32_e32 v86, 0xbfb8aa3b, v225
	v_exp_f32_e32 v86, v86
	v_pk_fma_f32 v[14:15], v[50:51], v[54:55], v[14:15]
	v_mul_f32_e32 v50, 0xbfb8aa3b, v92
	v_mul_f32_e32 v51, 0xbfb8aa3b, v93
	v_exp_f32_e32 v50, v50
	v_exp_f32_e32 v51, v51
	v_lshlrev_b32_e32 v52, 16, v53
	v_and_b32_e32 v53, 0xffff0000, v53
	v_add_f32_e32 v50, 1.0, v50
	v_add_f32_e32 v51, 1.0, v51
	v_rcp_f32_e32 v50, v50
	v_rcp_f32_e32 v51, v51
	v_add_f32_e32 v86, 1.0, v86
	v_rcp_f32_e32 v225, v86
	v_lshlrev_b32_e32 v86, 16, v87
	v_pk_fma_f32 v[16:17], v[50:51], v[52:53], v[16:17]
	v_cvt_pk_bf16_f32 v50, v10, v11
	v_cvt_pk_bf16_f32 v51, v12, v13
	v_cvt_pk_bf16_f32 v52, v14, v15
	v_cvt_pk_bf16_f32 v53, v16, v17
	global_store_dwordx4 v[82:83], v[10:13], off offset:512 sc1
	global_store_dwordx4 v[82:83], v[14:17], off offset:528 sc1
	global_store_dwordx4 v[58:59], v[50:53], off offset:256 sc1
	v_lshlrev_b64 v[58:59], 13, v[232:233]
	v_lshl_add_u64 v[222:223], v[118:119], 0, v[58:59]
	v_lshlrev_b64 v[50:51], 13, v[236:237]
	v_lshl_add_u64 v[234:235], v[118:119], 0, v[50:51]
	global_load_dwordx4 v[54:57], v[234:235], off offset:16
	global_load_dwordx4 v[50:53], v[234:235], off
	global_load_dwordx4 v[78:81], v[234:235], off offset:528
	global_load_dwordx4 v[66:69], v[234:235], off offset:512
	global_load_dwordx4 v[82:85], v[222:223], off offset:16
	global_load_dwordx4 v[90:93], v[222:223], off
	global_load_dwordx4 v[58:61], v[222:223], off offset:528
	global_load_dwordx4 v[70:73], v[222:223], off offset:512
	global_load_dwordx4 v[94:97], v[74:75], off
	s_nop 0
	global_load_dwordx4 v[74:77], v[74:75], off offset:256
	v_and_b32_e32 v87, 0xffff0000, v87
	v_pk_fma_f32 v[20:21], v[224:225], v[86:87], v[20:21]
	v_mul_f32_e32 v86, 0xbfb8aa3b, v128
	v_mul_f32_e32 v87, 0xbfb8aa3b, v129
	v_exp_f32_e32 v86, v86
	v_exp_f32_e32 v87, v87
	v_lshlrev_b32_e32 v128, 16, v88
	v_and_b32_e32 v129, 0xffff0000, v88
	v_add_f32_e32 v86, 1.0, v86
	v_add_f32_e32 v87, 1.0, v87
	v_rcp_f32_e32 v86, v86
	v_rcp_f32_e32 v87, v87
	v_lshlrev_b32_e32 v88, 16, v89
	v_and_b32_e32 v89, 0xffff0000, v89
	v_pk_fma_f32 v[22:23], v[86:87], v[128:129], v[22:23]
	v_mul_f32_e32 v86, 0xbfb8aa3b, v126
	v_mul_f32_e32 v87, 0xbfb8aa3b, v127
	v_exp_f32_e32 v86, v86
	v_exp_f32_e32 v87, v87
	v_lshl_add_u64 v[126:127], v[186:187], 1, s[54:55]
	v_add_u32_e32 v224, 0xb0, v172
	v_add_f32_e32 v86, 1.0, v86
	v_add_f32_e32 v87, 1.0, v87
	v_rcp_f32_e32 v86, v86
	v_rcp_f32_e32 v87, v87
	v_ashrrev_i32_e32 v225, 31, v224
	v_pk_fma_f32 v[24:25], v[86:87], v[88:89], v[24:25]
	v_cvt_pk_bf16_f32 v86, v18, v19
	v_cvt_pk_bf16_f32 v87, v20, v21
	v_cvt_pk_bf16_f32 v88, v22, v23
	v_cvt_pk_bf16_f32 v89, v24, v25
	global_store_dwordx4 v[230:231], v[18:21], off sc1
	global_store_dwordx4 v[230:231], v[22:25], off offset:16 sc1
	global_store_dwordx4 v[126:127], v[86:89], off sc1
	s_nop 1
	v_mul_f32_e32 v86, 0xbfb8aa3b, v124
	v_mul_f32_e32 v87, 0xbfb8aa3b, v125
	v_exp_f32_e32 v86, v86
	v_exp_f32_e32 v87, v87
	s_waitcnt vmcnt(19)
; __device__ __forceinline__ float sigmoidf_(float x) { return __builtin_amdgcn_rcpf(1.0f + __expf(-x)); }
; __device__ __forceinline__ float ssq4(const f32x4 o) { return (o[0] * o[0] + o[1] * o[1]) + (o[2] * o[2] + o[3] * o[3]); }
;     __device__ __forceinline__ void operator()(f32x4 (&acc)[2][2][4][2], const Unit& u, int wr, int wc, int fr, int fq) const {
;     ...
;             for (int q = 0; q < 2; ++q) { const int r = 2 * k + q, ai = r >> 2, m = r & 3; const size_t off = (size_t)EPI_ROW(r) * D + col0; float sr = 0.f;
;                 if (r < 7) {
; #pragma unroll
;                     for (int c = 0; c < 4; ++c) pnxt[c] = *(const u32x2*)(pp + (size_t)EPI_ROW(r + 1) * D + col0 + (c >> 1) * HALF + (c & 1) * 4);
;                 }
;                 asm volatile("" ::: "memory");
; #pragma unroll
;                 for (int bj = 0; bj < 2; ++bj) { f32x4 o2[2];
; #pragma unroll
;                     for (int n = 0; n < 2; ++n) { const f32x4 b = cur[q][2 * bj + n]; const u32x2 qw = pcur[2 * bj + n];
;                         const f32x4 pq = (f32x4){bflo(qw.x), bfhi(qw.x), bflo(qw.y), bfhi(qw.y)}; const f32x4 a = acc[ai][bj][m][n];
; #pragma unroll
;                         for (int j = 0; j < 4; ++j) o2[n][j] = b[j] + pq[j] * sigmoidf_(a[j]); }
;                     *(f32x4*)(h + off + bj * HALF) = o2[0]; *(f32x4*)(h + off + bj * HALF + 4) = o2[1];
;                     if (!LAST) { u32x4 w; w.x = cvt_pk_bf16(o2[0][0], o2[0][1]); w.y = cvt_pk_bf16(o2[0][2], o2[0][3]); w.z = cvt_pk_bf16(o2[1][0], o2[1][1]); w.w = cvt_pk_bf16(o2[1][2], o2[1][3]);
;                         *(u32x4*)(hb + off + bj * HALF) = w; sr += ssq4(o2[0]) + ssq4(o2[1]); } }
;                 s[ai][m] = sr;
;                 asm volatile("" ::: "memory");
; #pragma unroll
;                 for (int c = 0; c < 4; ++c) pcur[c] = pnxt[c];
;             }
	v_lshlrev_b32_e32 v88, 16, v62
	v_and_b32_e32 v89, 0xffff0000, v62
	v_mul_f32_e32 v62, 0xbfb8aa3b, v122
	v_add_f32_e32 v86, 1.0, v86
	v_add_f32_e32 v87, 1.0, v87
	v_exp_f32_e32 v62, v62
	v_rcp_f32_e32 v86, v86
	v_rcp_f32_e32 v87, v87
	v_add_f32_e32 v62, 1.0, v62
	v_pk_fma_f32 v[26:27], v[86:87], v[88:89], v[26:27]
	v_rcp_f32_e32 v86, v62
	v_mul_f32_e32 v62, 0xbfb8aa3b, v123
	v_exp_f32_e32 v62, v62
	s_nop 0
	v_add_f32_e32 v62, 1.0, v62
	v_rcp_f32_e32 v87, v62
	v_lshlrev_b32_e32 v62, 16, v63
	v_and_b32_e32 v63, 0xffff0000, v63
	v_pk_fma_f32 v[28:29], v[86:87], v[62:63], v[28:29]
	v_mul_f32_e32 v62, 0xbfb8aa3b, v116
	v_mul_f32_e32 v63, 0xbfb8aa3b, v117
	v_exp_f32_e32 v62, v62
	v_exp_f32_e32 v63, v63
	v_lshlrev_b32_e32 v86, 16, v64
	v_and_b32_e32 v87, 0xffff0000, v64
	v_add_f32_e32 v62, 1.0, v62
	v_add_f32_e32 v63, 1.0, v63
	v_rcp_f32_e32 v62, v62
	v_rcp_f32_e32 v63, v63
	v_lshlrev_b32_e32 v64, 16, v65
	v_and_b32_e32 v65, 0xffff0000, v65
	v_pk_fma_f32 v[30:31], v[62:63], v[86:87], v[30:31]
	v_mul_f32_e32 v62, 0xbfb8aa3b, v114
	v_mul_f32_e32 v63, 0xbfb8aa3b, v115
	v_exp_f32_e32 v62, v62
	v_exp_f32_e32 v63, v63
	v_add_f32_e32 v62, 1.0, v62
	v_add_f32_e32 v63, 1.0, v63
	v_rcp_f32_e32 v62, v62
	v_rcp_f32_e32 v63, v63
	s_nop 0
	v_pk_fma_f32 v[32:33], v[62:63], v[64:65], v[32:33]
	v_cvt_pk_bf16_f32 v62, v26, v27
	v_cvt_pk_bf16_f32 v63, v28, v29
	v_cvt_pk_bf16_f32 v64, v30, v31
	v_cvt_pk_bf16_f32 v65, v32, v33
	global_store_dwordx4 v[230:231], v[26:29], off offset:512 sc1
	global_store_dwordx4 v[230:231], v[30:33], off offset:528 sc1
	global_store_dwordx4 v[126:127], v[62:65], off offset:256 sc1
	s_nop 1
	v_lshlrev_b64 v[62:63], 11, v[228:229]
	v_lshl_add_u64 v[86:87], v[62:63], 0, v[152:153]
	v_lshlrev_b64 v[62:63], 12, v[236:237]
	v_lshl_add_u64 v[62:63], s[56:57], 0, v[62:63]
	v_lshl_add_u64 v[62:63], v[62:63], 0, v[198:199]
	global_load_dwordx4 v[122:125], v[62:63], off
	global_load_dwordx4 v[114:117], v[62:63], off offset:256
	v_mul_f32_e32 v62, 0xbfb8aa3b, v112
	v_mul_f32_e32 v63, 0xbfb8aa3b, v113
	v_exp_f32_e32 v62, v62
	v_exp_f32_e32 v63, v63
	s_waitcnt vmcnt(9)
	v_lshlrev_b32_e32 v64, 16, v94
	v_and_b32_e32 v65, 0xffff0000, v94
	v_add_f32_e32 v62, 1.0, v62
	v_add_f32_e32 v63, 1.0, v63
	v_rcp_f32_e32 v62, v62
	v_rcp_f32_e32 v63, v63
	v_lshl_add_u64 v[86:87], v[86:87], 1, s[54:55]
	v_add_u32_e32 v228, 0xa0, v172
	v_pk_fma_f32 v[34:35], v[62:63], v[64:65], v[34:35]
	v_mul_f32_e32 v62, 0xbfb8aa3b, v110
	v_mul_f32_e32 v63, 0xbfb8aa3b, v111
	v_exp_f32_e32 v62, v62
	v_exp_f32_e32 v63, v63
	v_lshlrev_b32_e32 v64, 16, v95
	v_and_b32_e32 v65, 0xffff0000, v95
	v_add_f32_e32 v62, 1.0, v62
	v_add_f32_e32 v63, 1.0, v63
	v_rcp_f32_e32 v62, v62
	v_rcp_f32_e32 v63, v63
	v_ashrrev_i32_e32 v229, 31, v228
	v_pk_fma_f32 v[36:37], v[62:63], v[64:65], v[36:37]
	v_mul_f32_e32 v62, 0xbfb8aa3b, v108
	v_mul_f32_e32 v63, 0xbfb8aa3b, v109
	v_exp_f32_e32 v62, v62
	v_exp_f32_e32 v63, v63
	v_lshlrev_b32_e32 v64, 16, v96
	v_and_b32_e32 v65, 0xffff0000, v96
	v_add_f32_e32 v62, 1.0, v62
	v_add_f32_e32 v63, 1.0, v63
	v_rcp_f32_e32 v62, v62
	v_rcp_f32_e32 v63, v63
	s_waitcnt vmcnt(1)
	v_lshlrev_b32_e32 v230, 16, v122
	v_pk_fma_f32 v[38:39], v[62:63], v[64:65], v[38:39]
	v_mul_f32_e32 v62, 0xbfb8aa3b, v106
	v_mul_f32_e32 v63, 0xbfb8aa3b, v107
	v_exp_f32_e32 v62, v62
	v_exp_f32_e32 v63, v63
	v_lshlrev_b32_e32 v64, 16, v97
	v_and_b32_e32 v65, 0xffff0000, v97
	v_add_f32_e32 v62, 1.0, v62
	v_add_f32_e32 v63, 1.0, v63
	v_rcp_f32_e32 v62, v62
	v_rcp_f32_e32 v63, v63
	v_and_b32_e32 v231, 0xffff0000, v122
	v_mul_f32_e32 v122, 0xbfb8aa3b, v218
	v_exp_f32_e32 v122, v122
	v_pk_fma_f32 v[40:41], v[62:63], v[64:65], v[40:41]
	v_cvt_pk_bf16_f32 v62, v34, v35
	v_cvt_pk_bf16_f32 v63, v36, v37
	v_cvt_pk_bf16_f32 v64, v38, v39
	v_cvt_pk_bf16_f32 v65, v40, v41
	global_store_dwordx4 v[120:121], v[34:37], off sc1
	global_store_dwordx4 v[120:121], v[38:41], off offset:16 sc1
	global_store_dwordx4 v[86:87], v[62:65], off sc1
	v_add_f32_e32 v122, 1.0, v122
	v_rcp_f32_e32 v218, v122
	v_mul_f32_e32 v62, 0xbfb8aa3b, v104
	v_mul_f32_e32 v63, 0xbfb8aa3b, v105
	v_exp_f32_e32 v62, v62
	v_exp_f32_e32 v63, v63
	v_lshlrev_b32_e32 v64, 16, v74
	v_and_b32_e32 v65, 0xffff0000, v74
	v_add_f32_e32 v62, 1.0, v62
	v_add_f32_e32 v63, 1.0, v63
	v_rcp_f32_e32 v62, v62
	v_rcp_f32_e32 v63, v63
	v_mul_f32_e32 v122, 0xbfb8aa3b, v219
	v_exp_f32_e32 v122, v122
	v_pk_fma_f32 v[50:51], v[220:221], v[230:231], v[50:51]
	v_pk_fma_f32 v[42:43], v[62:63], v[64:65], v[42:43]
	v_mul_f32_e32 v62, 0xbfb8aa3b, v102
	v_mul_f32_e32 v63, 0xbfb8aa3b, v103
	v_exp_f32_e32 v62, v62
	v_exp_f32_e32 v63, v63
	v_lshlrev_b32_e32 v64, 16, v75
	v_and_b32_e32 v65, 0xffff0000, v75
	v_add_f32_e32 v62, 1.0, v62
	v_add_f32_e32 v63, 1.0, v63
	v_rcp_f32_e32 v62, v62
	v_rcp_f32_e32 v63, v63
	v_add_f32_e32 v122, 1.0, v122
	v_rcp_f32_e32 v219, v122
	v_lshlrev_b32_e32 v122, 16, v123
	v_pk_fma_f32 v[44:45], v[62:63], v[64:65], v[44:45]
	v_mul_f32_e32 v62, 0xbfb8aa3b, v100
	v_mul_f32_e32 v63, 0xbfb8aa3b, v101
	v_exp_f32_e32 v62, v62
	v_exp_f32_e32 v63, v63
	v_lshlrev_b32_e32 v64, 16, v76
	v_and_b32_e32 v65, 0xffff0000, v76
	v_add_f32_e32 v62, 1.0, v62
	v_add_f32_e32 v63, 1.0, v63
	v_rcp_f32_e32 v62, v62
	v_rcp_f32_e32 v63, v63
	v_and_b32_e32 v123, 0xffff0000, v123
	v_pk_fma_f32 v[52:53], v[218:219], v[122:123], v[52:53]
	v_mul_f32_e32 v122, 0xbfb8aa3b, v216
	v_pk_fma_f32 v[46:47], v[62:63], v[64:65], v[46:47]
	v_mul_f32_e32 v62, 0xbfb8aa3b, v98
	v_mul_f32_e32 v63, 0xbfb8aa3b, v99
	v_exp_f32_e32 v62, v62
	v_exp_f32_e32 v63, v63
	v_lshlrev_b32_e32 v64, 16, v77
	v_and_b32_e32 v65, 0xffff0000, v77
	v_add_f32_e32 v62, 1.0, v62
	v_add_f32_e32 v63, 1.0, v63
; __device__ __forceinline__ float sigmoidf_(float x) { return __builtin_amdgcn_rcpf(1.0f + __expf(-x)); }
; __device__ __forceinline__ float ssq4(const f32x4 o) { return (o[0] * o[0] + o[1] * o[1]) + (o[2] * o[2] + o[3] * o[3]); }
;     __device__ __forceinline__ void operator()(f32x4 (&acc)[2][2][4][2], const Unit& u, int wr, int wc, int fr, int fq) const {
;     ...
;             for (int q = 0; q < 2; ++q) { const int r = 2 * k + q, ai = r >> 2, m = r & 3; const size_t off = (size_t)EPI_ROW(r) * D + col0; float sr = 0.f;
;                 if (r < 7) {
; #pragma unroll
;                     for (int c = 0; c < 4; ++c) pnxt[c] = *(const u32x2*)(pp + (size_t)EPI_ROW(r + 1) * D + col0 + (c >> 1) * HALF + (c & 1) * 4);
;                 }
;                 asm volatile("" ::: "memory");
; #pragma unroll
;                 for (int bj = 0; bj < 2; ++bj) { f32x4 o2[2];
; #pragma unroll
;                     for (int n = 0; n < 2; ++n) { const f32x4 b = cur[q][2 * bj + n]; const u32x2 qw = pcur[2 * bj + n];
;                         const f32x4 pq = (f32x4){bflo(qw.x), bfhi(qw.x), bflo(qw.y), bfhi(qw.y)}; const f32x4 a = acc[ai][bj][m][n];
; #pragma unroll
;                         for (int j = 0; j < 4; ++j) o2[n][j] = b[j] + pq[j] * sigmoidf_(a[j]); }
;                     *(f32x4*)(h + off + bj * HALF) = o2[0]; *(f32x4*)(h + off + bj * HALF + 4) = o2[1];
;                     if (!LAST) { u32x4 w; w.x = cvt_pk_bf16(o2[0][0], o2[0][1]); w.y = cvt_pk_bf16(o2[0][2], o2[0][3]); w.z = cvt_pk_bf16(o2[1][0], o2[1][1]); w.w = cvt_pk_bf16(o2[1][2], o2[1][3]);
;                         *(u32x4*)(hb + off + bj * HALF) = w; sr += ssq4(o2[0]) + ssq4(o2[1]); } }
;                 s[ai][m] = sr;
;                 asm volatile("" ::: "memory");
; #pragma unroll
;                 for (int c = 0; c < 4; ++c) pcur[c] = pnxt[c];
;             }
	v_rcp_f32_e32 v62, v62
	v_rcp_f32_e32 v63, v63
	v_mul_f32_e32 v123, 0xbfb8aa3b, v217
	v_exp_f32_e32 v122, v122
	v_exp_f32_e32 v123, v123
	v_pk_fma_f32 v[48:49], v[62:63], v[64:65], v[48:49]
	v_cvt_pk_bf16_f32 v62, v42, v43
	v_cvt_pk_bf16_f32 v63, v44, v45
	v_cvt_pk_bf16_f32 v64, v46, v47
	v_cvt_pk_bf16_f32 v65, v48, v49
	global_store_dwordx4 v[120:121], v[42:45], off offset:512 sc1
	global_store_dwordx4 v[120:121], v[46:49], off offset:528 sc1
	global_store_dwordx4 v[86:87], v[62:65], off offset:256 sc1
	v_add_f32_e32 v122, 1.0, v122
	v_add_f32_e32 v123, 1.0, v123
	v_lshlrev_b64 v[62:63], 13, v[228:229]
	v_lshl_add_u64 v[226:227], v[118:119], 0, v[62:63]
	v_lshlrev_b64 v[62:63], 13, v[224:225]
	v_lshl_add_u64 v[172:173], v[118:119], 0, v[62:63]
	v_lshlrev_b64 v[118:119], 11, v[236:237]
	v_lshl_add_u64 v[186:187], v[118:119], 0, v[152:153]
	v_lshlrev_b64 v[118:119], 12, v[232:233]
	v_lshl_add_u64 v[118:119], s[56:57], 0, v[118:119]
	v_lshl_add_u64 v[118:119], v[118:119], 0, v[198:199]
	global_load_dwordx4 v[110:113], v[226:227], off offset:16
	global_load_dwordx4 v[106:109], v[226:227], off
	global_load_dwordx4 v[98:101], v[226:227], off offset:528
	global_load_dwordx4 v[102:105], v[226:227], off offset:512
	global_load_dwordx4 v[86:89], v[172:173], off offset:16
	global_load_dwordx4 v[94:97], v[172:173], off
	global_load_dwordx4 v[62:65], v[172:173], off offset:528
	global_load_dwordx4 v[74:77], v[172:173], off offset:512
	global_load_dwordx4 v[126:129], v[118:119], off
	s_nop 0
	global_load_dwordx4 v[118:121], v[118:119], off offset:256
	v_rcp_f32_e32 v122, v122
	v_rcp_f32_e32 v123, v123
	v_lshlrev_b32_e32 v216, 16, v124
	v_and_b32_e32 v217, 0xffff0000, v124
	v_lshlrev_b32_e32 v124, 16, v125
	v_pk_fma_f32 v[54:55], v[122:123], v[216:217], v[54:55]
	v_mul_f32_e32 v122, 0xbfb8aa3b, v214
	v_mul_f32_e32 v123, 0xbfb8aa3b, v215
	v_exp_f32_e32 v122, v122
	v_exp_f32_e32 v123, v123
	v_and_b32_e32 v125, 0xffff0000, v125
	v_lshl_add_u64 v[186:187], v[186:187], 1, s[54:55]
	v_add_f32_e32 v122, 1.0, v122
	v_add_f32_e32 v123, 1.0, v123
	v_rcp_f32_e32 v122, v122
	v_rcp_f32_e32 v123, v123
	s_nop 0
	v_pk_fma_f32 v[56:57], v[122:123], v[124:125], v[56:57]
	v_cvt_pk_bf16_f32 v122, v50, v51
	v_cvt_pk_bf16_f32 v123, v52, v53
	v_cvt_pk_bf16_f32 v124, v54, v55
	v_cvt_pk_bf16_f32 v125, v56, v57
	global_store_dwordx4 v[234:235], v[50:53], off sc1
	global_store_dwordx4 v[234:235], v[54:57], off offset:16 sc1
	global_store_dwordx4 v[186:187], v[122:125], off sc1
	s_nop 1
	v_mul_f32_e32 v122, 0xbfb8aa3b, v212
	v_mul_f32_e32 v123, 0xbfb8aa3b, v213
	v_exp_f32_e32 v122, v122
	v_exp_f32_e32 v123, v123
	s_waitcnt vmcnt(19)
	v_lshlrev_b32_e32 v124, 16, v114
	v_and_b32_e32 v125, 0xffff0000, v114
	v_mul_f32_e32 v114, 0xbfb8aa3b, v210
	v_add_f32_e32 v122, 1.0, v122
	v_add_f32_e32 v123, 1.0, v123
	v_exp_f32_e32 v114, v114
	v_rcp_f32_e32 v122, v122
	v_rcp_f32_e32 v123, v123
	v_add_f32_e32 v114, 1.0, v114
	v_pk_fma_f32 v[66:67], v[122:123], v[124:125], v[66:67]
	v_rcp_f32_e32 v122, v114
	v_mul_f32_e32 v114, 0xbfb8aa3b, v211
	v_exp_f32_e32 v114, v114
	s_nop 0
	v_add_f32_e32 v114, 1.0, v114
	v_rcp_f32_e32 v123, v114
	v_lshlrev_b32_e32 v114, 16, v115
	v_and_b32_e32 v115, 0xffff0000, v115
	v_pk_fma_f32 v[68:69], v[122:123], v[114:115], v[68:69]
	v_mul_f32_e32 v114, 0xbfb8aa3b, v208
	v_mul_f32_e32 v115, 0xbfb8aa3b, v209
	v_exp_f32_e32 v114, v114
	v_exp_f32_e32 v115, v115
	v_lshlrev_b32_e32 v122, 16, v116
	v_and_b32_e32 v123, 0xffff0000, v116
	v_add_f32_e32 v114, 1.0, v114
	v_add_f32_e32 v115, 1.0, v115
	v_rcp_f32_e32 v114, v114
	v_rcp_f32_e32 v115, v115
	v_lshlrev_b32_e32 v116, 16, v117
	v_and_b32_e32 v117, 0xffff0000, v117
	v_pk_fma_f32 v[78:79], v[114:115], v[122:123], v[78:79]
	v_mul_f32_e32 v114, 0xbfb8aa3b, v206
	v_mul_f32_e32 v115, 0xbfb8aa3b, v207
	v_exp_f32_e32 v114, v114
	v_exp_f32_e32 v115, v115
	v_add_f32_e32 v114, 1.0, v114
	v_add_f32_e32 v115, 1.0, v115
	v_rcp_f32_e32 v114, v114
	v_rcp_f32_e32 v115, v115
	s_waitcnt vmcnt(4)
	v_lshlrev_b32_e32 v206, 16, v126
	v_and_b32_e32 v207, 0xffff0000, v126
	v_mul_f32_e32 v126, 0xbfb8aa3b, v202
	v_pk_fma_f32 v[80:81], v[114:115], v[116:117], v[80:81]
	v_cvt_pk_bf16_f32 v114, v66, v67
	v_cvt_pk_bf16_f32 v115, v68, v69
	v_cvt_pk_bf16_f32 v116, v78, v79
	v_cvt_pk_bf16_f32 v117, v80, v81
	global_store_dwordx4 v[234:235], v[66:69], off offset:512 sc1
	global_store_dwordx4 v[234:235], v[78:81], off offset:528 sc1
	global_store_dwordx4 v[186:187], v[114:117], off offset:256 sc1
	v_exp_f32_e32 v126, v126
	v_pk_fma_f32 v[90:91], v[204:205], v[206:207], v[90:91]
	v_lshlrev_b64 v[114:115], 11, v[232:233]
	v_lshl_add_u64 v[186:187], v[114:115], 0, v[152:153]
	v_lshlrev_b64 v[114:115], 12, v[228:229]
	v_lshl_add_u64 v[114:115], s[56:57], 0, v[114:115]
	v_lshl_add_u64 v[114:115], v[114:115], 0, v[198:199]
	global_load_dwordx4 v[122:125], v[114:115], off
	s_nop 0
	global_load_dwordx4 v[114:117], v[114:115], off offset:256
	v_add_f32_e32 v126, 1.0, v126
	v_rcp_f32_e32 v202, v126
	v_mul_f32_e32 v126, 0xbfb8aa3b, v203
	v_exp_f32_e32 v126, v126
	v_lshl_add_u64 v[186:187], v[186:187], 1, s[54:55]
	v_add_f32_e32 v126, 1.0, v126
	v_rcp_f32_e32 v203, v126
	v_lshlrev_b32_e32 v126, 16, v127
	v_and_b32_e32 v127, 0xffff0000, v127
	v_pk_fma_f32 v[92:93], v[202:203], v[126:127], v[92:93]
	v_mul_f32_e32 v126, 0xbfb8aa3b, v200
	v_mul_f32_e32 v127, 0xbfb8aa3b, v201
	v_exp_f32_e32 v126, v126
	v_exp_f32_e32 v127, v127
	v_lshlrev_b32_e32 v200, 16, v128
	v_and_b32_e32 v201, 0xffff0000, v128
	v_add_f32_e32 v126, 1.0, v126
	v_add_f32_e32 v127, 1.0, v127
	v_rcp_f32_e32 v126, v126
	v_rcp_f32_e32 v127, v127
	v_lshlrev_b32_e32 v128, 16, v129
	v_and_b32_e32 v129, 0xffff0000, v129
	v_pk_fma_f32 v[82:83], v[126:127], v[200:201], v[82:83]
	v_mul_f32_e32 v126, 0xbfb8aa3b, v196
	v_mul_f32_e32 v127, 0xbfb8aa3b, v197
	v_exp_f32_e32 v126, v126
	v_exp_f32_e32 v127, v127
	v_add_f32_e32 v126, 1.0, v126
	v_add_f32_e32 v127, 1.0, v127
	v_rcp_f32_e32 v126, v126
	v_rcp_f32_e32 v127, v127
	s_nop 0
	v_pk_fma_f32 v[84:85], v[126:127], v[128:129], v[84:85]
	v_cvt_pk_bf16_f32 v126, v90, v91
	v_cvt_pk_bf16_f32 v127, v92, v93
	v_cvt_pk_bf16_f32 v128, v82, v83
	v_cvt_pk_bf16_f32 v129, v84, v85
	global_store_dwordx4 v[222:223], v[90:93], off sc1
	global_store_dwordx4 v[222:223], v[82:85], off offset:16 sc1
	global_store_dwordx4 v[186:187], v[126:129], off sc1
	s_nop 1
	v_mul_f32_e32 v126, 0xbfb8aa3b, v194
	v_mul_f32_e32 v127, 0xbfb8aa3b, v195
	v_exp_f32_e32 v126, v126
	v_exp_f32_e32 v127, v127
	s_waitcnt vmcnt(11)
; __device__ __forceinline__ float sigmoidf_(float x) { return __builtin_amdgcn_rcpf(1.0f + __expf(-x)); }
; __device__ __forceinline__ float ssq4(const f32x4 o) { return (o[0] * o[0] + o[1] * o[1]) + (o[2] * o[2] + o[3] * o[3]); }
;     __device__ __forceinline__ void operator()(f32x4 (&acc)[2][2][4][2], const Unit& u, int wr, int wc, int fr, int fq) const {
;     ...
;             for (int q = 0; q < 2; ++q) { const int r = 2 * k + q, ai = r >> 2, m = r & 3; const size_t off = (size_t)EPI_ROW(r) * D + col0; float sr = 0.f;
;                 if (r < 7) {
; #pragma unroll
;                     for (int c = 0; c < 4; ++c) pnxt[c] = *(const u32x2*)(pp + (size_t)EPI_ROW(r + 1) * D + col0 + (c >> 1) * HALF + (c & 1) * 4);
;                 }
;                 asm volatile("" ::: "memory");
; #pragma unroll
;                 for (int bj = 0; bj < 2; ++bj) { f32x4 o2[2];
; #pragma unroll
;                     for (int n = 0; n < 2; ++n) { const f32x4 b = cur[q][2 * bj + n]; const u32x2 qw = pcur[2 * bj + n];
;                         const f32x4 pq = (f32x4){bflo(qw.x), bfhi(qw.x), bflo(qw.y), bfhi(qw.y)}; const f32x4 a = acc[ai][bj][m][n];
; #pragma unroll
;                         for (int j = 0; j < 4; ++j) o2[n][j] = b[j] + pq[j] * sigmoidf_(a[j]); }
;                     *(f32x4*)(h + off + bj * HALF) = o2[0]; *(f32x4*)(h + off + bj * HALF + 4) = o2[1];
;                     if (!LAST) { u32x4 w; w.x = cvt_pk_bf16(o2[0][0], o2[0][1]); w.y = cvt_pk_bf16(o2[0][2], o2[0][3]); w.z = cvt_pk_bf16(o2[1][0], o2[1][1]); w.w = cvt_pk_bf16(o2[1][2], o2[1][3]);
;                         *(u32x4*)(hb + off + bj * HALF) = w; sr += ssq4(o2[0]) + ssq4(o2[1]); } }
;                 s[ai][m] = sr;
;                 asm volatile("" ::: "memory");
; #pragma unroll
;                 for (int c = 0; c < 4; ++c) pcur[c] = pnxt[c];
;             }
	v_lshlrev_b32_e32 v128, 16, v118
	v_and_b32_e32 v129, 0xffff0000, v118
	v_mul_f32_e32 v118, 0xbfb8aa3b, v192
	v_add_f32_e32 v126, 1.0, v126
	v_add_f32_e32 v127, 1.0, v127
	v_exp_f32_e32 v118, v118
	v_rcp_f32_e32 v126, v126
	v_rcp_f32_e32 v127, v127
	v_add_f32_e32 v118, 1.0, v118
	v_pk_fma_f32 v[70:71], v[126:127], v[128:129], v[70:71]
	v_rcp_f32_e32 v126, v118
	v_mul_f32_e32 v118, 0xbfb8aa3b, v193
	v_exp_f32_e32 v118, v118
	s_nop 0
	v_add_f32_e32 v118, 1.0, v118
	v_rcp_f32_e32 v127, v118
	v_lshlrev_b32_e32 v118, 16, v119
	v_and_b32_e32 v119, 0xffff0000, v119
	v_pk_fma_f32 v[72:73], v[126:127], v[118:119], v[72:73]
	v_mul_f32_e32 v118, 0xbfb8aa3b, v190
	v_mul_f32_e32 v119, 0xbfb8aa3b, v191
	v_exp_f32_e32 v118, v118
	v_exp_f32_e32 v119, v119
	v_lshlrev_b32_e32 v126, 16, v120
	v_and_b32_e32 v127, 0xffff0000, v120
	v_add_f32_e32 v118, 1.0, v118
	v_add_f32_e32 v119, 1.0, v119
	v_rcp_f32_e32 v118, v118
	v_rcp_f32_e32 v119, v119
	v_lshlrev_b32_e32 v120, 16, v121
	v_and_b32_e32 v121, 0xffff0000, v121
	v_pk_fma_f32 v[58:59], v[118:119], v[126:127], v[58:59]
	v_mul_f32_e32 v118, 0xbfb8aa3b, v188
	v_mul_f32_e32 v119, 0xbfb8aa3b, v189
	v_exp_f32_e32 v118, v118
	v_exp_f32_e32 v119, v119
	s_waitcnt vmcnt(4)
	v_lshlrev_b32_e32 v188, 16, v122
	v_and_b32_e32 v189, 0xffff0000, v122
	v_add_f32_e32 v118, 1.0, v118
	v_add_f32_e32 v119, 1.0, v119
	v_mul_f32_e32 v122, 0xbfb8aa3b, v174
	v_rcp_f32_e32 v118, v118
	v_rcp_f32_e32 v119, v119
	v_exp_f32_e32 v122, v122
	v_pk_fma_f32 v[106:107], v[176:177], v[188:189], v[106:107]
	v_pk_fma_f32 v[60:61], v[118:119], v[120:121], v[60:61]
	v_add_f32_e32 v122, 1.0, v122
	v_cvt_pk_bf16_f32 v118, v70, v71
	v_cvt_pk_bf16_f32 v119, v72, v73
	v_cvt_pk_bf16_f32 v120, v58, v59
	v_cvt_pk_bf16_f32 v121, v60, v61
	v_rcp_f32_e32 v174, v122
	v_mul_f32_e32 v122, 0xbfb8aa3b, v175
	global_store_dwordx4 v[222:223], v[70:73], off offset:512 sc1
	global_store_dwordx4 v[222:223], v[58:61], off offset:528 sc1
	global_store_dwordx4 v[186:187], v[118:121], off offset:256 sc1
	v_exp_f32_e32 v122, v122
	s_nop 0
	v_lshlrev_b64 v[118:119], 11, v[228:229]
	v_lshl_add_u64 v[186:187], v[118:119], 0, v[152:153]
	v_lshlrev_b64 v[118:119], 12, v[224:225]
	v_lshl_add_u64 v[118:119], s[56:57], 0, v[118:119]
	v_lshl_add_u64 v[118:119], v[118:119], 0, v[198:199]
	global_load_dwordx4 v[126:129], v[118:119], off
	s_nop 0
	global_load_dwordx4 v[118:121], v[118:119], off offset:256
	v_add_f32_e32 v122, 1.0, v122
	v_rcp_f32_e32 v175, v122
	v_lshlrev_b32_e32 v122, 16, v123
	v_and_b32_e32 v123, 0xffff0000, v123
	v_pk_fma_f32 v[108:109], v[174:175], v[122:123], v[108:109]
	v_mul_f32_e32 v122, 0xbfb8aa3b, v170
	v_mul_f32_e32 v123, 0xbfb8aa3b, v171
	v_exp_f32_e32 v122, v122
	v_exp_f32_e32 v123, v123
	v_lshlrev_b32_e32 v170, 16, v124
	v_and_b32_e32 v171, 0xffff0000, v124
	v_add_f32_e32 v122, 1.0, v122
	v_add_f32_e32 v123, 1.0, v123
	v_rcp_f32_e32 v122, v122
	v_rcp_f32_e32 v123, v123
	v_lshlrev_b32_e32 v124, 16, v125
	v_and_b32_e32 v125, 0xffff0000, v125
	v_pk_fma_f32 v[110:111], v[122:123], v[170:171], v[110:111]
	v_mul_f32_e32 v122, 0xbfb8aa3b, v168
	v_mul_f32_e32 v123, 0xbfb8aa3b, v169
	v_exp_f32_e32 v122, v122
	v_exp_f32_e32 v123, v123
	v_lshl_add_u64 v[168:169], v[186:187], 1, s[54:55]
	v_add_f32_e32 v122, 1.0, v122
	v_add_f32_e32 v123, 1.0, v123
	v_rcp_f32_e32 v122, v122
	v_rcp_f32_e32 v123, v123
	s_nop 0
	v_pk_fma_f32 v[112:113], v[122:123], v[124:125], v[112:113]
	v_cvt_pk_bf16_f32 v122, v106, v107
	v_cvt_pk_bf16_f32 v123, v108, v109
	v_cvt_pk_bf16_f32 v124, v110, v111
	v_cvt_pk_bf16_f32 v125, v112, v113
	global_store_dwordx4 v[226:227], v[106:109], off sc1
	global_store_dwordx4 v[226:227], v[110:113], off offset:16 sc1
	global_store_dwordx4 v[168:169], v[122:125], off sc1
	s_nop 1
	v_mul_f32_e32 v122, 0xbfb8aa3b, v166
	v_mul_f32_e32 v123, 0xbfb8aa3b, v167
	v_exp_f32_e32 v122, v122
	v_exp_f32_e32 v123, v123
	s_waitcnt vmcnt(11)
	v_lshlrev_b32_e32 v124, 16, v114
	v_and_b32_e32 v125, 0xffff0000, v114
	v_mul_f32_e32 v114, 0xbfb8aa3b, v150
	v_add_f32_e32 v122, 1.0, v122
	v_add_f32_e32 v123, 1.0, v123
	v_exp_f32_e32 v114, v114
	v_rcp_f32_e32 v122, v122
	v_rcp_f32_e32 v123, v123
	v_add_f32_e32 v114, 1.0, v114
	v_pk_fma_f32 v[102:103], v[122:123], v[124:125], v[102:103]
	v_rcp_f32_e32 v122, v114
	v_mul_f32_e32 v114, 0xbfb8aa3b, v151
	v_exp_f32_e32 v114, v114
	s_nop 0
	v_add_f32_e32 v114, 1.0, v114
	v_rcp_f32_e32 v123, v114
	v_lshlrev_b32_e32 v114, 16, v115
	v_and_b32_e32 v115, 0xffff0000, v115
	v_pk_fma_f32 v[104:105], v[122:123], v[114:115], v[104:105]
	v_mul_f32_e32 v114, 0xbfb8aa3b, v148
	v_mul_f32_e32 v115, 0xbfb8aa3b, v149
	v_exp_f32_e32 v114, v114
	v_exp_f32_e32 v115, v115
	v_lshlrev_b32_e32 v122, 16, v116
	v_and_b32_e32 v123, 0xffff0000, v116
	v_add_f32_e32 v114, 1.0, v114
	v_add_f32_e32 v115, 1.0, v115
	v_rcp_f32_e32 v114, v114
	v_rcp_f32_e32 v115, v115
	v_lshlrev_b32_e32 v116, 16, v117
	v_and_b32_e32 v117, 0xffff0000, v117
	v_pk_fma_f32 v[98:99], v[114:115], v[122:123], v[98:99]
	v_mul_f32_e32 v114, 0xbfb8aa3b, v146
	v_mul_f32_e32 v115, 0xbfb8aa3b, v147
	v_exp_f32_e32 v114, v114
	v_exp_f32_e32 v115, v115
	v_add_f32_e32 v114, 1.0, v114
	v_add_f32_e32 v115, 1.0, v115
	v_rcp_f32_e32 v114, v114
	v_rcp_f32_e32 v115, v115
	s_nop 0
	v_pk_fma_f32 v[100:101], v[114:115], v[116:117], v[100:101]
	v_cvt_pk_bf16_f32 v114, v102, v103
	v_cvt_pk_bf16_f32 v115, v104, v105
	v_cvt_pk_bf16_f32 v116, v98, v99
	v_cvt_pk_bf16_f32 v117, v100, v101
	global_store_dwordx4 v[226:227], v[102:105], off offset:512 sc1
	global_store_dwordx4 v[226:227], v[98:101], off offset:528 sc1
	global_store_dwordx4 v[168:169], v[114:117], off offset:256 sc1
	s_nop 1
	v_lshlrev_b64 v[114:115], 11, v[224:225]
	v_lshl_add_u64 v[122:123], v[114:115], 0, v[152:153]
	v_mul_f32_e32 v114, 0xbfb8aa3b, v144
	v_mul_f32_e32 v115, 0xbfb8aa3b, v145
	v_exp_f32_e32 v114, v114
	v_exp_f32_e32 v115, v115
	s_waitcnt vmcnt(7)
; __device__ __forceinline__ float sigmoidf_(float x) { return __builtin_amdgcn_rcpf(1.0f + __expf(-x)); }
; __device__ __forceinline__ float shx(float v, int o, int lane) { return __builtin_bit_cast(float, __builtin_amdgcn_ds_bpermute((lane ^ o) << 2, __builtin_bit_cast(int, v))); }
; __device__ __forceinline__ float ssq4(const f32x4 o) { return (o[0] * o[0] + o[1] * o[1]) + (o[2] * o[2] + o[3] * o[3]); }
; template <bool SIXTEEN> __device__ __forceinline__ void tile_ssq(const float (&s)[2][4], const Unit& u, int wr, int wc, int fr, int fq, float* ssq, LAS float* ptab) {
;     ...
;         for (int m = 0; m < 4; ++m) { float v = s[ai][m]; v += shx(v, 16, lane); v += shx(v, 32, lane); if (fq == 0) ptab[(ai * HALF + wr * 64 + m * 16 + fr) * 4 + wc] = v; }
;     __device__ __forceinline__ void operator()(f32x4 (&acc)[2][2][4][2], const Unit& u, int wr, int wc, int fr, int fq) const {
;     ...
;             for (int q = 0; q < 2; ++q) { const int r = 2 * k + q, ai = r >> 2, m = r & 3; const size_t off = (size_t)EPI_ROW(r) * D + col0; float sr = 0.f;
;                 if (r < 7) {
; #pragma unroll
;                     for (int c = 0; c < 4; ++c) pnxt[c] = *(const u32x2*)(pp + (size_t)EPI_ROW(r + 1) * D + col0 + (c >> 1) * HALF + (c & 1) * 4);
;                 }
;                 asm volatile("" ::: "memory");
; #pragma unroll
;                 for (int bj = 0; bj < 2; ++bj) { f32x4 o2[2];
; #pragma unroll
;                     for (int n = 0; n < 2; ++n) { const f32x4 b = cur[q][2 * bj + n]; const u32x2 qw = pcur[2 * bj + n];
;                         const f32x4 pq = (f32x4){bflo(qw.x), bfhi(qw.x), bflo(qw.y), bfhi(qw.y)}; const f32x4 a = acc[ai][bj][m][n];
; #pragma unroll
;                         for (int j = 0; j < 4; ++j) o2[n][j] = b[j] + pq[j] * sigmoidf_(a[j]); }
;                     *(f32x4*)(h + off + bj * HALF) = o2[0]; *(f32x4*)(h + off + bj * HALF + 4) = o2[1];
;                     if (!LAST) { u32x4 w; w.x = cvt_pk_bf16(o2[0][0], o2[0][1]); w.y = cvt_pk_bf16(o2[0][2], o2[0][3]); w.z = cvt_pk_bf16(o2[1][0], o2[1][1]); w.w = cvt_pk_bf16(o2[1][2], o2[1][3]);
;                         *(u32x4*)(hb + off + bj * HALF) = w; sr += ssq4(o2[0]) + ssq4(o2[1]); } }
;                 s[ai][m] = sr;
;                 asm volatile("" ::: "memory");
; #pragma unroll
;                 for (int c = 0; c < 4; ++c) pcur[c] = pnxt[c];
;             }
	v_lshlrev_b32_e32 v116, 16, v126
	v_and_b32_e32 v117, 0xffff0000, v126
	v_add_f32_e32 v114, 1.0, v114
	v_add_f32_e32 v115, 1.0, v115
	v_rcp_f32_e32 v114, v114
	v_rcp_f32_e32 v115, v115
	v_lshl_add_u64 v[122:123], v[122:123], 1, s[54:55]
	v_pk_fma_f32 v[94:95], v[114:115], v[116:117], v[94:95]
	v_mul_f32_e32 v114, 0xbfb8aa3b, v142
	v_mul_f32_e32 v115, 0xbfb8aa3b, v143
	v_exp_f32_e32 v114, v114
	v_exp_f32_e32 v115, v115
	v_lshlrev_b32_e32 v116, 16, v127
	v_and_b32_e32 v117, 0xffff0000, v127
	v_add_f32_e32 v114, 1.0, v114
	v_add_f32_e32 v115, 1.0, v115
	v_rcp_f32_e32 v114, v114
	v_rcp_f32_e32 v115, v115
	s_nop 0
	v_pk_fma_f32 v[96:97], v[114:115], v[116:117], v[96:97]
	v_mul_f32_e32 v114, 0xbfb8aa3b, v140
	v_mul_f32_e32 v115, 0xbfb8aa3b, v141
	v_exp_f32_e32 v114, v114
	v_exp_f32_e32 v115, v115
	v_lshlrev_b32_e32 v116, 16, v128
	v_and_b32_e32 v117, 0xffff0000, v128
	v_add_f32_e32 v114, 1.0, v114
	v_add_f32_e32 v115, 1.0, v115
	v_rcp_f32_e32 v114, v114
	v_rcp_f32_e32 v115, v115
	s_nop 0
	v_pk_fma_f32 v[86:87], v[114:115], v[116:117], v[86:87]
	v_mul_f32_e32 v114, 0xbfb8aa3b, v138
	v_mul_f32_e32 v115, 0xbfb8aa3b, v139
	v_exp_f32_e32 v114, v114
	v_exp_f32_e32 v115, v115
	v_lshlrev_b32_e32 v116, 16, v129
	v_and_b32_e32 v117, 0xffff0000, v129
	v_add_f32_e32 v114, 1.0, v114
	v_add_f32_e32 v115, 1.0, v115
	v_rcp_f32_e32 v114, v114
	v_rcp_f32_e32 v115, v115
	s_nop 0
	v_pk_fma_f32 v[88:89], v[114:115], v[116:117], v[88:89]
	v_cvt_pk_bf16_f32 v114, v94, v95
	v_cvt_pk_bf16_f32 v115, v96, v97
	v_cvt_pk_bf16_f32 v116, v86, v87
	v_cvt_pk_bf16_f32 v117, v88, v89
	global_store_dwordx4 v[172:173], v[94:97], off sc1
	global_store_dwordx4 v[172:173], v[86:89], off offset:16 sc1
	global_store_dwordx4 v[122:123], v[114:117], off sc1
	s_nop 1
	v_mul_f32_e32 v114, 0xbfb8aa3b, v136
	v_mul_f32_e32 v115, 0xbfb8aa3b, v137
	v_exp_f32_e32 v114, v114
	v_exp_f32_e32 v115, v115
	s_waitcnt vmcnt(9)
	v_lshlrev_b32_e32 v116, 16, v118
	v_and_b32_e32 v117, 0xffff0000, v118
	v_add_f32_e32 v114, 1.0, v114
	v_add_f32_e32 v115, 1.0, v115
	v_rcp_f32_e32 v114, v114
	v_rcp_f32_e32 v115, v115
	s_nop 0
	v_pk_fma_f32 v[74:75], v[114:115], v[116:117], v[74:75]
	v_mul_f32_e32 v114, 0xbfb8aa3b, v134
	v_mul_f32_e32 v115, 0xbfb8aa3b, v135
	v_exp_f32_e32 v114, v114
	v_exp_f32_e32 v115, v115
	v_lshlrev_b32_e32 v116, 16, v119
	v_and_b32_e32 v117, 0xffff0000, v119
	v_add_f32_e32 v114, 1.0, v114
	v_add_f32_e32 v115, 1.0, v115
	v_rcp_f32_e32 v114, v114
	v_rcp_f32_e32 v115, v115
	s_nop 0
	v_pk_fma_f32 v[76:77], v[114:115], v[116:117], v[76:77]
	v_mul_f32_e32 v114, 0xbfb8aa3b, v132
	v_mul_f32_e32 v115, 0xbfb8aa3b, v133
	v_exp_f32_e32 v114, v114
	v_exp_f32_e32 v115, v115
	v_lshlrev_b32_e32 v116, 16, v120
	v_and_b32_e32 v117, 0xffff0000, v120
	v_add_f32_e32 v114, 1.0, v114
	v_add_f32_e32 v115, 1.0, v115
	v_rcp_f32_e32 v114, v114
	v_rcp_f32_e32 v115, v115
	s_nop 0
	v_pk_fma_f32 v[62:63], v[114:115], v[116:117], v[62:63]
	v_mul_f32_e32 v114, 0xbfb8aa3b, v130
	v_mul_f32_e32 v115, 0xbfb8aa3b, v131
	v_exp_f32_e32 v114, v114
	v_exp_f32_e32 v115, v115
	v_lshlrev_b32_e32 v116, 16, v121
	v_and_b32_e32 v117, 0xffff0000, v121
	v_add_f32_e32 v114, 1.0, v114
	v_add_f32_e32 v115, 1.0, v115
	v_rcp_f32_e32 v114, v114
	v_rcp_f32_e32 v115, v115
	s_nop 0
	v_pk_fma_f32 v[64:65], v[114:115], v[116:117], v[64:65]
	v_cvt_pk_bf16_f32 v114, v74, v75
	v_cvt_pk_bf16_f32 v115, v76, v77
	v_cvt_pk_bf16_f32 v116, v62, v63
	v_cvt_pk_bf16_f32 v117, v64, v65
	global_store_dwordx4 v[172:173], v[74:77], off offset:512 sc1
	global_store_dwordx4 v[172:173], v[62:65], off offset:528 sc1
	global_store_dwordx4 v[122:123], v[114:117], off offset:256 sc1
	s_nop 1
	v_and_b32_e32 v114, 63, v183
	v_lshlrev_b32_e32 v115, 2, v114
	v_xor_b32_e32 v116, 64, v115
	ds_bpermute_b32 v117, v116, v178
	v_xor_b32_e32 v115, 0x80, v115
	s_waitcnt lgkmcnt(0)
	v_add_f32_e32 v118, v178, v117
	ds_bpermute_b32 v119, v115, v118
	v_lshl_add_u32 v117, v184, 4, s4
	s_and_saveexec_b64 s[8:9], vcc
	s_cbranch_execz .LBB0_2337
	s_waitcnt lgkmcnt(0)
	v_add_f32_e32 v118, v118, v119
	ds_write_b32 v117, v118

; __device__ __forceinline__ float shx(float v, int o, int lane) { return __builtin_bit_cast(float, __builtin_amdgcn_ds_bpermute((lane ^ o) << 2, __builtin_bit_cast(int, v))); }
; __device__ __forceinline__ void rows_rstd(const float* ssq, int row0  , int fr, int fq, float (&rs)[8]) {
;     const int lane = fq * 16 + fr; f32x4 p[8];
;     const float* b0 = ssq + (size_t)row0 * 16 + fq * 4;
; #pragma unroll
;     for (int r = 0; r < 8; ++r) p[r] = *(const f32x4*)(b0 + (r >> 2) * (HALF * 16) + (r & 3) * 256);
; #pragma unroll
;     for (int r = 0; r < 8; ++r) { float v = (p[r][0] + p[r][1]) + (p[r][2] + p[r][3]); v += shx(v, 16, lane); v += shx(v, 32, lane); rs[r] = rsqrtf(v * (1.0f / 2048.0f) + 1e-6f); }
; }
;     __device__ __forceinline__ void operator()(f32x4 (&acc)[2][2][4][2], const Unit& u, int wr, int wc, int fr, int fq) const {
;     ...
;         { float rsv[8]; rows_rstd(ssq_in, u.pm * BM + wr * 64 + fr, fr, fq, rsv);
; #pragma unroll
;             for (int r = 0; r < 8; ++r)
; #pragma unroll
;                 for (int c = 0; c < 4; ++c) acc[r >> 2][c >> 1][r & 3][c & 1] = acc[r >> 2][c >> 1][r & 3][c & 1] * rsv[r]; }
.LBB0_2379:
	v_mov_b32_e32 v130, v246
	s_lshl_b32 s3, s8, 8
	s_add_i32 s3, s3, s42
	v_and_b32_e32 v168, 15, v130
	v_or_b32_e32 v166, s3, v168
	v_ashrrev_i32_e32 v167, 31, v166
	v_readlane_b32 s8, v254, 13
	v_bfe_u32 v178, v130, 4, 2
	v_lshlrev_b64 v[130:131], 6, v[166:167]
	v_readlane_b32 s9, v254, 14
	v_lshlrev_b32_e32 v132, 4, v178
	v_mov_b32_e32 v133, v0
	v_lshl_add_u64 v[130:131], s[8:9], 0, v[130:131]
	v_lshl_add_u64 v[130:131], v[130:131], 0, v[132:133]
	global_load_dwordx4 v[172:175], v[130:131], off
	global_load_dwordx4 v[188:191], v[130:131], off offset:1024
	global_load_dwordx4 v[150:153], v[130:131], off offset:2048
	global_load_dwordx4 v[146:149], v[130:131], off offset:3072
	v_add_co_u32_e32 v130, vcc, s91, v130
	v_lshlrev_b32_e32 v169, 6, v178
	s_nop 0
	v_addc_co_u32_e32 v131, vcc, 0, v131, vcc
	global_load_dwordx4 v[142:145], v[130:131], off
	global_load_dwordx4 v[138:141], v[130:131], off offset:1024
	global_load_dwordx4 v[134:137], v[130:131], off offset:2048
	s_nop 0
	global_load_dwordx4 v[130:133], v[130:131], off offset:3072
	v_lshlrev_b32_e32 v168, 2, v168
	v_bitop3_b32 v171, v169, 64, v168 bitop3:0x36
	v_bitop3_b32 v169, v169, s71, v168 bitop3:0x36
	s_mov_b32 s8, 0x358637bd
	v_mov_b32_e32 v182, v246
	v_or_b32_e32 v248, 32, v166
	v_or_b32_e32 v238, 48, v166
	v_ashrrev_i32_e32 v249, 31, v248
	v_ashrrev_i32_e32 v239, 31, v238
	v_lshlrev_b64 v[224:225], 13, v[248:249]
	s_waitcnt vmcnt(0)
	v_mov_b32_e32 v176, v173
	v_mov_b32_e32 v177, v174
	v_mov_b32_e32 v173, v175
	v_mov_b32_e32 v174, v189
	v_mov_b32_e32 v175, v190
	v_mov_b32_e32 v189, v191
	v_pk_add_f32 v[172:173], v[176:177], v[172:173]
	v_pk_add_f32 v[174:175], v[174:175], v[188:189]
	v_mov_b32_e32 v177, v172
	v_mov_b32_e32 v176, v174
	v_mov_b32_e32 v172, v175
	v_pk_add_f32 v[172:173], v[176:177], v[172:173]
	ds_bpermute_b32 v175, v171, v173
	ds_bpermute_b32 v174, v171, v172
	s_waitcnt lgkmcnt(0)
	v_pk_add_f32 v[172:173], v[172:173], v[174:175]
	ds_bpermute_b32 v175, v169, v173
	ds_bpermute_b32 v174, v169, v172
	s_waitcnt lgkmcnt(0)
	v_pk_add_f32 v[174:175], v[172:173], v[174:175]
	v_mov_b64_e32 v[172:173], s[8:9]
	v_pk_fma_f32 v[174:175], v[174:175], s[2:3], v[172:173] op_sel_hi:[1,0,0]
	s_nop 0
	v_mul_f32_e32 v168, 0x4b800000, v175
	v_cmp_gt_f32_e64 s[8:9], s46, v175
	v_cmp_gt_f32_e32 vcc, s46, v174
	s_nop 0
	v_cndmask_b32_e64 v168, v175, v168, s[8:9]
	v_rsq_f32_e32 v168, v168
	v_mov_b32_e32 v175, v152
	v_mov_b32_e32 v152, v147
	v_mov_b32_e32 v147, v149
	v_mul_f32_e32 v170, 0x45800000, v168
	v_cndmask_b32_e64 v170, v168, v170, s[8:9]
	v_mul_f32_e32 v168, 0x4b800000, v174
	v_cndmask_b32_e32 v168, v174, v168, vcc
	v_rsq_f32_e32 v168, v168
	v_pk_mul_f32 v[236:237], v[110:111], v[170:171] op_sel_hi:[1,0]
	v_pk_mul_f32 v[234:235], v[112:113], v[170:171] op_sel_hi:[1,0]
	v_pk_mul_f32 v[228:229], v[108:109], v[170:171] op_sel_hi:[1,0]
	v_mul_f32_e32 v174, 0x45800000, v168
	v_cndmask_b32_e32 v168, v168, v174, vcc
	v_mov_b32_e32 v174, v151
	v_mov_b32_e32 v151, v153
	v_mov_b32_e32 v153, v148
	v_pk_add_f32 v[150:151], v[174:175], v[150:151]
	v_pk_add_f32 v[146:147], v[152:153], v[146:147]
	v_mov_b32_e32 v149, v150
	v_mov_b32_e32 v148, v146
	v_mov_b32_e32 v150, v147
	v_pk_add_f32 v[146:147], v[148:149], v[150:151]
	ds_bpermute_b32 v149, v171, v147
	ds_bpermute_b32 v148, v171, v146
	v_mov_b32_e32 v150, v143
	v_mov_b32_e32 v151, v144
	v_mov_b32_e32 v143, v145
	v_mov_b32_e32 v144, v139
	v_mov_b32_e32 v145, v140
	v_mov_b32_e32 v139, v141
	v_pk_add_f32 v[142:143], v[150:151], v[142:143]
	v_pk_add_f32 v[138:139], v[144:145], v[138:139]
	s_waitcnt lgkmcnt(0)
	v_pk_add_f32 v[146:147], v[146:147], v[148:149]
	v_mov_b32_e32 v140, v138
	v_mov_b32_e32 v141, v142
	v_mov_b32_e32 v142, v139
	ds_bpermute_b32 v149, v169, v147
	ds_bpermute_b32 v148, v169, v146
	v_pk_add_f32 v[138:139], v[140:141], v[142:143]
	ds_bpermute_b32 v141, v171, v139
	ds_bpermute_b32 v140, v171, v138
	v_pk_mul_f32 v[230:231], v[106:107], v[170:171] op_sel_hi:[1,0]
	s_waitcnt lgkmcnt(2)
	v_pk_add_f32 v[146:147], v[146:147], v[148:149]
	v_pk_mul_f32 v[220:221], v[114:115], v[168:169] op_sel_hi:[1,0]
	v_pk_fma_f32 v[146:147], v[146:147], s[2:3], v[172:173] op_sel_hi:[1,0,0]
	s_waitcnt lgkmcnt(0)
	v_pk_add_f32 v[138:139], v[138:139], v[140:141]
	v_mul_f32_e32 v148, 0x4b800000, v147
	v_cmp_gt_f32_e64 s[8:9], s46, v147
	ds_bpermute_b32 v141, v169, v139
	ds_bpermute_b32 v140, v169, v138
	v_cndmask_b32_e64 v147, v147, v148, s[8:9]
	v_rsq_f32_e32 v147, v147
	v_cmp_gt_f32_e32 vcc, s46, v146
	v_pk_mul_f32 v[214:215], v[96:97], v[168:169] op_sel_hi:[1,0]
	s_waitcnt lgkmcnt(0)
	v_pk_add_f32 v[138:139], v[138:139], v[140:141]
	v_mul_f32_e32 v148, 0x45800000, v147
	v_pk_fma_f32 v[138:139], v[138:139], s[2:3], v[172:173] op_sel_hi:[1,0,0]
	v_cndmask_b32_e64 v148, v147, v148, s[8:9]
	v_mul_f32_e32 v147, 0x4b800000, v146
	v_mul_f32_e32 v140, 0x4b800000, v139
	v_cmp_gt_f32_e64 s[8:9], s46, v139
	v_cndmask_b32_e32 v146, v146, v147, vcc
	v_rsq_f32_e32 v146, v146
	v_cndmask_b32_e64 v139, v139, v140, s[8:9]
	v_rsq_f32_e32 v139, v139
	v_pk_mul_f32 v[202:203], v[98:99], v[148:149] op_sel_hi:[1,0]
	v_mul_f32_e32 v147, 0x45800000, v146
	v_cndmask_b32_e32 v146, v146, v147, vcc
	v_mul_f32_e32 v140, 0x45800000, v139
	v_cmp_gt_f32_e32 vcc, s46, v138
	v_cndmask_b32_e64 v184, v139, v140, s[8:9]
	v_mul_f32_e32 v139, 0x4b800000, v138
	v_cndmask_b32_e32 v138, v138, v139, vcc
	v_rsq_f32_e32 v138, v138
	v_pk_mul_f32 v[174:175], v[84:85], v[146:147] op_sel_hi:[1,0]
	v_pk_mul_f32 v[204:205], v[104:105], v[148:149] op_sel_hi:[1,0]
	v_pk_mul_f32 v[206:207], v[102:103], v[148:149] op_sel_hi:[1,0]
	v_mul_f32_e32 v139, 0x45800000, v138
	v_cndmask_b32_e32 v186, v138, v139, vcc
	v_mov_b32_e32 v138, v135
	v_mov_b32_e32 v139, v136
	v_mov_b32_e32 v135, v137
	v_mov_b32_e32 v136, v131
	v_mov_b32_e32 v137, v132
	v_mov_b32_e32 v131, v133
	v_pk_add_f32 v[134:135], v[138:139], v[134:135]
	v_pk_add_f32 v[130:131], v[136:137], v[130:131]
	v_mov_b32_e32 v133, v134
	v_mov_b32_e32 v132, v130
	v_mov_b32_e32 v134, v131
	v_pk_add_f32 v[130:131], v[132:133], v[134:135]
	ds_bpermute_b32 v133, v171, v131
	ds_bpermute_b32 v132, v171, v130
	v_pk_mul_f32 v[200:201], v[100:101], v[148:149] op_sel_hi:[1,0]
	v_pk_mul_f32 v[176:177], v[82:83], v[146:147] op_sel_hi:[1,0]
	v_pk_mul_f32 v[192:193], v[76:77], v[148:149] op_sel_hi:[1,0]
	v_pk_mul_f32 v[194:195], v[74:75], v[148:149] op_sel_hi:[1,0]
	s_waitcnt lgkmcnt(0)
; __device__ __forceinline__ float shx(float v, int o, int lane) { return __builtin_bit_cast(float, __builtin_amdgcn_ds_bpermute((lane ^ o) << 2, __builtin_bit_cast(int, v))); }
; __device__ __forceinline__ void rows_rstd(const float* ssq, int row0  , int fr, int fq, float (&rs)[8]) {
;     const int lane = fq * 16 + fr; f32x4 p[8];
;     const float* b0 = ssq + (size_t)row0 * 16 + fq * 4;
; #pragma unroll
;     for (int r = 0; r < 8; ++r) p[r] = *(const f32x4*)(b0 + (r >> 2) * (HALF * 16) + (r & 3) * 256);
; #pragma unroll
;     for (int r = 0; r < 8; ++r) { float v = (p[r][0] + p[r][1]) + (p[r][2] + p[r][3]); v += shx(v, 16, lane); v += shx(v, 32, lane); rs[r] = rsqrtf(v * (1.0f / 2048.0f) + 1e-6f); }
; }
;     __device__ __forceinline__ void operator()(f32x4 (&acc)[2][2][4][2], const Unit& u, int wr, int wc, int fr, int fq) const {
;         const int col0 = u.pn * BM + wc * 32 + 8 * fq;
;         float s[2][4];
;         { float rsv[8]; rows_rstd(ssq_in, u.pm * BM + wr * 64 + fr, fr, fq, rsv);
; #pragma unroll
;             for (int r = 0; r < 8; ++r)
; #pragma unroll
;                 for (int c = 0; c < 4; ++c) acc[r >> 2][c >> 1][r & 3][c & 1] = acc[r >> 2][c >> 1][r & 3][c & 1] * rsv[r]; }
;         f32x4 cur[2][4], nxt[2][4]; u32x2 pcur[4], pnxt[4];
; #pragma unroll
;         for (int q = 0; q < 2; ++q)
; #pragma unroll
;             for (int c = 0; c < 4; ++c) cur[q][c] = *(const f32x4*)(h + (size_t)EPI_ROW(q) * D + col0 + (c >> 1) * HALF + (c & 1) * 4);
; #pragma unroll
;         for (int c = 0; c < 4; ++c) pcur[c] = *(const u32x2*)(pp + (size_t)EPI_ROW(0) * D + col0 + (c >> 1) * HALF + (c & 1) * 4);
; #pragma unroll
;         for (int k = 0; k < 4; ++k) {
;             if (k < 3) {
; #pragma unroll
;                 for (int q = 0; q < 2; ++q)
; #pragma unroll
;                     for (int c = 0; c < 4; ++c) nxt[q][c] = *(const f32x4*)(h + (size_t)EPI_ROW(2 * k + 2 + q) * D + col0 + (c >> 1) * HALF + (c & 1) * 4);
;             }
; #pragma unroll
;             for (int q = 0; q < 2; ++q) { const int r = 2 * k + q, ai = r >> 2, m = r & 3; const size_t off = (size_t)EPI_ROW(r) * D + col0; float sr = 0.f;
;                 if (r < 7) {
; #pragma unroll
;                     for (int c = 0; c < 4; ++c) pnxt[c] = *(const u32x2*)(pp + (size_t)EPI_ROW(r + 1) * D + col0 + (c >> 1) * HALF + (c & 1) * 4);
	v_pk_add_f32 v[130:131], v[130:131], v[132:133]
	ds_bpermute_b32 v133, v169, v131
	ds_bpermute_b32 v132, v169, v130
	v_pk_mul_f32 v[150:151], v[68:69], v[146:147] op_sel_hi:[1,0]
	v_pk_mul_f32 v[152:153], v[66:67], v[146:147] op_sel_hi:[1,0]
	v_pk_mul_f32 v[216:217], v[94:95], v[168:169] op_sel_hi:[1,0]
	v_pk_mul_f32 v[210:211], v[92:93], v[168:169] op_sel_hi:[1,0]
	s_waitcnt lgkmcnt(0)
	v_pk_add_f32 v[130:131], v[130:131], v[132:133]
	v_pk_mul_f32 v[212:213], v[90:91], v[168:169] op_sel_hi:[1,0]
	v_pk_fma_f32 v[130:131], v[130:131], s[2:3], v[172:173] op_sel_hi:[1,0,0]
	s_lshl_b32 s3, s33, 8
	v_mul_f32_e32 v132, 0x4b800000, v131
	v_cmp_gt_f32_e64 s[8:9], s46, v131
	v_cmp_gt_f32_e32 vcc, s46, v130
	v_pk_mul_f32 v[188:189], v[88:89], v[146:147] op_sel_hi:[1,0]
	v_cndmask_b32_e64 v131, v131, v132, s[8:9]
	v_rsq_f32_e32 v131, v131
	v_pk_mul_f32 v[190:191], v[86:87], v[146:147] op_sel_hi:[1,0]
	v_pk_mul_f32 v[244:245], v[128:129], v[170:171] op_sel_hi:[1,0]
	v_pk_mul_f32 v[246:247], v[126:127], v[170:171] op_sel_hi:[1,0]
	v_mul_f32_e32 v132, 0x45800000, v131
	v_cndmask_b32_e64 v172, v131, v132, s[8:9]
	v_mul_f32_e32 v131, 0x4b800000, v130
	v_cndmask_b32_e32 v130, v130, v131, vcc
	v_rsq_f32_e32 v130, v130
	v_pk_mul_f32 v[110:111], v[38:39], v[172:173] op_sel_hi:[1,0]
	v_or_b32_e32 v38, 16, v166
	v_pk_mul_f32 v[112:113], v[48:49], v[172:173] op_sel_hi:[1,0]
	v_mul_f32_e32 v131, 0x45800000, v130
	v_cndmask_b32_e32 v208, v130, v131, vcc
	v_pk_mul_f32 v[84:85], v[2:3], v[208:209] op_sel_hi:[1,0]
	v_lshl_or_b32 v2, v178, 3, s3
	v_or_b32_e32 v2, s44, v2
	v_ashrrev_i32_e32 v3, 31, v2
	v_lshlrev_b64 v[98:99], 2, v[2:3]
	v_pk_mul_f32 v[114:115], v[46:47], v[172:173] op_sel_hi:[1,0]
	v_pk_mul_f32 v[108:109], v[40:41], v[172:173] op_sel_hi:[1,0]
	v_pk_mul_f32 v[104:105], v[16:17], v[172:173] op_sel_hi:[1,0]
	v_pk_mul_f32 v[106:107], v[14:15], v[172:173] op_sel_hi:[1,0]
	v_pk_mul_f32 v[100:101], v[12:13], v[172:173] op_sel_hi:[1,0]
	v_pk_mul_f32 v[102:103], v[10:11], v[172:173] op_sel_hi:[1,0]
	v_lshl_add_u64 v[172:173], s[36:37], 0, v[98:99]
	v_lshlrev_b64 v[178:179], 13, v[166:167]
	v_ashrrev_i32_e32 v39, 31, v38
	v_pk_mul_f32 v[82:83], v[4:5], v[208:209] op_sel_hi:[1,0]
	v_lshl_add_u64 v[4:5], v[172:173], 0, v[178:179]
	v_lshlrev_b64 v[232:233], 13, v[38:39]
	v_pk_mul_f32 v[130:131], v[56:57], v[186:187] op_sel_hi:[1,0]
	v_pk_mul_f32 v[132:133], v[54:55], v[186:187] op_sel_hi:[1,0]
	global_load_dwordx4 v[66:69], v[4:5], off offset:16
	global_load_dwordx4 v[74:77], v[4:5], off
	global_load_dwordx4 v[46:49], v[4:5], off offset:528
	global_load_dwordx4 v[54:57], v[4:5], off offset:512
	v_lshl_add_u64 v[4:5], v[172:173], 0, v[232:233]
	v_pk_mul_f32 v[94:95], v[32:33], v[208:209] op_sel_hi:[1,0]
	v_pk_mul_f32 v[96:97], v[30:31], v[208:209] op_sel_hi:[1,0]
	v_pk_mul_f32 v[90:91], v[24:25], v[208:209] op_sel_hi:[1,0]
	v_pk_mul_f32 v[92:93], v[22:23], v[208:209] op_sel_hi:[1,0]
	v_pk_mul_f32 v[86:87], v[8:9], v[208:209] op_sel_hi:[1,0]
	v_pk_mul_f32 v[88:89], v[6:7], v[208:209] op_sel_hi:[1,0]
	global_load_dwordx4 v[22:25], v[4:5], off offset:16
	global_load_dwordx4 v[30:33], v[4:5], off
	global_load_dwordx4 v[6:9], v[4:5], off offset:528
	global_load_dwordx4 v[14:17], v[4:5], off offset:512
	v_lshlrev_b64 v[4:5], 12, v[166:167]
	v_lshl_add_u64 v[4:5], s[56:57], 0, v[4:5]
	v_lshlrev_b64 v[128:129], 1, v[2:3]
	v_lshl_add_u64 v[2:3], v[4:5], 0, v[128:129]
	v_pk_mul_f32 v[240:241], v[124:125], v[170:171] op_sel_hi:[1,0]
	v_pk_mul_f32 v[242:243], v[122:123], v[170:171] op_sel_hi:[1,0]
	v_pk_mul_f32 v[222:223], v[120:121], v[168:169] op_sel_hi:[1,0]
	v_pk_mul_f32 v[226:227], v[118:119], v[168:169] op_sel_hi:[1,0]
	v_pk_mul_f32 v[218:219], v[116:117], v[168:169] op_sel_hi:[1,0]
	v_pk_mul_f32 v[196:197], v[80:81], v[148:149] op_sel_hi:[1,0]
	v_pk_mul_f32 v[198:199], v[78:79], v[148:149] op_sel_hi:[1,0]
	v_pk_mul_f32 v[168:169], v[72:73], v[146:147] op_sel_hi:[1,0]
	v_pk_mul_f32 v[170:171], v[70:71], v[146:147] op_sel_hi:[1,0]
	global_load_dwordx4 v[70:73], v[2:3], off
	global_load_dwordx4 v[78:81], v[2:3], off offset:256
	v_mul_f32_e32 v167, 0xbfb8aa3b, v246
	v_exp_f32_e32 v167, v167
	v_pk_mul_f32 v[146:147], v[64:65], v[184:185] op_sel_hi:[1,0]
	v_pk_mul_f32 v[148:149], v[62:63], v[184:185] op_sel_hi:[1,0]
	v_pk_mul_f32 v[142:143], v[60:61], v[184:185] op_sel_hi:[1,0]
	v_add_f32_e32 v167, 1.0, v167
	v_pk_mul_f32 v[144:145], v[58:59], v[184:185] op_sel_hi:[1,0]
	v_pk_mul_f32 v[138:139], v[44:45], v[184:185] op_sel_hi:[1,0]
	v_pk_mul_f32 v[140:141], v[42:43], v[184:185] op_sel_hi:[1,0]
	v_pk_mul_f32 v[134:135], v[36:37], v[184:185] op_sel_hi:[1,0]
	v_pk_mul_f32 v[136:137], v[34:35], v[184:185] op_sel_hi:[1,0]
	v_rcp_f32_e32 v184, v167
	v_mul_f32_e32 v167, 0xbfb8aa3b, v247
	v_exp_f32_e32 v167, v167
	v_pk_mul_f32 v[124:125], v[52:53], v[186:187] op_sel_hi:[1,0]
	v_pk_mul_f32 v[126:127], v[50:51], v[186:187] op_sel_hi:[1,0]
	v_pk_mul_f32 v[120:121], v[28:29], v[186:187] op_sel_hi:[1,0]
	v_pk_mul_f32 v[122:123], v[26:27], v[186:187] op_sel_hi:[1,0]
	v_pk_mul_f32 v[116:117], v[20:21], v[186:187] op_sel_hi:[1,0]
	v_pk_mul_f32 v[118:119], v[18:19], v[186:187] op_sel_hi:[1,0]
	v_add_f32_e32 v167, 1.0, v167
	v_rcp_f32_e32 v185, v167
	v_lshlrev_b64 v[38:39], 12, v[38:39]
	v_lshlrev_b64 v[208:209], 13, v[238:239]
	v_lshl_add_u64 v[38:39], s[56:57], 0, v[38:39]
	v_lshl_add_u64 v[2:3], v[172:173], 0, v[224:225]
	v_lshl_add_u64 v[10:11], v[172:173], 0, v[208:209]
	v_lshl_add_u64 v[38:39], v[38:39], 0, v[128:129]
	global_load_dwordx4 v[50:53], v[2:3], off offset:16
	global_load_dwordx4 v[58:61], v[2:3], off
	global_load_dwordx4 v[34:37], v[2:3], off offset:528
	global_load_dwordx4 v[42:45], v[2:3], off offset:512
	global_load_dwordx4 v[18:21], v[10:11], off offset:16
	global_load_dwordx4 v[26:29], v[10:11], off
	s_nop 0
	global_load_dwordx4 v[2:5], v[10:11], off offset:528
	s_nop 0
	global_load_dwordx4 v[10:13], v[10:11], off offset:512
	s_nop 0
	global_load_dwordx4 v[62:65], v[38:39], off
	s_nop 0
	global_load_dwordx4 v[38:41], v[38:39], off offset:256
	v_mul_f32_e32 v167, 0xbfb8aa3b, v206
	v_exp_f32_e32 v167, v167
	v_mul_f32_e32 v148, 0xbfb8aa3b, v148
	v_mul_f32_e32 v149, 0xbfb8aa3b, v149
	v_exp_f32_e32 v148, v148
	v_add_f32_e32 v167, 1.0, v167
	v_exp_f32_e32 v149, v149
	s_mov_b64 s[8:9], -1
	v_add_f32_e32 v148, 1.0, v148
	v_rcp_f32_e32 v148, v148
	v_add_f32_e32 v149, 1.0, v149
	v_rcp_f32_e32 v149, v149
	s_andn2_b64 vcc, exec, s[6:7]
	s_waitcnt vmcnt(11)
; __device__ __forceinline__ float sigmoidf_(float x) { return __builtin_amdgcn_rcpf(1.0f + __expf(-x)); }
; __device__ __forceinline__ float ssq4(const f32x4 o) { return (o[0] * o[0] + o[1] * o[1]) + (o[2] * o[2] + o[3] * o[3]); }
;     __device__ __forceinline__ void operator()(f32x4 (&acc)[2][2][4][2], const Unit& u, int wr, int wc, int fr, int fq) const {
;     ...
;             for (int q = 0; q < 2; ++q) { const int r = 2 * k + q, ai = r >> 2, m = r & 3; const size_t off = (size_t)EPI_ROW(r) * D + col0; float sr = 0.f;
;                 if (r < 7) {
; #pragma unroll
;                     for (int c = 0; c < 4; ++c) pnxt[c] = *(const u32x2*)(pp + (size_t)EPI_ROW(r + 1) * D + col0 + (c >> 1) * HALF + (c & 1) * 4);
;                 }
;                 asm volatile("" ::: "memory");
; #pragma unroll
;                 for (int bj = 0; bj < 2; ++bj) { f32x4 o2[2];
; #pragma unroll
;                     for (int n = 0; n < 2; ++n) { const f32x4 b = cur[q][2 * bj + n]; const u32x2 qw = pcur[2 * bj + n];
;                         const f32x4 pq = (f32x4){bflo(qw.x), bfhi(qw.x), bflo(qw.y), bfhi(qw.y)}; const f32x4 a = acc[ai][bj][m][n];
; #pragma unroll
;                         for (int j = 0; j < 4; ++j) o2[n][j] = b[j] + pq[j] * sigmoidf_(a[j]); }
;                     *(f32x4*)(h + off + bj * HALF) = o2[0]; *(f32x4*)(h + off + bj * HALF + 4) = o2[1];
;                     if (!LAST) { u32x4 w; w.x = cvt_pk_bf16(o2[0][0], o2[0][1]); w.y = cvt_pk_bf16(o2[0][2], o2[0][3]); w.z = cvt_pk_bf16(o2[1][0], o2[1][1]); w.w = cvt_pk_bf16(o2[1][2], o2[1][3]);
;                         *(u32x4*)(hb + off + bj * HALF) = w; sr += ssq4(o2[0]) + ssq4(o2[1]); } }
	v_lshlrev_b32_e32 v186, 16, v70
	v_and_b32_e32 v187, 0xffff0000, v70
	v_mul_f32_e32 v70, 0xbfb8aa3b, v244
	v_exp_f32_e32 v70, v70
	v_pk_fma_f32 v[74:75], v[184:185], v[186:187], v[74:75]
	v_add_f32_e32 v70, 1.0, v70
	v_rcp_f32_e32 v184, v70
	v_mul_f32_e32 v70, 0xbfb8aa3b, v245
	v_exp_f32_e32 v70, v70
	s_nop 0
	v_add_f32_e32 v70, 1.0, v70
	v_rcp_f32_e32 v185, v70
	v_lshlrev_b32_e32 v70, 16, v71
	v_and_b32_e32 v71, 0xffff0000, v71
	v_pk_fma_f32 v[76:77], v[184:185], v[70:71], v[76:77]
	v_mul_f32_e32 v70, 0xbfb8aa3b, v242
	v_mul_f32_e32 v71, 0xbfb8aa3b, v243
	v_exp_f32_e32 v70, v70
	v_exp_f32_e32 v71, v71
	v_lshlrev_b32_e32 v184, 16, v72
	v_and_b32_e32 v185, 0xffff0000, v72
	v_add_f32_e32 v70, 1.0, v70
	v_add_f32_e32 v71, 1.0, v71
	v_rcp_f32_e32 v70, v70
	v_rcp_f32_e32 v71, v71
	v_lshlrev_b32_e32 v72, 16, v73
	v_and_b32_e32 v73, 0xffff0000, v73
	v_pk_fma_f32 v[66:67], v[70:71], v[184:185], v[66:67]
	v_mul_f32_e32 v70, 0xbfb8aa3b, v240
	v_mul_f32_e32 v71, 0xbfb8aa3b, v241
	v_exp_f32_e32 v70, v70
	v_exp_f32_e32 v71, v71
	v_rcp_f32_e32 v184, v167
	v_mul_f32_e32 v167, 0xbfb8aa3b, v207
	v_add_f32_e32 v70, 1.0, v70
	v_add_f32_e32 v71, 1.0, v71
	v_rcp_f32_e32 v70, v70
	v_rcp_f32_e32 v71, v71
	v_exp_f32_e32 v167, v167
	v_pk_fma_f32 v[68:69], v[70:71], v[72:73], v[68:69]
	v_lshl_add_u64 v[70:71], s[36:37], 0, v[178:179]
	v_lshl_add_u64 v[70:71], v[70:71], 0, v[98:99]
	global_store_dwordx4 v[70:71], v[74:77], off sc1
	global_store_dwordx4 v[70:71], v[66:69], off offset:16 sc1
	v_add_f32_e32 v167, 1.0, v167
	v_rcp_f32_e32 v185, v167
	v_mul_f32_e32 v66, 0xbfb8aa3b, v236
	v_mul_f32_e32 v67, 0xbfb8aa3b, v237
	v_exp_f32_e32 v66, v66
	v_exp_f32_e32 v67, v67
	s_waitcnt vmcnt(12)
	v_lshlrev_b32_e32 v68, 16, v78
	v_and_b32_e32 v69, 0xffff0000, v78
	v_add_f32_e32 v66, 1.0, v66
	v_add_f32_e32 v67, 1.0, v67
	v_rcp_f32_e32 v66, v66
	v_rcp_f32_e32 v67, v67
	v_add_u32_e32 v178, 0x80, v166
	v_ashrrev_i32_e32 v179, 31, v178
	v_pk_fma_f32 v[54:55], v[66:67], v[68:69], v[54:55]
	v_mul_f32_e32 v66, 0xbfb8aa3b, v234
	v_mul_f32_e32 v67, 0xbfb8aa3b, v235
	v_exp_f32_e32 v66, v66
	v_exp_f32_e32 v67, v67
	v_lshlrev_b32_e32 v68, 16, v79
	v_and_b32_e32 v69, 0xffff0000, v79
	v_add_f32_e32 v66, 1.0, v66
	v_add_f32_e32 v67, 1.0, v67
	v_rcp_f32_e32 v66, v66
	v_rcp_f32_e32 v67, v67
	s_nop 0
	v_pk_fma_f32 v[56:57], v[66:67], v[68:69], v[56:57]
	v_mul_f32_e32 v66, 0xbfb8aa3b, v230
	v_mul_f32_e32 v67, 0xbfb8aa3b, v231
	v_exp_f32_e32 v66, v66
	v_exp_f32_e32 v67, v67
	v_lshlrev_b32_e32 v68, 16, v80
	v_and_b32_e32 v69, 0xffff0000, v80
	v_add_f32_e32 v66, 1.0, v66
	v_add_f32_e32 v67, 1.0, v67
	v_rcp_f32_e32 v66, v66
	v_rcp_f32_e32 v67, v67
	s_nop 0
	v_pk_fma_f32 v[46:47], v[66:67], v[68:69], v[46:47]
	v_mul_f32_e32 v66, 0xbfb8aa3b, v228
	v_mul_f32_e32 v67, 0xbfb8aa3b, v229
	v_exp_f32_e32 v66, v66
	v_exp_f32_e32 v67, v67
	v_lshlrev_b32_e32 v68, 16, v81
	v_and_b32_e32 v69, 0xffff0000, v81
	v_add_f32_e32 v66, 1.0, v66
	v_add_f32_e32 v67, 1.0, v67
	v_rcp_f32_e32 v66, v66
	v_rcp_f32_e32 v67, v67
	s_nop 0
	v_pk_fma_f32 v[48:49], v[66:67], v[68:69], v[48:49]
	global_store_dwordx4 v[70:71], v[54:57], off offset:512 sc1
	global_store_dwordx4 v[70:71], v[46:49], off offset:528 sc1
	v_lshlrev_b64 v[70:71], 12, v[238:239]
	v_lshl_add_u64 v[70:71], s[56:57], 0, v[70:71]
	v_lshlrev_b64 v[46:47], 12, v[248:249]
	v_lshl_add_u64 v[46:47], s[56:57], 0, v[46:47]
	v_lshl_add_u64 v[46:47], v[46:47], 0, v[128:129]
	global_load_dwordx4 v[74:77], v[46:47], off
	global_load_dwordx4 v[66:69], v[46:47], off offset:256
	v_mul_f32_e32 v46, 0xbfb8aa3b, v226
	v_mul_f32_e32 v47, 0xbfb8aa3b, v227
	v_exp_f32_e32 v46, v46
	v_exp_f32_e32 v47, v47
	s_waitcnt vmcnt(7)
	v_lshlrev_b32_e32 v48, 16, v62
	v_and_b32_e32 v49, 0xffff0000, v62
	v_add_f32_e32 v46, 1.0, v46
	v_add_f32_e32 v47, 1.0, v47
	v_rcp_f32_e32 v46, v46
	v_rcp_f32_e32 v47, v47
	v_lshl_add_u64 v[70:71], v[70:71], 0, v[128:129]
	v_pk_fma_f32 v[30:31], v[46:47], v[48:49], v[30:31]
	v_mul_f32_e32 v46, 0xbfb8aa3b, v222
	v_mul_f32_e32 v47, 0xbfb8aa3b, v223
	v_exp_f32_e32 v46, v46
	v_exp_f32_e32 v47, v47
	v_lshlrev_b32_e32 v48, 16, v63
	v_and_b32_e32 v49, 0xffff0000, v63
	v_add_f32_e32 v46, 1.0, v46
	v_add_f32_e32 v47, 1.0, v47
	v_rcp_f32_e32 v46, v46
	v_rcp_f32_e32 v47, v47
	s_waitcnt vmcnt(1)
; __device__ __forceinline__ float sigmoidf_(float x) { return __builtin_amdgcn_rcpf(1.0f + __expf(-x)); }
; __device__ __forceinline__ float ssq4(const f32x4 o) { return (o[0] * o[0] + o[1] * o[1]) + (o[2] * o[2] + o[3] * o[3]); }
;     __device__ __forceinline__ void operator()(f32x4 (&acc)[2][2][4][2], const Unit& u, int wr, int wc, int fr, int fq) const {
;     ...
;         for (int k = 0; k < 4; ++k) {
;             if (k < 3) {
; #pragma unroll
;                 for (int q = 0; q < 2; ++q)
; #pragma unroll
;                     for (int c = 0; c < 4; ++c) nxt[q][c] = *(const f32x4*)(h + (size_t)EPI_ROW(2 * k + 2 + q) * D + col0 + (c >> 1) * HALF + (c & 1) * 4);
;             }
; #pragma unroll
;             for (int q = 0; q < 2; ++q) { const int r = 2 * k + q, ai = r >> 2, m = r & 3; const size_t off = (size_t)EPI_ROW(r) * D + col0; float sr = 0.f;
;                 if (r < 7) {
; #pragma unroll
;                     for (int c = 0; c < 4; ++c) pnxt[c] = *(const u32x2*)(pp + (size_t)EPI_ROW(r + 1) * D + col0 + (c >> 1) * HALF + (c & 1) * 4);
;                 }
;                 asm volatile("" ::: "memory");
; #pragma unroll
;                 for (int bj = 0; bj < 2; ++bj) { f32x4 o2[2];
; #pragma unroll
;                     for (int n = 0; n < 2; ++n) { const f32x4 b = cur[q][2 * bj + n]; const u32x2 qw = pcur[2 * bj + n];
;                         const f32x4 pq = (f32x4){bflo(qw.x), bfhi(qw.x), bflo(qw.y), bfhi(qw.y)}; const f32x4 a = acc[ai][bj][m][n];
; #pragma unroll
;                         for (int j = 0; j < 4; ++j) o2[n][j] = b[j] + pq[j] * sigmoidf_(a[j]); }
;                     *(f32x4*)(h + off + bj * HALF) = o2[0]; *(f32x4*)(h + off + bj * HALF + 4) = o2[1];
;                     if (!LAST) { u32x4 w; w.x = cvt_pk_bf16(o2[0][0], o2[0][1]); w.y = cvt_pk_bf16(o2[0][2], o2[0][3]); w.z = cvt_pk_bf16(o2[1][0], o2[1][1]); w.w = cvt_pk_bf16(o2[1][2], o2[1][3]);
;                         *(u32x4*)(hb + off + bj * HALF) = w; sr += ssq4(o2[0]) + ssq4(o2[1]); } }
	v_lshlrev_b32_e32 v186, 16, v74
	v_pk_fma_f32 v[32:33], v[46:47], v[48:49], v[32:33]
	v_mul_f32_e32 v46, 0xbfb8aa3b, v220
	v_mul_f32_e32 v47, 0xbfb8aa3b, v221
	v_exp_f32_e32 v46, v46
	v_exp_f32_e32 v47, v47
	v_lshlrev_b32_e32 v48, 16, v64
	v_and_b32_e32 v49, 0xffff0000, v64
	v_add_f32_e32 v46, 1.0, v46
	v_add_f32_e32 v47, 1.0, v47
	v_rcp_f32_e32 v46, v46
	v_rcp_f32_e32 v47, v47
	v_and_b32_e32 v187, 0xffff0000, v74
	v_mul_f32_e32 v74, 0xbfb8aa3b, v204
	v_exp_f32_e32 v74, v74
	v_pk_fma_f32 v[22:23], v[46:47], v[48:49], v[22:23]
	v_mul_f32_e32 v46, 0xbfb8aa3b, v218
	v_mul_f32_e32 v47, 0xbfb8aa3b, v219
	v_exp_f32_e32 v46, v46
	v_exp_f32_e32 v47, v47
	v_lshlrev_b32_e32 v48, 16, v65
	v_and_b32_e32 v49, 0xffff0000, v65
	v_add_f32_e32 v46, 1.0, v46
	v_add_f32_e32 v47, 1.0, v47
	v_rcp_f32_e32 v46, v46
	v_rcp_f32_e32 v47, v47
	v_add_f32_e32 v74, 1.0, v74
	v_pk_fma_f32 v[58:59], v[184:185], v[186:187], v[58:59]
	v_rcp_f32_e32 v184, v74
	v_pk_fma_f32 v[24:25], v[46:47], v[48:49], v[24:25]
	v_lshl_add_u64 v[46:47], s[36:37], 0, v[232:233]
	v_lshl_add_u64 v[46:47], v[46:47], 0, v[98:99]
	global_store_dwordx4 v[46:47], v[30:33], off sc1
	global_store_dwordx4 v[46:47], v[22:25], off offset:16 sc1
	v_mul_f32_e32 v74, 0xbfb8aa3b, v205
	v_exp_f32_e32 v74, v74
	v_mul_f32_e32 v22, 0xbfb8aa3b, v216
	v_mul_f32_e32 v23, 0xbfb8aa3b, v217
	v_exp_f32_e32 v22, v22
	v_exp_f32_e32 v23, v23
	v_lshlrev_b32_e32 v24, 16, v38
	v_and_b32_e32 v25, 0xffff0000, v38
	v_add_f32_e32 v22, 1.0, v22
	v_add_f32_e32 v23, 1.0, v23
	v_rcp_f32_e32 v22, v22
	v_rcp_f32_e32 v23, v23
	v_add_f32_e32 v74, 1.0, v74
	v_rcp_f32_e32 v185, v74
	v_lshlrev_b32_e32 v74, 16, v75
	v_pk_fma_f32 v[14:15], v[22:23], v[24:25], v[14:15]
	v_mul_f32_e32 v22, 0xbfb8aa3b, v214
	v_mul_f32_e32 v23, 0xbfb8aa3b, v215
	v_exp_f32_e32 v22, v22
	v_exp_f32_e32 v23, v23
	v_lshlrev_b32_e32 v24, 16, v39
	v_and_b32_e32 v25, 0xffff0000, v39
	v_add_f32_e32 v22, 1.0, v22
	v_add_f32_e32 v23, 1.0, v23
	v_rcp_f32_e32 v22, v22
	v_rcp_f32_e32 v23, v23
	v_add_u32_e32 v214, 0x90, v166
	v_ashrrev_i32_e32 v215, 31, v214
	v_and_b32_e32 v75, 0xffff0000, v75
	v_pk_fma_f32 v[16:17], v[22:23], v[24:25], v[16:17]
	v_mul_f32_e32 v22, 0xbfb8aa3b, v212
	v_mul_f32_e32 v23, 0xbfb8aa3b, v213
	v_exp_f32_e32 v22, v22
	v_exp_f32_e32 v23, v23
	v_lshlrev_b32_e32 v24, 16, v40
	v_and_b32_e32 v25, 0xffff0000, v40
	v_add_f32_e32 v22, 1.0, v22
	v_add_f32_e32 v23, 1.0, v23
	v_rcp_f32_e32 v22, v22
	v_rcp_f32_e32 v23, v23
	v_lshlrev_b64 v[212:213], 13, v[178:179]
	v_pk_fma_f32 v[60:61], v[184:185], v[74:75], v[60:61]
	v_mul_f32_e32 v74, 0xbfb8aa3b, v202
	v_pk_fma_f32 v[6:7], v[22:23], v[24:25], v[6:7]
	v_mul_f32_e32 v22, 0xbfb8aa3b, v210
	v_mul_f32_e32 v23, 0xbfb8aa3b, v211
	v_exp_f32_e32 v22, v22
	v_exp_f32_e32 v23, v23
	v_lshlrev_b32_e32 v24, 16, v41
	v_and_b32_e32 v25, 0xffff0000, v41
	v_add_f32_e32 v22, 1.0, v22
	v_add_f32_e32 v23, 1.0, v23
	v_rcp_f32_e32 v22, v22
	v_rcp_f32_e32 v23, v23
	v_lshlrev_b64 v[210:211], 13, v[214:215]
	v_mul_f32_e32 v75, 0xbfb8aa3b, v203
	v_exp_f32_e32 v74, v74
	v_pk_fma_f32 v[8:9], v[22:23], v[24:25], v[8:9]
	global_store_dwordx4 v[46:47], v[14:17], off offset:512 sc1
	global_store_dwordx4 v[46:47], v[6:9], off offset:528 sc1
	v_exp_f32_e32 v75, v75
	v_lshl_add_u64 v[14:15], v[172:173], 0, v[210:211]
	v_lshl_add_u64 v[6:7], v[172:173], 0, v[212:213]
	global_load_dwordx4 v[54:57], v[6:7], off offset:16
	global_load_dwordx4 v[62:65], v[6:7], off
	global_load_dwordx4 v[38:41], v[6:7], off offset:528
	global_load_dwordx4 v[46:49], v[6:7], off offset:512
	global_load_dwordx4 v[22:25], v[14:15], off offset:16
	global_load_dwordx4 v[30:33], v[14:15], off
	s_nop 0
	global_load_dwordx4 v[6:9], v[14:15], off offset:528
	s_nop 0
	global_load_dwordx4 v[14:17], v[14:15], off offset:512
	s_nop 0
	global_load_dwordx4 v[78:81], v[70:71], off
	s_nop 0
	global_load_dwordx4 v[70:73], v[70:71], off offset:256
	v_add_f32_e32 v74, 1.0, v74
	v_add_f32_e32 v75, 1.0, v75
	v_rcp_f32_e32 v74, v74
	v_rcp_f32_e32 v75, v75
	v_lshlrev_b32_e32 v184, 16, v76
	v_and_b32_e32 v185, 0xffff0000, v76
	v_lshlrev_b32_e32 v76, 16, v77
	v_pk_fma_f32 v[50:51], v[74:75], v[184:185], v[50:51]
	v_mul_f32_e32 v74, 0xbfb8aa3b, v200
	v_mul_f32_e32 v75, 0xbfb8aa3b, v201
	v_exp_f32_e32 v74, v74
	v_exp_f32_e32 v75, v75
	v_and_b32_e32 v77, 0xffff0000, v77
	v_add_f32_e32 v74, 1.0, v74
	v_add_f32_e32 v75, 1.0, v75
	v_rcp_f32_e32 v74, v74
	v_rcp_f32_e32 v75, v75
	s_nop 0
	v_pk_fma_f32 v[52:53], v[74:75], v[76:77], v[52:53]
	v_lshl_add_u64 v[74:75], s[36:37], 0, v[224:225]
	v_lshl_add_u64 v[74:75], v[74:75], 0, v[98:99]
	global_store_dwordx4 v[74:75], v[58:61], off sc1
	global_store_dwordx4 v[74:75], v[50:53], off offset:16 sc1
	s_nop 1
	v_mul_f32_e32 v50, 0xbfb8aa3b, v198
	v_mul_f32_e32 v51, 0xbfb8aa3b, v199
	v_exp_f32_e32 v50, v50
	v_exp_f32_e32 v51, v51
	s_waitcnt vmcnt(16)
; __device__ __forceinline__ float sigmoidf_(float x) { return __builtin_amdgcn_rcpf(1.0f + __expf(-x)); }
; __device__ __forceinline__ float ssq4(const f32x4 o) { return (o[0] * o[0] + o[1] * o[1]) + (o[2] * o[2] + o[3] * o[3]); }
;     __device__ __forceinline__ void operator()(f32x4 (&acc)[2][2][4][2], const Unit& u, int wr, int wc, int fr, int fq) const {
;     ...
;         for (int k = 0; k < 4; ++k) {
;             if (k < 3) {
; #pragma unroll
;                 for (int q = 0; q < 2; ++q)
; #pragma unroll
;                     for (int c = 0; c < 4; ++c) nxt[q][c] = *(const f32x4*)(h + (size_t)EPI_ROW(2 * k + 2 + q) * D + col0 + (c >> 1) * HALF + (c & 1) * 4);
;             }
; #pragma unroll
;             for (int q = 0; q < 2; ++q) { const int r = 2 * k + q, ai = r >> 2, m = r & 3; const size_t off = (size_t)EPI_ROW(r) * D + col0; float sr = 0.f;
;                 if (r < 7) {
; #pragma unroll
;                     for (int c = 0; c < 4; ++c) pnxt[c] = *(const u32x2*)(pp + (size_t)EPI_ROW(r + 1) * D + col0 + (c >> 1) * HALF + (c & 1) * 4);
;                 }
;                 asm volatile("" ::: "memory");
; #pragma unroll
;                 for (int bj = 0; bj < 2; ++bj) { f32x4 o2[2];
; #pragma unroll
;                     for (int n = 0; n < 2; ++n) { const f32x4 b = cur[q][2 * bj + n]; const u32x2 qw = pcur[2 * bj + n];
;                         const f32x4 pq = (f32x4){bflo(qw.x), bfhi(qw.x), bflo(qw.y), bfhi(qw.y)}; const f32x4 a = acc[ai][bj][m][n];
; #pragma unroll
;                         for (int j = 0; j < 4; ++j) o2[n][j] = b[j] + pq[j] * sigmoidf_(a[j]); }
;                     *(f32x4*)(h + off + bj * HALF) = o2[0]; *(f32x4*)(h + off + bj * HALF + 4) = o2[1];
;                     if (!LAST) { u32x4 w; w.x = cvt_pk_bf16(o2[0][0], o2[0][1]); w.y = cvt_pk_bf16(o2[0][2], o2[0][3]); w.z = cvt_pk_bf16(o2[1][0], o2[1][1]); w.w = cvt_pk_bf16(o2[1][2], o2[1][3]);
;                         *(u32x4*)(hb + off + bj * HALF) = w; sr += ssq4(o2[0]) + ssq4(o2[1]); } }
	v_lshlrev_b32_e32 v52, 16, v66
	v_and_b32_e32 v53, 0xffff0000, v66
	v_add_f32_e32 v50, 1.0, v50
	v_add_f32_e32 v51, 1.0, v51
	v_rcp_f32_e32 v50, v50
	v_rcp_f32_e32 v51, v51
	s_nop 0
	v_pk_fma_f32 v[42:43], v[50:51], v[52:53], v[42:43]
	v_mul_f32_e32 v50, 0xbfb8aa3b, v196
	v_mul_f32_e32 v51, 0xbfb8aa3b, v197
	v_exp_f32_e32 v50, v50
	v_exp_f32_e32 v51, v51
	v_lshlrev_b32_e32 v52, 16, v67
	v_and_b32_e32 v53, 0xffff0000, v67
	v_add_f32_e32 v50, 1.0, v50
	v_add_f32_e32 v51, 1.0, v51
	v_rcp_f32_e32 v50, v50
	v_rcp_f32_e32 v51, v51
	s_nop 0
	v_pk_fma_f32 v[44:45], v[50:51], v[52:53], v[44:45]
	v_mul_f32_e32 v50, 0xbfb8aa3b, v194
	v_mul_f32_e32 v51, 0xbfb8aa3b, v195
	v_exp_f32_e32 v50, v50
	v_exp_f32_e32 v51, v51
	v_lshlrev_b32_e32 v52, 16, v68
	v_and_b32_e32 v53, 0xffff0000, v68
	v_add_f32_e32 v50, 1.0, v50
	v_add_f32_e32 v51, 1.0, v51
	v_rcp_f32_e32 v50, v50
	v_rcp_f32_e32 v51, v51
	s_nop 0
	v_pk_fma_f32 v[34:35], v[50:51], v[52:53], v[34:35]
	v_mul_f32_e32 v50, 0xbfb8aa3b, v192
	v_mul_f32_e32 v51, 0xbfb8aa3b, v193
	v_exp_f32_e32 v50, v50
	v_exp_f32_e32 v51, v51
	v_lshlrev_b32_e32 v52, 16, v69
	v_and_b32_e32 v53, 0xffff0000, v69
	v_add_f32_e32 v50, 1.0, v50
	v_add_f32_e32 v51, 1.0, v51
	v_rcp_f32_e32 v50, v50
	v_rcp_f32_e32 v51, v51
	s_nop 0
	v_pk_fma_f32 v[36:37], v[50:51], v[52:53], v[36:37]
	global_store_dwordx4 v[74:75], v[42:45], off offset:512 sc1
	global_store_dwordx4 v[74:75], v[34:37], off offset:528 sc1
	s_nop 1
	v_lshlrev_b64 v[34:35], 12, v[178:179]
	v_lshl_add_u64 v[34:35], s[56:57], 0, v[34:35]
	v_lshl_add_u64 v[34:35], v[34:35], 0, v[128:129]
	global_load_dwordx4 v[74:77], v[34:35], off
	global_load_dwordx4 v[66:69], v[34:35], off offset:256
	v_mul_f32_e32 v34, 0xbfb8aa3b, v190
	v_mul_f32_e32 v35, 0xbfb8aa3b, v191
	v_exp_f32_e32 v34, v34
	v_exp_f32_e32 v35, v35
	s_waitcnt vmcnt(7)
	v_lshlrev_b32_e32 v36, 16, v78
	v_and_b32_e32 v37, 0xffff0000, v78
	v_add_f32_e32 v34, 1.0, v34
	v_add_f32_e32 v35, 1.0, v35
	v_rcp_f32_e32 v34, v34
	v_rcp_f32_e32 v35, v35
	s_nop 0
	v_pk_fma_f32 v[26:27], v[34:35], v[36:37], v[26:27]
	v_mul_f32_e32 v34, 0xbfb8aa3b, v188
	v_mul_f32_e32 v35, 0xbfb8aa3b, v189
	v_exp_f32_e32 v34, v34
	v_exp_f32_e32 v35, v35
	v_lshlrev_b32_e32 v36, 16, v79
	v_and_b32_e32 v37, 0xffff0000, v79
	v_add_f32_e32 v34, 1.0, v34
	v_add_f32_e32 v35, 1.0, v35
	v_rcp_f32_e32 v34, v34
	v_rcp_f32_e32 v35, v35
	s_nop 0
	v_pk_fma_f32 v[28:29], v[34:35], v[36:37], v[28:29]
	v_mul_f32_e32 v34, 0xbfb8aa3b, v176
	v_mul_f32_e32 v35, 0xbfb8aa3b, v177
	v_exp_f32_e32 v34, v34
	v_exp_f32_e32 v35, v35
	v_lshlrev_b32_e32 v36, 16, v80
	v_and_b32_e32 v37, 0xffff0000, v80
	v_add_f32_e32 v34, 1.0, v34
	v_add_f32_e32 v35, 1.0, v35
	v_rcp_f32_e32 v34, v34
	v_rcp_f32_e32 v35, v35
	s_nop 0
	v_pk_fma_f32 v[18:19], v[34:35], v[36:37], v[18:19]
	v_mul_f32_e32 v34, 0xbfb8aa3b, v174
	v_mul_f32_e32 v35, 0xbfb8aa3b, v175
	v_exp_f32_e32 v34, v34
	v_exp_f32_e32 v35, v35
	v_lshlrev_b32_e32 v36, 16, v81
	v_and_b32_e32 v37, 0xffff0000, v81
	v_add_f32_e32 v34, 1.0, v34
	v_add_f32_e32 v35, 1.0, v35
	v_rcp_f32_e32 v34, v34
	v_rcp_f32_e32 v35, v35
	s_nop 0
	v_pk_fma_f32 v[20:21], v[34:35], v[36:37], v[20:21]
	v_lshl_add_u64 v[34:35], s[36:37], 0, v[208:209]
	v_lshl_add_u64 v[34:35], v[34:35], 0, v[98:99]
	global_store_dwordx4 v[34:35], v[26:29], off sc1
	global_store_dwordx4 v[34:35], v[18:21], off offset:16 sc1
	s_nop 1
	v_mul_f32_e32 v18, 0xbfb8aa3b, v170
	v_mul_f32_e32 v19, 0xbfb8aa3b, v171
	v_exp_f32_e32 v18, v18
	v_exp_f32_e32 v19, v19
	s_waitcnt vmcnt(8)
	v_lshlrev_b32_e32 v20, 16, v70
	v_and_b32_e32 v21, 0xffff0000, v70
	v_add_f32_e32 v18, 1.0, v18
	v_add_f32_e32 v19, 1.0, v19
	v_rcp_f32_e32 v18, v18
	v_rcp_f32_e32 v19, v19
	s_waitcnt vmcnt(3)
	v_lshlrev_b32_e32 v170, 16, v74
	v_pk_fma_f32 v[10:11], v[18:19], v[20:21], v[10:11]
	v_mul_f32_e32 v18, 0xbfb8aa3b, v168
	v_mul_f32_e32 v19, 0xbfb8aa3b, v169
	v_exp_f32_e32 v18, v18
	v_exp_f32_e32 v19, v19
	v_lshlrev_b32_e32 v20, 16, v71
	v_and_b32_e32 v21, 0xffff0000, v71
	v_add_f32_e32 v18, 1.0, v18
	v_add_f32_e32 v19, 1.0, v19
	v_rcp_f32_e32 v18, v18
	v_rcp_f32_e32 v19, v19
	v_and_b32_e32 v171, 0xffff0000, v74
	v_mul_f32_e32 v74, 0xbfb8aa3b, v146
	v_exp_f32_e32 v74, v74
	v_pk_fma_f32 v[12:13], v[18:19], v[20:21], v[12:13]
	v_mul_f32_e32 v18, 0xbfb8aa3b, v152
	v_mul_f32_e32 v19, 0xbfb8aa3b, v153
	v_exp_f32_e32 v18, v18
	v_exp_f32_e32 v19, v19
	v_lshlrev_b32_e32 v20, 16, v72
	v_and_b32_e32 v21, 0xffff0000, v72
	v_add_f32_e32 v18, 1.0, v18
	v_add_f32_e32 v19, 1.0, v19
	v_rcp_f32_e32 v18, v18
	v_rcp_f32_e32 v19, v19
	v_add_u32_e32 v168, 0xa0, v166
	v_add_u32_e32 v166, 0xb0, v166
	v_ashrrev_i32_e32 v169, 31, v168
	v_pk_fma_f32 v[2:3], v[18:19], v[20:21], v[2:3]
	v_mul_f32_e32 v18, 0xbfb8aa3b, v150
	v_mul_f32_e32 v19, 0xbfb8aa3b, v151
	v_exp_f32_e32 v18, v18
	v_exp_f32_e32 v19, v19
	v_lshlrev_b32_e32 v20, 16, v73
	v_and_b32_e32 v21, 0xffff0000, v73
	v_add_f32_e32 v18, 1.0, v18
	v_add_f32_e32 v19, 1.0, v19
	v_rcp_f32_e32 v18, v18
	v_rcp_f32_e32 v19, v19
	v_ashrrev_i32_e32 v167, 31, v166
	v_lshlrev_b64 v[70:71], 12, v[214:215]
	v_add_f32_e32 v74, 1.0, v74
	v_pk_fma_f32 v[4:5], v[18:19], v[20:21], v[4:5]
	global_store_dwordx4 v[34:35], v[10:13], off offset:512 sc1
	global_store_dwordx4 v[34:35], v[2:5], off offset:528 sc1
	v_lshlrev_b64 v[152:153], 13, v[168:169]
	v_lshlrev_b64 v[150:151], 13, v[166:167]
	v_lshl_add_u64 v[70:71], s[56:57], 0, v[70:71]
	v_rcp_f32_e32 v146, v74
	v_mul_f32_e32 v74, 0xbfb8aa3b, v147
	v_lshl_add_u64 v[2:3], v[172:173], 0, v[152:153]
	v_lshl_add_u64 v[10:11], v[172:173], 0, v[150:151]
	v_lshl_add_u64 v[70:71], v[70:71], 0, v[128:129]
	v_exp_f32_e32 v74, v74
	global_load_dwordx4 v[50:53], v[2:3], off offset:16
; __device__ __forceinline__ float sigmoidf_(float x) { return __builtin_amdgcn_rcpf(1.0f + __expf(-x)); }
; __device__ __forceinline__ float ssq4(const f32x4 o) { return (o[0] * o[0] + o[1] * o[1]) + (o[2] * o[2] + o[3] * o[3]); }
;     __device__ __forceinline__ void operator()(f32x4 (&acc)[2][2][4][2], const Unit& u, int wr, int wc, int fr, int fq) const {
;     ...
;         for (int k = 0; k < 4; ++k) {
;             if (k < 3) {
; #pragma unroll
;                 for (int q = 0; q < 2; ++q)
; #pragma unroll
;                     for (int c = 0; c < 4; ++c) nxt[q][c] = *(const f32x4*)(h + (size_t)EPI_ROW(2 * k + 2 + q) * D + col0 + (c >> 1) * HALF + (c & 1) * 4);
;             }
; #pragma unroll
;             for (int q = 0; q < 2; ++q) { const int r = 2 * k + q, ai = r >> 2, m = r & 3; const size_t off = (size_t)EPI_ROW(r) * D + col0; float sr = 0.f;
;                 if (r < 7) {
; #pragma unroll
;                     for (int c = 0; c < 4; ++c) pnxt[c] = *(const u32x2*)(pp + (size_t)EPI_ROW(r + 1) * D + col0 + (c >> 1) * HALF + (c & 1) * 4);
;                 }
;                 asm volatile("" ::: "memory");
; #pragma unroll
;                 for (int bj = 0; bj < 2; ++bj) { f32x4 o2[2];
; #pragma unroll
;                     for (int n = 0; n < 2; ++n) { const f32x4 b = cur[q][2 * bj + n]; const u32x2 qw = pcur[2 * bj + n];
;                         const f32x4 pq = (f32x4){bflo(qw.x), bfhi(qw.x), bflo(qw.y), bfhi(qw.y)}; const f32x4 a = acc[ai][bj][m][n];
; #pragma unroll
;                         for (int j = 0; j < 4; ++j) o2[n][j] = b[j] + pq[j] * sigmoidf_(a[j]); }
;                     *(f32x4*)(h + off + bj * HALF) = o2[0]; *(f32x4*)(h + off + bj * HALF + 4) = o2[1];
;                     if (!LAST) { u32x4 w; w.x = cvt_pk_bf16(o2[0][0], o2[0][1]); w.y = cvt_pk_bf16(o2[0][2], o2[0][3]); w.z = cvt_pk_bf16(o2[1][0], o2[1][1]); w.w = cvt_pk_bf16(o2[1][2], o2[1][3]);
;                         *(u32x4*)(hb + off + bj * HALF) = w; sr += ssq4(o2[0]) + ssq4(o2[1]); } }
;                 s[ai][m] = sr;
;                 asm volatile("" ::: "memory");
; #pragma unroll
;                 for (int c = 0; c < 4; ++c) pcur[c] = pnxt[c];
;             }
; #pragma unroll
;             for (int q = 0; q < 2; ++q)
; #pragma unroll
;                 for (int c = 0; c < 4; ++c) cur[q][c] = nxt[q][c];
;         }
	global_load_dwordx4 v[58:61], v[2:3], off
	global_load_dwordx4 v[34:37], v[2:3], off offset:528
	global_load_dwordx4 v[42:45], v[2:3], off offset:512
	global_load_dwordx4 v[18:21], v[10:11], off offset:16
	global_load_dwordx4 v[26:29], v[10:11], off
	s_nop 0
	global_load_dwordx4 v[2:5], v[10:11], off offset:528
	s_nop 0
	global_load_dwordx4 v[10:13], v[10:11], off offset:512
	s_nop 0
	global_load_dwordx4 v[78:81], v[70:71], off
	s_nop 0
	global_load_dwordx4 v[70:73], v[70:71], off offset:256
	v_add_f32_e32 v74, 1.0, v74
	v_rcp_f32_e32 v147, v74
	v_lshlrev_b32_e32 v74, 16, v75
	v_and_b32_e32 v75, 0xffff0000, v75
	v_pk_fma_f32 v[62:63], v[148:149], v[170:171], v[62:63]
	v_pk_fma_f32 v[64:65], v[146:147], v[74:75], v[64:65]
	v_mul_f32_e32 v74, 0xbfb8aa3b, v144
	v_mul_f32_e32 v75, 0xbfb8aa3b, v145
	v_exp_f32_e32 v74, v74
	v_exp_f32_e32 v75, v75
	v_lshlrev_b32_e32 v144, 16, v76
	v_and_b32_e32 v145, 0xffff0000, v76
	v_add_f32_e32 v74, 1.0, v74
	v_add_f32_e32 v75, 1.0, v75
	v_rcp_f32_e32 v74, v74
	v_rcp_f32_e32 v75, v75
	v_lshlrev_b32_e32 v76, 16, v77
	v_and_b32_e32 v77, 0xffff0000, v77
	v_pk_fma_f32 v[54:55], v[74:75], v[144:145], v[54:55]
	v_mul_f32_e32 v74, 0xbfb8aa3b, v142
	v_mul_f32_e32 v75, 0xbfb8aa3b, v143
	v_exp_f32_e32 v74, v74
	v_exp_f32_e32 v75, v75
	v_add_f32_e32 v74, 1.0, v74
	v_add_f32_e32 v75, 1.0, v75
	v_rcp_f32_e32 v74, v74
	v_rcp_f32_e32 v75, v75
	s_nop 0
	v_pk_fma_f32 v[56:57], v[74:75], v[76:77], v[56:57]
	v_lshl_add_u64 v[74:75], s[36:37], 0, v[212:213]
	v_lshl_add_u64 v[74:75], v[74:75], 0, v[98:99]
	global_store_dwordx4 v[74:75], v[62:65], off sc1
	global_store_dwordx4 v[74:75], v[54:57], off offset:16 sc1
	s_nop 1
	v_mul_f32_e32 v54, 0xbfb8aa3b, v140
	v_mul_f32_e32 v55, 0xbfb8aa3b, v141
	v_exp_f32_e32 v54, v54
	v_exp_f32_e32 v55, v55
	s_waitcnt vmcnt(16)
	v_lshlrev_b32_e32 v56, 16, v66
	v_and_b32_e32 v57, 0xffff0000, v66
	v_add_f32_e32 v54, 1.0, v54
	v_add_f32_e32 v55, 1.0, v55
	v_rcp_f32_e32 v54, v54
	v_rcp_f32_e32 v55, v55
	s_nop 0
	v_pk_fma_f32 v[46:47], v[54:55], v[56:57], v[46:47]
	v_mul_f32_e32 v54, 0xbfb8aa3b, v138
	v_mul_f32_e32 v55, 0xbfb8aa3b, v139
	v_exp_f32_e32 v54, v54
	v_exp_f32_e32 v55, v55
	v_lshlrev_b32_e32 v56, 16, v67
	v_and_b32_e32 v57, 0xffff0000, v67
	v_add_f32_e32 v54, 1.0, v54
	v_add_f32_e32 v55, 1.0, v55
	v_rcp_f32_e32 v54, v54
	v_rcp_f32_e32 v55, v55
	s_nop 0
	v_pk_fma_f32 v[48:49], v[54:55], v[56:57], v[48:49]
	v_mul_f32_e32 v54, 0xbfb8aa3b, v136
	v_mul_f32_e32 v55, 0xbfb8aa3b, v137
	v_exp_f32_e32 v54, v54
	v_exp_f32_e32 v55, v55
	v_lshlrev_b32_e32 v56, 16, v68
	v_and_b32_e32 v57, 0xffff0000, v68
	v_add_f32_e32 v54, 1.0, v54
	v_add_f32_e32 v55, 1.0, v55
	v_rcp_f32_e32 v54, v54
	v_rcp_f32_e32 v55, v55
	s_nop 0
	v_pk_fma_f32 v[38:39], v[54:55], v[56:57], v[38:39]
	v_mul_f32_e32 v54, 0xbfb8aa3b, v134
	v_mul_f32_e32 v55, 0xbfb8aa3b, v135
	v_exp_f32_e32 v54, v54
	v_exp_f32_e32 v55, v55
	v_lshlrev_b32_e32 v56, 16, v69
	v_and_b32_e32 v57, 0xffff0000, v69
	v_add_f32_e32 v54, 1.0, v54
	v_add_f32_e32 v55, 1.0, v55
	v_rcp_f32_e32 v54, v54
	v_rcp_f32_e32 v55, v55
	s_nop 0
	v_pk_fma_f32 v[40:41], v[54:55], v[56:57], v[40:41]
	v_mul_f32_e32 v54, 0xbfb8aa3b, v132
	v_mul_f32_e32 v55, 0xbfb8aa3b, v133
	v_exp_f32_e32 v54, v54
	v_exp_f32_e32 v55, v55
	global_store_dwordx4 v[74:75], v[46:49], off offset:512 sc1
	global_store_dwordx4 v[74:75], v[38:41], off offset:528 sc1
	s_waitcnt vmcnt(5)
	v_lshlrev_b32_e32 v56, 16, v78
	v_add_f32_e32 v54, 1.0, v54
	v_add_f32_e32 v55, 1.0, v55
	v_rcp_f32_e32 v54, v54
	v_rcp_f32_e32 v55, v55
	v_lshlrev_b64 v[38:39], 12, v[168:169]
	v_and_b32_e32 v57, 0xffff0000, v78
	v_lshl_add_u64 v[38:39], s[56:57], 0, v[38:39]
	v_pk_fma_f32 v[30:31], v[54:55], v[56:57], v[30:31]
	v_mul_f32_e32 v54, 0xbfb8aa3b, v130
	v_mul_f32_e32 v55, 0xbfb8aa3b, v131
	v_lshl_add_u64 v[38:39], v[38:39], 0, v[128:129]
	v_exp_f32_e32 v54, v54
	v_exp_f32_e32 v55, v55
	global_load_dwordx4 v[46:49], v[38:39], off
	s_nop 0
	global_load_dwordx4 v[38:41], v[38:39], off offset:256
	v_lshlrev_b32_e32 v56, 16, v79
	v_add_f32_e32 v54, 1.0, v54
	v_add_f32_e32 v55, 1.0, v55
	v_rcp_f32_e32 v54, v54
	v_rcp_f32_e32 v55, v55
	v_and_b32_e32 v57, 0xffff0000, v79
	v_pk_fma_f32 v[32:33], v[54:55], v[56:57], v[32:33]
	v_mul_f32_e32 v54, 0xbfb8aa3b, v126
	v_mul_f32_e32 v55, 0xbfb8aa3b, v127
	v_exp_f32_e32 v54, v54
	v_exp_f32_e32 v55, v55
	v_lshlrev_b32_e32 v56, 16, v80
	v_and_b32_e32 v57, 0xffff0000, v80
	v_add_f32_e32 v54, 1.0, v54
	v_add_f32_e32 v55, 1.0, v55
	v_rcp_f32_e32 v54, v54
	v_rcp_f32_e32 v55, v55
	s_nop 0
	v_pk_fma_f32 v[22:23], v[54:55], v[56:57], v[22:23]
	v_mul_f32_e32 v54, 0xbfb8aa3b, v124
	v_mul_f32_e32 v55, 0xbfb8aa3b, v125
	v_exp_f32_e32 v54, v54
	v_exp_f32_e32 v55, v55
	v_lshlrev_b32_e32 v56, 16, v81
	v_and_b32_e32 v57, 0xffff0000, v81
	v_add_f32_e32 v54, 1.0, v54
	v_add_f32_e32 v55, 1.0, v55
	v_rcp_f32_e32 v54, v54
	v_rcp_f32_e32 v55, v55
	s_nop 0
	v_pk_fma_f32 v[24:25], v[54:55], v[56:57], v[24:25]
	v_lshl_add_u64 v[54:55], s[36:37], 0, v[210:211]
	v_lshl_add_u64 v[54:55], v[54:55], 0, v[98:99]
	global_store_dwordx4 v[54:55], v[30:33], off sc1
	global_store_dwordx4 v[54:55], v[22:25], off offset:16 sc1
	s_waitcnt vmcnt(3)
; __device__ __forceinline__ float sigmoidf_(float x) { return __builtin_amdgcn_rcpf(1.0f + __expf(-x)); }
; __device__ __forceinline__ float ssq4(const f32x4 o) { return (o[0] * o[0] + o[1] * o[1]) + (o[2] * o[2] + o[3] * o[3]); }
;     __device__ __forceinline__ void operator()(f32x4 (&acc)[2][2][4][2], const Unit& u, int wr, int wc, int fr, int fq) const {
;     ...
;             for (int q = 0; q < 2; ++q) { const int r = 2 * k + q, ai = r >> 2, m = r & 3; const size_t off = (size_t)EPI_ROW(r) * D + col0; float sr = 0.f;
;                 if (r < 7) {
; #pragma unroll
;                     for (int c = 0; c < 4; ++c) pnxt[c] = *(const u32x2*)(pp + (size_t)EPI_ROW(r + 1) * D + col0 + (c >> 1) * HALF + (c & 1) * 4);
;                 }
;                 asm volatile("" ::: "memory");
; #pragma unroll
;                 for (int bj = 0; bj < 2; ++bj) { f32x4 o2[2];
; #pragma unroll
;                     for (int n = 0; n < 2; ++n) { const f32x4 b = cur[q][2 * bj + n]; const u32x2 qw = pcur[2 * bj + n];
;                         const f32x4 pq = (f32x4){bflo(qw.x), bfhi(qw.x), bflo(qw.y), bfhi(qw.y)}; const f32x4 a = acc[ai][bj][m][n];
; #pragma unroll
;                         for (int j = 0; j < 4; ++j) o2[n][j] = b[j] + pq[j] * sigmoidf_(a[j]); }
;                     *(f32x4*)(h + off + bj * HALF) = o2[0]; *(f32x4*)(h + off + bj * HALF + 4) = o2[1];
;                     if (!LAST) { u32x4 w; w.x = cvt_pk_bf16(o2[0][0], o2[0][1]); w.y = cvt_pk_bf16(o2[0][2], o2[0][3]); w.z = cvt_pk_bf16(o2[1][0], o2[1][1]); w.w = cvt_pk_bf16(o2[1][2], o2[1][3]);
;                         *(u32x4*)(hb + off + bj * HALF) = w; sr += ssq4(o2[0]) + ssq4(o2[1]); } }
	v_lshlrev_b32_e32 v30, 16, v47
	v_mul_f32_e32 v22, 0xbfb8aa3b, v122
	v_mul_f32_e32 v23, 0xbfb8aa3b, v123
	v_exp_f32_e32 v22, v22
	v_exp_f32_e32 v23, v23
	v_lshlrev_b32_e32 v24, 16, v70
	v_and_b32_e32 v25, 0xffff0000, v70
	v_add_f32_e32 v22, 1.0, v22
	v_add_f32_e32 v23, 1.0, v23
	v_rcp_f32_e32 v22, v22
	v_rcp_f32_e32 v23, v23
	v_and_b32_e32 v31, 0xffff0000, v47
	v_lshlrev_b32_e32 v32, 16, v48
	v_and_b32_e32 v33, 0xffff0000, v48
	v_pk_fma_f32 v[14:15], v[22:23], v[24:25], v[14:15]
	v_mul_f32_e32 v22, 0xbfb8aa3b, v120
	v_mul_f32_e32 v23, 0xbfb8aa3b, v121
	v_exp_f32_e32 v22, v22
	v_exp_f32_e32 v23, v23
	v_lshlrev_b32_e32 v24, 16, v71
	v_and_b32_e32 v25, 0xffff0000, v71
	v_add_f32_e32 v22, 1.0, v22
	v_add_f32_e32 v23, 1.0, v23
	v_rcp_f32_e32 v22, v22
	v_rcp_f32_e32 v23, v23
	v_and_b32_e32 v47, 0xffff0000, v49
	v_pk_fma_f32 v[16:17], v[22:23], v[24:25], v[16:17]
	v_mul_f32_e32 v22, 0xbfb8aa3b, v118
	v_mul_f32_e32 v23, 0xbfb8aa3b, v119
	v_exp_f32_e32 v22, v22
	v_exp_f32_e32 v23, v23
	v_lshlrev_b32_e32 v24, 16, v72
	v_and_b32_e32 v25, 0xffff0000, v72
	v_add_f32_e32 v22, 1.0, v22
	v_add_f32_e32 v23, 1.0, v23
	v_rcp_f32_e32 v22, v22
	v_rcp_f32_e32 v23, v23
	s_nop 0
	v_pk_fma_f32 v[6:7], v[22:23], v[24:25], v[6:7]
	v_mul_f32_e32 v22, 0xbfb8aa3b, v116
	v_mul_f32_e32 v23, 0xbfb8aa3b, v117
	v_exp_f32_e32 v22, v22
	v_exp_f32_e32 v23, v23
	v_lshlrev_b32_e32 v24, 16, v73
	v_and_b32_e32 v25, 0xffff0000, v73
	v_add_f32_e32 v22, 1.0, v22
	v_add_f32_e32 v23, 1.0, v23
	v_rcp_f32_e32 v22, v22
	v_rcp_f32_e32 v23, v23
	s_nop 0
	v_pk_fma_f32 v[8:9], v[22:23], v[24:25], v[8:9]
	v_mul_f32_e32 v22, 0xbfb8aa3b, v114
	v_mul_f32_e32 v23, 0xbfb8aa3b, v115
	v_exp_f32_e32 v22, v22
	v_exp_f32_e32 v23, v23
	global_store_dwordx4 v[54:55], v[14:17], off offset:512 sc1
	global_store_dwordx4 v[54:55], v[6:9], off offset:528 sc1
	v_add_f32_e32 v22, 1.0, v22
	v_add_f32_e32 v23, 1.0, v23
	v_lshlrev_b64 v[6:7], 12, v[166:167]
	v_lshl_add_u64 v[6:7], s[56:57], 0, v[6:7]
	v_lshl_add_u64 v[6:7], v[6:7], 0, v[128:129]
	v_rcp_f32_e32 v22, v22
	v_rcp_f32_e32 v23, v23
	global_load_dwordx4 v[14:17], v[6:7], off
	s_nop 0
	global_load_dwordx4 v[6:9], v[6:7], off offset:256
	v_lshlrev_b32_e32 v24, 16, v46
	v_and_b32_e32 v25, 0xffff0000, v46
	v_pk_fma_f32 v[22:23], v[22:23], v[24:25], v[58:59]
	v_mul_f32_e32 v24, 0xbfb8aa3b, v112
	v_mul_f32_e32 v25, 0xbfb8aa3b, v113
	v_exp_f32_e32 v24, v24
	v_exp_f32_e32 v25, v25
	v_lshlrev_b32_e32 v46, 16, v49
	v_add_f32_e32 v24, 1.0, v24
	v_add_f32_e32 v25, 1.0, v25
	v_rcp_f32_e32 v24, v24
	v_rcp_f32_e32 v25, v25
	s_nop 0
	v_pk_fma_f32 v[24:25], v[24:25], v[30:31], v[60:61]
	v_mul_f32_e32 v30, 0xbfb8aa3b, v110
	v_mul_f32_e32 v31, 0xbfb8aa3b, v111
	v_exp_f32_e32 v30, v30
	v_exp_f32_e32 v31, v31
	v_add_f32_e32 v30, 1.0, v30
	v_add_f32_e32 v31, 1.0, v31
	v_rcp_f32_e32 v30, v30
	v_rcp_f32_e32 v31, v31
	s_nop 0
	v_pk_fma_f32 v[30:31], v[30:31], v[32:33], v[50:51]
	v_mul_f32_e32 v32, 0xbfb8aa3b, v108
	v_mul_f32_e32 v33, 0xbfb8aa3b, v109
	v_exp_f32_e32 v32, v32
	v_exp_f32_e32 v33, v33
	v_add_f32_e32 v32, 1.0, v32
	v_add_f32_e32 v33, 1.0, v33
	v_rcp_f32_e32 v32, v32
	v_rcp_f32_e32 v33, v33
	s_nop 0
	v_pk_fma_f32 v[32:33], v[32:33], v[46:47], v[52:53]
	v_lshl_add_u64 v[46:47], s[36:37], 0, v[152:153]
	v_lshl_add_u64 v[46:47], v[46:47], 0, v[98:99]
	global_store_dwordx4 v[46:47], v[22:25], off sc1
	global_store_dwordx4 v[46:47], v[30:33], off offset:16 sc1
	s_nop 0
	v_mul_f32_e32 v22, 0xbfb8aa3b, v106
	v_mul_f32_e32 v23, 0xbfb8aa3b, v107
	v_exp_f32_e32 v22, v22
	v_exp_f32_e32 v23, v23
	s_waitcnt vmcnt(8)
; __device__ __forceinline__ float sigmoidf_(float x) { return __builtin_amdgcn_rcpf(1.0f + __expf(-x)); }
; __device__ __forceinline__ float ssq4(const f32x4 o) { return (o[0] * o[0] + o[1] * o[1]) + (o[2] * o[2] + o[3] * o[3]); }
; #define PG8_BAR __builtin_amdgcn_s_barrier()
;     __device__ __forceinline__ void operator()(f32x4 (&acc)[2][2][4][2], const Unit& u, int wr, int wc, int fr, int fq) const {
;     ...
;                 for (int bj = 0; bj < 2; ++bj) { f32x4 o2[2];
; #pragma unroll
;                     for (int n = 0; n < 2; ++n) { const f32x4 b = cur[q][2 * bj + n]; const u32x2 qw = pcur[2 * bj + n];
;                         const f32x4 pq = (f32x4){bflo(qw.x), bfhi(qw.x), bflo(qw.y), bfhi(qw.y)}; const f32x4 a = acc[ai][bj][m][n];
; #pragma unroll
;                         for (int j = 0; j < 4; ++j) o2[n][j] = b[j] + pq[j] * sigmoidf_(a[j]); }
;                     *(f32x4*)(h + off + bj * HALF) = o2[0]; *(f32x4*)(h + off + bj * HALF + 4) = o2[1];
;                     if (!LAST) { u32x4 w; w.x = cvt_pk_bf16(o2[0][0], o2[0][1]); w.y = cvt_pk_bf16(o2[0][2], o2[0][3]); w.z = cvt_pk_bf16(o2[1][0], o2[1][1]); w.w = cvt_pk_bf16(o2[1][2], o2[1][3]);
;                         *(u32x4*)(hb + off + bj * HALF) = w; sr += ssq4(o2[0]) + ssq4(o2[1]); } }
; template <class Epi>
; __device__ __forceinline__ void gemm_phase(LAS unsigned char* lds, const Gemm g, const StaticOrder& S, const Epi& E) {
;     ...
;         if (!has_next) break;
; #pragma unroll
;         for (int a = 0; a < 2; ++a)
; #pragma unroll
;             for (int b = 0; b < 2; ++b)
; #pragma unroll
;                 for (int m = 0; m < 4; ++m)
; #pragma unroll
;                     for (int n = 0; n < 2; ++n) acc[a][b][m][n] = (f32x4){0.f, 0.f, 0.f, 0.f};
;         cur = nxt; cA = nA; cB = nB; ++ui;
;         if (wr == 1) PG8_BAR;
	v_lshlrev_b32_e32 v24, 16, v38
	v_and_b32_e32 v25, 0xffff0000, v38
	v_add_f32_e32 v22, 1.0, v22
	v_add_f32_e32 v23, 1.0, v23
	v_rcp_f32_e32 v22, v22
	v_rcp_f32_e32 v23, v23
	v_lshlrev_b32_e32 v30, 16, v39
	v_and_b32_e32 v31, 0xffff0000, v39
	v_lshlrev_b32_e32 v32, 16, v40
	v_pk_fma_f32 v[22:23], v[22:23], v[24:25], v[42:43]
	v_mul_f32_e32 v24, 0xbfb8aa3b, v104
	v_mul_f32_e32 v25, 0xbfb8aa3b, v105
	v_exp_f32_e32 v24, v24
	v_exp_f32_e32 v25, v25
	v_and_b32_e32 v33, 0xffff0000, v40
	v_add_f32_e32 v24, 1.0, v24
	v_add_f32_e32 v25, 1.0, v25
	v_rcp_f32_e32 v24, v24
	v_rcp_f32_e32 v25, v25
	s_nop 0
	v_pk_fma_f32 v[24:25], v[24:25], v[30:31], v[44:45]
	v_mul_f32_e32 v30, 0xbfb8aa3b, v102
	v_mul_f32_e32 v31, 0xbfb8aa3b, v103
	v_exp_f32_e32 v30, v30
	v_exp_f32_e32 v31, v31
	v_add_f32_e32 v30, 1.0, v30
	v_add_f32_e32 v31, 1.0, v31
	v_rcp_f32_e32 v30, v30
	v_rcp_f32_e32 v31, v31
	s_nop 0
	v_pk_fma_f32 v[30:31], v[30:31], v[32:33], v[34:35]
	v_mul_f32_e32 v32, 0xbfb8aa3b, v100
	v_mul_f32_e32 v33, 0xbfb8aa3b, v101
	v_exp_f32_e32 v32, v32
	v_exp_f32_e32 v33, v33
	v_lshlrev_b32_e32 v34, 16, v41
	v_and_b32_e32 v35, 0xffff0000, v41
	v_add_f32_e32 v32, 1.0, v32
	v_add_f32_e32 v33, 1.0, v33
	v_rcp_f32_e32 v32, v32
	v_rcp_f32_e32 v33, v33
	s_nop 0
	v_pk_fma_f32 v[32:33], v[32:33], v[34:35], v[36:37]
	global_store_dwordx4 v[46:47], v[22:25], off offset:512 sc1
	global_store_dwordx4 v[46:47], v[30:33], off offset:528 sc1
	s_nop 0
	v_mul_f32_e32 v22, 0xbfb8aa3b, v96
	v_mul_f32_e32 v23, 0xbfb8aa3b, v97
	v_exp_f32_e32 v22, v22
	v_exp_f32_e32 v23, v23
	s_waitcnt vmcnt(5)
	v_lshlrev_b32_e32 v24, 16, v14
	v_and_b32_e32 v25, 0xffff0000, v14
	v_mul_f32_e32 v14, 0xbfb8aa3b, v94
	v_add_f32_e32 v22, 1.0, v22
	v_add_f32_e32 v23, 1.0, v23
	v_exp_f32_e32 v14, v14
	v_rcp_f32_e32 v22, v22
	v_rcp_f32_e32 v23, v23
	v_add_f32_e32 v14, 1.0, v14
	v_pk_fma_f32 v[22:23], v[22:23], v[24:25], v[26:27]
	v_rcp_f32_e32 v24, v14
	v_mul_f32_e32 v14, 0xbfb8aa3b, v95
	v_exp_f32_e32 v14, v14
	v_lshlrev_b32_e32 v26, 16, v16
	v_and_b32_e32 v27, 0xffff0000, v16
	v_mul_f32_e32 v16, 0xbfb8aa3b, v90
	v_add_f32_e32 v14, 1.0, v14
	v_rcp_f32_e32 v25, v14
	v_lshlrev_b32_e32 v14, 16, v15
	v_and_b32_e32 v15, 0xffff0000, v15
	v_exp_f32_e32 v16, v16
	v_pk_fma_f32 v[24:25], v[24:25], v[14:15], v[28:29]
	v_mul_f32_e32 v14, 0xbfb8aa3b, v92
	v_mul_f32_e32 v15, 0xbfb8aa3b, v93
	v_exp_f32_e32 v14, v14
	v_exp_f32_e32 v15, v15
	v_add_f32_e32 v16, 1.0, v16
	v_add_f32_e32 v14, 1.0, v14
	v_add_f32_e32 v15, 1.0, v15
	v_rcp_f32_e32 v14, v14
	v_rcp_f32_e32 v15, v15
	s_nop 0
	v_pk_fma_f32 v[14:15], v[14:15], v[26:27], v[18:19]
	v_rcp_f32_e32 v18, v16
	v_mul_f32_e32 v16, 0xbfb8aa3b, v91
	v_exp_f32_e32 v16, v16
	s_nop 0
	v_add_f32_e32 v16, 1.0, v16
	v_rcp_f32_e32 v19, v16
	v_lshlrev_b32_e32 v16, 16, v17
	v_and_b32_e32 v17, 0xffff0000, v17
	v_pk_fma_f32 v[16:17], v[18:19], v[16:17], v[20:21]
	v_lshl_add_u64 v[18:19], s[36:37], 0, v[150:151]
	v_lshl_add_u64 v[18:19], v[18:19], 0, v[98:99]
	global_store_dwordx4 v[18:19], v[22:25], off sc1
	global_store_dwordx4 v[18:19], v[14:17], off offset:16 sc1
	s_nop 1
	v_mul_f32_e32 v14, 0xbfb8aa3b, v88
	v_mul_f32_e32 v15, 0xbfb8aa3b, v89
	v_exp_f32_e32 v14, v14
	v_exp_f32_e32 v15, v15
	s_waitcnt vmcnt(6)
	v_lshlrev_b32_e32 v16, 16, v6
	v_and_b32_e32 v17, 0xffff0000, v6
	v_mul_f32_e32 v6, 0xbfb8aa3b, v86
	v_add_f32_e32 v14, 1.0, v14
	v_add_f32_e32 v15, 1.0, v15
	v_exp_f32_e32 v6, v6
	v_rcp_f32_e32 v14, v14
	v_rcp_f32_e32 v15, v15
	v_add_f32_e32 v6, 1.0, v6
	v_pk_fma_f32 v[10:11], v[14:15], v[16:17], v[10:11]
	v_rcp_f32_e32 v14, v6
	v_mul_f32_e32 v6, 0xbfb8aa3b, v87
	v_exp_f32_e32 v6, v6
	s_nop 0
	v_add_f32_e32 v6, 1.0, v6
	v_rcp_f32_e32 v15, v6
	v_lshlrev_b32_e32 v6, 16, v7
	v_and_b32_e32 v7, 0xffff0000, v7
	v_pk_fma_f32 v[12:13], v[14:15], v[6:7], v[12:13]
	v_mul_f32_e32 v6, 0xbfb8aa3b, v84
	v_mul_f32_e32 v7, 0xbfb8aa3b, v85
	v_exp_f32_e32 v6, v6
	v_exp_f32_e32 v7, v7
	v_lshlrev_b32_e32 v14, 16, v8
	v_and_b32_e32 v15, 0xffff0000, v8
	v_add_f32_e32 v6, 1.0, v6
	v_add_f32_e32 v7, 1.0, v7
	v_rcp_f32_e32 v6, v6
	v_rcp_f32_e32 v7, v7
	v_lshlrev_b32_e32 v8, 16, v9
	v_and_b32_e32 v9, 0xffff0000, v9
	v_pk_fma_f32 v[2:3], v[6:7], v[14:15], v[2:3]
	v_mul_f32_e32 v6, 0xbfb8aa3b, v82
	v_mul_f32_e32 v7, 0xbfb8aa3b, v83
	v_exp_f32_e32 v6, v6
	v_exp_f32_e32 v7, v7
	v_add_f32_e32 v6, 1.0, v6
	v_add_f32_e32 v7, 1.0, v7
	v_rcp_f32_e32 v6, v6
	v_rcp_f32_e32 v7, v7
	s_nop 0
	v_pk_fma_f32 v[4:5], v[6:7], v[8:9], v[4:5]
	global_store_dwordx4 v[18:19], v[10:13], off offset:512 sc1
	global_store_dwordx4 v[18:19], v[2:5], off offset:528 sc1
	s_cbranch_vccnz .LBB0_2368
	s_andn2_b64 vcc, exec, s[0:1]
	s_cbranch_vccnz .LBB0_2367
	s_barrier
	s_branch .LBB0_2367
